# speedup vs baseline: 1.0013x; 1.0013x over previous
; #define GAS __attribute__((address_space(1)))
; __device__ __forceinline__ uint2 pack4(f32x4 v) { return make_uint2(pack2(v[0], v[1]), pack2(v[2], v[3])); }
; template <int MODE>
; __device__ __forceinline__ void epi_elem(char* ws, float* outp, const float* b_gate, int g0, int rl, int col, f32x4 v) {
;     ...
;   } else if (MODE == E_T || MODE == E_FF) {
;     *(GAS uint2*)((u16*)(ws + (MODE == E_T ? W_T : W_FF)) + (size_t)rl * 1024 + col) = pack4(v);
;     ...
;     int rbase = cur_brow + wr * 64 + fr;
;     int cbase = cur_bcol + wc * 32 + fq * 4;
;     asm volatile("" : "+v"(rbase), "+v"(cbase));
;     char* wsl = p->ws; float* outl = p->out; const float* bgl = p->b_gate;
;     asm volatile("" : "+s"(wsl), "+s"(outl), "+s"(bgl));
;     int em = (mode == E_FFX) ? (int)E_FF : (mode == E_DUAL ? (cur_sub ? (int)E_MG : (int)E_M1) : mode);
;     if (mode == 0) { int seg = cur_bcol >> 10; em = seg >= 5 ? E_G : seg; }
;     switch (em) {
;       case E_U:  epi_store<E_U>(wsl, outl, bgl, g0, acc, rbase, cbase); break;
;       case E_GV: epi_store<E_GV>(wsl, outl, bgl, g0, acc, rbase, cbase); break;
;       case E_Q:  epi_store<E_Q>(wsl, outl, bgl, g0, acc, rbase, cbase); break;
;       case E_K:  epi_store<E_K>(wsl, outl, bgl, g0, acc, rbase, cbase); break;
;       case E_V:  epi_store<E_V>(wsl, outl, bgl, g0, acc, rbase, cbase); break;
;       case E_G:  epi_store<E_G>(wsl, outl, bgl, g0, acc, rbase, cbase); break;
;       case E_M1: epi_store<E_M1>(wsl, outl, bgl, g0, acc, rbase, cbase); break;
;       case E_MG: epi_store<E_MG>(wsl, outl, bgl, g0, acc, rbase, cbase); break;
;       case E_T:  epi_store<E_T>(wsl, outl, bgl, g0, acc, rbase, cbase); break;
;       default:   epi_store<E_FF>(wsl, outl, bgl, g0, acc, rbase, cbase); break;
;     }
.LBB0_583:
	v_readlane_b32 s2, v255, 21
	v_readlane_b32 s3, v255, 22
	s_mov_b64 s[6:7], -1
	s_and_b64 vcc, exec, s[2:3]
	s_cbranch_vccz .LBB0_620
	s_and_b64 s[4:5], s[4:5], exec
	s_cselect_b32 s8, 6, 7
	s_and_b64 s[4:5], s[30:31], exec
	v_readlane_b32 s4, v255, 29
	v_add_u32_e32 v142, s35, v1
	v_add_u32_e32 v140, s56, v184
	s_cselect_b32 s8, s8, s4
	s_ashr_i32 s4, s56, 10
	s_load_dwordx2 s[6:7], s[0:1], 0xb8
	s_load_dwordx2 s[10:11], s[0:1], 0x60
	s_load_dwordx2 s[2:3], s[0:1], 0xc0
	s_min_i32 s9, s4, 5
	v_readlane_b32 s4, v255, 14
	v_readlane_b32 s5, v255, 15
	s_and_b64 s[4:5], s[4:5], exec
	s_cselect_b32 s16, s9, s8
	s_mov_b64 s[12:13], -1
	s_mov_b64 s[8:9], 0
	s_cmp_lt_i32 s16, 4
	s_mov_b64 s[4:5], 0
	s_waitcnt lgkmcnt(0)
	s_cbranch_scc1 .LBB0_603
	s_cmp_gt_i32 s16, 5
	s_cbranch_scc0 .LBB0_597
	s_cmp_gt_i32 s16, 6
	s_cbranch_scc0 .LBB0_594
	s_cmp_gt_i32 s16, 7
	s_cbranch_scc0 .LBB0_591
	s_cmp_eq_u32 s16, 8
	s_mov_b64 s[4:5], -1
	s_cbranch_scc0 .LBB0_590
	v_bfe_u32 v141, v184, 2, 2
	v_and_b32_e32 v143, 1, v141
	v_lshrrev_b32_e32 v187, 1, v141
	v_lshlrev_b32_e32 v143, 4, v143
	v_lshl_add_u32 v143, v187, 3, v143
	v_lshlrev_b32_e32 v141, 2, v141
	v_sub_u32_e32 v143, v143, v141
	v_add_u32_e32 v143, v140, v143
	v_lshlrev_b32_e32 v141, 11, v142
	v_lshl_add_u32 v250, v143, 1, v141
	v_add_u32_e32 v251, 0x8000, v250
	v_add_u32_e32 v252, 0x10000, v250
	v_add_u32_e32 v253, 0x18000, v250
	s_add_u32 s4, s2, 0x2aec0000
	s_addc_u32 s5, s3, 0
	s_add_u32 s6, s2, 0x2af00000
	s_addc_u32 s7, s3, 0
	v_cvt_pk_bf16_f32 v144, v126, v127
	v_cvt_pk_bf16_f32 v145, v128, v129
	v_cvt_pk_bf16_f32 v146, v122, v123
	v_cvt_pk_bf16_f32 v147, v124, v125
	v_cvt_pk_bf16_f32 v148, v118, v119
	v_cvt_pk_bf16_f32 v149, v120, v121
	v_cvt_pk_bf16_f32 v150, v114, v115
	v_cvt_pk_bf16_f32 v151, v116, v117
	v_permlane16_swap_b32_e32 v144, v146
	v_permlane16_swap_b32_e32 v145, v147
	global_store_dwordx4 v250, v[144:147], s[4:5]
	v_cvt_pk_bf16_f32 v152, v110, v111
	v_cvt_pk_bf16_f32 v153, v112, v113
	v_cvt_pk_bf16_f32 v154, v106, v107
	v_cvt_pk_bf16_f32 v155, v108, v109
	v_permlane16_swap_b32_e32 v148, v150
	v_permlane16_swap_b32_e32 v149, v151
	global_store_dwordx4 v251, v[148:151], s[4:5]
	v_cvt_pk_bf16_f32 v156, v102, v103
	v_cvt_pk_bf16_f32 v157, v104, v105
	v_cvt_pk_bf16_f32 v158, v98, v99
	v_cvt_pk_bf16_f32 v159, v100, v101
	v_permlane16_swap_b32_e32 v152, v154
	v_permlane16_swap_b32_e32 v153, v155
	global_store_dwordx4 v252, v[152:155], s[4:5]
	v_cvt_pk_bf16_f32 v144, v94, v95
	v_cvt_pk_bf16_f32 v145, v96, v97
	v_cvt_pk_bf16_f32 v146, v90, v91
	v_cvt_pk_bf16_f32 v147, v92, v93
	v_permlane16_swap_b32_e32 v156, v158
	v_permlane16_swap_b32_e32 v157, v159
	global_store_dwordx4 v253, v[156:159], s[4:5]
	v_cvt_pk_bf16_f32 v148, v86, v87
	v_cvt_pk_bf16_f32 v149, v88, v89
	v_cvt_pk_bf16_f32 v150, v82, v83
	v_cvt_pk_bf16_f32 v151, v84, v85
	v_permlane16_swap_b32_e32 v144, v146
	v_permlane16_swap_b32_e32 v145, v147
	global_store_dwordx4 v250, v[144:147], s[4:5] offset:256
	v_cvt_pk_bf16_f32 v152, v78, v79
	v_cvt_pk_bf16_f32 v153, v80, v81
	v_cvt_pk_bf16_f32 v154, v74, v75
	v_cvt_pk_bf16_f32 v155, v76, v77
	v_permlane16_swap_b32_e32 v148, v150
	v_permlane16_swap_b32_e32 v149, v151
	global_store_dwordx4 v251, v[148:151], s[4:5] offset:256
	v_cvt_pk_bf16_f32 v156, v70, v71
	v_cvt_pk_bf16_f32 v157, v72, v73
	v_cvt_pk_bf16_f32 v158, v66, v67
	v_cvt_pk_bf16_f32 v159, v68, v69
	v_permlane16_swap_b32_e32 v152, v154
	v_permlane16_swap_b32_e32 v153, v155
	global_store_dwordx4 v252, v[152:155], s[4:5] offset:256
	v_cvt_pk_bf16_f32 v144, v62, v63
	v_cvt_pk_bf16_f32 v145, v64, v65
	v_cvt_pk_bf16_f32 v146, v58, v59
	v_cvt_pk_bf16_f32 v147, v60, v61
	v_permlane16_swap_b32_e32 v156, v158
	v_permlane16_swap_b32_e32 v157, v159
	global_store_dwordx4 v253, v[156:159], s[4:5] offset:256
	v_cvt_pk_bf16_f32 v148, v54, v55
	v_cvt_pk_bf16_f32 v149, v56, v57
	v_cvt_pk_bf16_f32 v150, v50, v51
	v_cvt_pk_bf16_f32 v151, v52, v53
	v_permlane16_swap_b32_e32 v144, v146
	v_permlane16_swap_b32_e32 v145, v147
	global_store_dwordx4 v250, v[144:147], s[6:7]
	v_cvt_pk_bf16_f32 v152, v46, v47
	v_cvt_pk_bf16_f32 v153, v48, v49
	v_cvt_pk_bf16_f32 v154, v42, v43
	v_cvt_pk_bf16_f32 v155, v44, v45
	v_permlane16_swap_b32_e32 v148, v150
	v_permlane16_swap_b32_e32 v149, v151
	global_store_dwordx4 v251, v[148:151], s[6:7]
	v_cvt_pk_bf16_f32 v156, v38, v39
	v_cvt_pk_bf16_f32 v157, v40, v41
	v_cvt_pk_bf16_f32 v158, v34, v35
	v_cvt_pk_bf16_f32 v159, v36, v37
	v_permlane16_swap_b32_e32 v152, v154
	v_permlane16_swap_b32_e32 v153, v155
	global_store_dwordx4 v252, v[152:155], s[6:7]
	v_cvt_pk_bf16_f32 v144, v30, v31
	v_cvt_pk_bf16_f32 v145, v32, v33
	v_cvt_pk_bf16_f32 v146, v26, v27
	v_cvt_pk_bf16_f32 v147, v28, v29
	v_permlane16_swap_b32_e32 v156, v158
	v_permlane16_swap_b32_e32 v157, v159
	global_store_dwordx4 v253, v[156:159], s[6:7]
	v_cvt_pk_bf16_f32 v148, v22, v23
	v_cvt_pk_bf16_f32 v149, v24, v25
	v_cvt_pk_bf16_f32 v150, v18, v19
	v_cvt_pk_bf16_f32 v151, v20, v21
	v_permlane16_swap_b32_e32 v144, v146
	v_permlane16_swap_b32_e32 v145, v147
	global_store_dwordx4 v250, v[144:147], s[6:7] offset:256
	v_cvt_pk_bf16_f32 v152, v14, v15
	v_cvt_pk_bf16_f32 v153, v16, v17
	v_cvt_pk_bf16_f32 v154, v10, v11
	v_cvt_pk_bf16_f32 v155, v12, v13
	v_permlane16_swap_b32_e32 v148, v150
	v_permlane16_swap_b32_e32 v149, v151
	global_store_dwordx4 v251, v[148:151], s[6:7] offset:256
	v_cvt_pk_bf16_f32 v156, v6, v7
	v_cvt_pk_bf16_f32 v157, v8, v9
	v_cvt_pk_bf16_f32 v158, v2, v3
	v_cvt_pk_bf16_f32 v159, v4, v5
	v_permlane16_swap_b32_e32 v152, v154
	v_permlane16_swap_b32_e32 v153, v155
	global_store_dwordx4 v252, v[152:155], s[6:7] offset:256
	s_nop 1
	v_permlane16_swap_b32_e32 v156, v158
	v_permlane16_swap_b32_e32 v157, v159
	global_store_dwordx4 v253, v[156:159], s[6:7] offset:256
	s_waitcnt vmcnt(16)
	s_branch .LBB0_619

; #define GAS __attribute__((address_space(1)))
; __device__ __forceinline__ uint2 pack4(f32x4 v) { return make_uint2(pack2(v[0], v[1]), pack2(v[2], v[3])); }
; template <int MODE>
; __device__ __forceinline__ void epi_elem(char* ws, float* outp, const float* b_gate, int g0, int rl, int col, f32x4 v) {
;     ...
;   } else if (MODE == E_K) {
;     int lc = col & 1023;
;     *(GAS uint2*)((u16*)(ws + W_K) + (size_t)rl * 1024 + lc) = pack4(v);
;     int rg = g0 + rl;
;     float* o = rg < NPROMPT ? outp + O_KP + (size_t)rg * 1024 : outp + O_KS + (size_t)(rg - NPROMPT) * 1024;
;     __builtin_nontemporal_store(v, (GAS f32x4*)(o + lc));
.LBB0_603:
	s_and_b64 vcc, exec, s[12:13]
	s_cbranch_vccz .LBB0_615
	s_cmp_gt_i32 s16, 1
	s_mov_b64 s[8:9], -1
	s_cbranch_scc0 .LBB0_610
	s_cmp_gt_i32 s16, 2
	s_cbranch_scc0 .LBB0_607
	s_mov_b32 s16, 0x8000
	v_bfe_u32 v141, v184, 2, 2
	v_and_b32_e32 v143, 1, v141
	v_lshrrev_b32_e32 v187, 1, v141
	v_lshlrev_b32_e32 v143, 4, v143
	v_lshl_add_u32 v143, v187, 3, v143
	v_lshlrev_b32_e32 v141, 2, v141
	v_sub_u32_e32 v143, v143, v141
	v_add_u32_e32 v143, v140, v143
	v_and_b32_e32 v143, 0x3ff, v143
	v_lshlrev_b32_e32 v141, 11, v142
	v_lshl_add_u32 v250, v143, 1, v141
	v_add_u32_e32 v251, 0x8000, v250
	v_add_u32_e32 v252, 0x10000, v250
	v_add_u32_e32 v253, 0x18000, v250
	s_add_u32 s4, s2, 0x128c0000
	s_addc_u32 s5, s3, 0
	s_add_u32 s8, s2, 0x12900000
	s_addc_u32 s9, s3, 0
	s_add_u32 s14, s6, 0x80000
	s_addc_u32 s15, s7, 0
	s_mov_b32 s17, 0x10000
	v_add_u32_e32 v187, s16, v142
	v_and_b32_e32 v141, 0x3ff, v140
	v_cmp_gt_i32_e32 vcc, s17, v187
	v_add_u32_e32 v188, 0xffff0000, v187
	v_lshlrev_b32_e32 v141, 2, v141
	s_nop 0
	v_cndmask_b32_e32 v187, v188, v187, vcc
	v_cndmask_b32_e32 v188, v207, v208, vcc
	v_lshl_add_u32 v187, v187, 12, v188
	v_add_u32_e32 v246, v187, v141
	v_add_u32_e32 v247, 0x10000, v246
	v_add_u32_e32 v248, 0x20000, v246
	v_add_u32_e32 v249, 0x30000, v246
	v_cvt_pk_bf16_f32 v144, v126, v127
	v_cvt_pk_bf16_f32 v145, v128, v129
	v_cvt_pk_bf16_f32 v146, v122, v123
	v_cvt_pk_bf16_f32 v147, v124, v125
	global_store_dwordx4 v246, v[126:129], s[6:7] nt
	global_store_dwordx4 v246, v[122:125], s[6:7] offset:64 nt
	v_cvt_pk_bf16_f32 v148, v118, v119
	v_cvt_pk_bf16_f32 v149, v120, v121
	v_cvt_pk_bf16_f32 v150, v114, v115
	v_cvt_pk_bf16_f32 v151, v116, v117
	global_store_dwordx4 v247, v[118:121], s[6:7] nt
	global_store_dwordx4 v247, v[114:117], s[6:7] offset:64 nt
	v_permlane16_swap_b32_e32 v144, v146
	v_permlane16_swap_b32_e32 v145, v147
	global_store_dwordx4 v250, v[144:147], s[4:5]
	v_cvt_pk_bf16_f32 v152, v110, v111
	v_cvt_pk_bf16_f32 v153, v112, v113
	v_cvt_pk_bf16_f32 v154, v106, v107
	v_cvt_pk_bf16_f32 v155, v108, v109
	global_store_dwordx4 v248, v[110:113], s[6:7] nt
	global_store_dwordx4 v248, v[106:109], s[6:7] offset:64 nt
	v_permlane16_swap_b32_e32 v148, v150
	v_permlane16_swap_b32_e32 v149, v151
	global_store_dwordx4 v251, v[148:151], s[4:5]
	v_cvt_pk_bf16_f32 v156, v102, v103
	v_cvt_pk_bf16_f32 v157, v104, v105
	v_cvt_pk_bf16_f32 v158, v98, v99
	v_cvt_pk_bf16_f32 v159, v100, v101
	global_store_dwordx4 v249, v[102:105], s[6:7] nt
	global_store_dwordx4 v249, v[98:101], s[6:7] offset:64 nt
	v_permlane16_swap_b32_e32 v152, v154
	v_permlane16_swap_b32_e32 v153, v155
	global_store_dwordx4 v252, v[152:155], s[4:5]
	v_cvt_pk_bf16_f32 v144, v94, v95
	v_cvt_pk_bf16_f32 v145, v96, v97
	v_cvt_pk_bf16_f32 v146, v90, v91
	v_cvt_pk_bf16_f32 v147, v92, v93
	global_store_dwordx4 v246, v[94:97], s[6:7] offset:512 nt
	global_store_dwordx4 v246, v[90:93], s[6:7] offset:576 nt
	v_permlane16_swap_b32_e32 v156, v158
	v_permlane16_swap_b32_e32 v157, v159
	global_store_dwordx4 v253, v[156:159], s[4:5]
	v_cvt_pk_bf16_f32 v148, v86, v87
	v_cvt_pk_bf16_f32 v149, v88, v89
	v_cvt_pk_bf16_f32 v150, v82, v83
	v_cvt_pk_bf16_f32 v151, v84, v85
	global_store_dwordx4 v247, v[86:89], s[6:7] offset:512 nt
	global_store_dwordx4 v247, v[82:85], s[6:7] offset:576 nt
	v_permlane16_swap_b32_e32 v144, v146
	v_permlane16_swap_b32_e32 v145, v147
	global_store_dwordx4 v250, v[144:147], s[4:5] offset:256
	v_cvt_pk_bf16_f32 v152, v78, v79
	v_cvt_pk_bf16_f32 v153, v80, v81
	v_cvt_pk_bf16_f32 v154, v74, v75
	v_cvt_pk_bf16_f32 v155, v76, v77
	global_store_dwordx4 v248, v[78:81], s[6:7] offset:512 nt
	global_store_dwordx4 v248, v[74:77], s[6:7] offset:576 nt
	v_permlane16_swap_b32_e32 v148, v150
	v_permlane16_swap_b32_e32 v149, v151
	global_store_dwordx4 v251, v[148:151], s[4:5] offset:256
	v_cvt_pk_bf16_f32 v156, v70, v71
	v_cvt_pk_bf16_f32 v157, v72, v73
	v_cvt_pk_bf16_f32 v158, v66, v67
	v_cvt_pk_bf16_f32 v159, v68, v69
	global_store_dwordx4 v249, v[70:73], s[6:7] offset:512 nt
	global_store_dwordx4 v249, v[66:69], s[6:7] offset:576 nt
	v_permlane16_swap_b32_e32 v152, v154
	v_permlane16_swap_b32_e32 v153, v155
	global_store_dwordx4 v252, v[152:155], s[4:5] offset:256
	v_cvt_pk_bf16_f32 v144, v62, v63
	v_cvt_pk_bf16_f32 v145, v64, v65
	v_cvt_pk_bf16_f32 v146, v58, v59
	v_cvt_pk_bf16_f32 v147, v60, v61
	global_store_dwordx4 v246, v[62:65], s[14:15] nt
	global_store_dwordx4 v246, v[58:61], s[14:15] offset:64 nt
	v_permlane16_swap_b32_e32 v156, v158
	v_permlane16_swap_b32_e32 v157, v159
	global_store_dwordx4 v253, v[156:159], s[4:5] offset:256
	v_cvt_pk_bf16_f32 v148, v54, v55
	v_cvt_pk_bf16_f32 v149, v56, v57
	v_cvt_pk_bf16_f32 v150, v50, v51
	v_cvt_pk_bf16_f32 v151, v52, v53
	global_store_dwordx4 v247, v[54:57], s[14:15] nt
	global_store_dwordx4 v247, v[50:53], s[14:15] offset:64 nt
	v_permlane16_swap_b32_e32 v144, v146
	v_permlane16_swap_b32_e32 v145, v147
	global_store_dwordx4 v250, v[144:147], s[8:9]
	v_cvt_pk_bf16_f32 v152, v46, v47
	v_cvt_pk_bf16_f32 v153, v48, v49
	v_cvt_pk_bf16_f32 v154, v42, v43
	v_cvt_pk_bf16_f32 v155, v44, v45
	global_store_dwordx4 v248, v[46:49], s[14:15] nt
	global_store_dwordx4 v248, v[42:45], s[14:15] offset:64 nt
	v_permlane16_swap_b32_e32 v148, v150
	v_permlane16_swap_b32_e32 v149, v151
	global_store_dwordx4 v251, v[148:151], s[8:9]
	v_cvt_pk_bf16_f32 v156, v38, v39
	v_cvt_pk_bf16_f32 v157, v40, v41
	v_cvt_pk_bf16_f32 v158, v34, v35
	v_cvt_pk_bf16_f32 v159, v36, v37
	global_store_dwordx4 v249, v[38:41], s[14:15] nt
	global_store_dwordx4 v249, v[34:37], s[14:15] offset:64 nt
	v_permlane16_swap_b32_e32 v152, v154
	v_permlane16_swap_b32_e32 v153, v155
; #define GAS __attribute__((address_space(1)))
; __device__ __forceinline__ uint2 pack4(f32x4 v) { return make_uint2(pack2(v[0], v[1]), pack2(v[2], v[3])); }
; template <int MODE>
; __device__ __forceinline__ void epi_elem(char* ws, float* outp, const float* b_gate, int g0, int rl, int col, f32x4 v) {
;     ...
;   } else if (MODE == E_Q) {
;     int lc = col & 1023;
;     f32x4 o = v * 0.18033688011112042f;
;     *(GAS uint2*)((u16*)(ws + W_Q) + (size_t)rl * 1024 + lc) = pack4(o);
;   } else if (MODE == E_K) {
;     int lc = col & 1023;
;     *(GAS uint2*)((u16*)(ws + W_K) + (size_t)rl * 1024 + lc) = pack4(v);
;     int rg = g0 + rl;
;     float* o = rg < NPROMPT ? outp + O_KP + (size_t)rg * 1024 : outp + O_KS + (size_t)(rg - NPROMPT) * 1024;
;     __builtin_nontemporal_store(v, (GAS f32x4*)(o + lc));
	global_store_dwordx4 v252, v[152:155], s[8:9]
	v_cvt_pk_bf16_f32 v144, v30, v31
	v_cvt_pk_bf16_f32 v145, v32, v33
	v_cvt_pk_bf16_f32 v146, v26, v27
	v_cvt_pk_bf16_f32 v147, v28, v29
	global_store_dwordx4 v246, v[30:33], s[14:15] offset:512 nt
	global_store_dwordx4 v246, v[26:29], s[14:15] offset:576 nt
	v_permlane16_swap_b32_e32 v156, v158
	v_permlane16_swap_b32_e32 v157, v159
	global_store_dwordx4 v253, v[156:159], s[8:9]
	v_cvt_pk_bf16_f32 v148, v22, v23
	v_cvt_pk_bf16_f32 v149, v24, v25
	v_cvt_pk_bf16_f32 v150, v18, v19
	v_cvt_pk_bf16_f32 v151, v20, v21
	global_store_dwordx4 v247, v[22:25], s[14:15] offset:512 nt
	global_store_dwordx4 v247, v[18:21], s[14:15] offset:576 nt
	v_permlane16_swap_b32_e32 v144, v146
	v_permlane16_swap_b32_e32 v145, v147
	global_store_dwordx4 v250, v[144:147], s[8:9] offset:256
	v_cvt_pk_bf16_f32 v152, v14, v15
	v_cvt_pk_bf16_f32 v153, v16, v17
	v_cvt_pk_bf16_f32 v154, v10, v11
	v_cvt_pk_bf16_f32 v155, v12, v13
	global_store_dwordx4 v248, v[14:17], s[14:15] offset:512 nt
	global_store_dwordx4 v248, v[10:13], s[14:15] offset:576 nt
	v_permlane16_swap_b32_e32 v148, v150
	v_permlane16_swap_b32_e32 v149, v151
	global_store_dwordx4 v251, v[148:151], s[8:9] offset:256
	v_cvt_pk_bf16_f32 v156, v6, v7
	v_cvt_pk_bf16_f32 v157, v8, v9
	v_cvt_pk_bf16_f32 v158, v2, v3
	v_cvt_pk_bf16_f32 v159, v4, v5
	global_store_dwordx4 v249, v[6:9], s[14:15] offset:512 nt
	global_store_dwordx4 v249, v[2:5], s[14:15] offset:576 nt
	v_permlane16_swap_b32_e32 v152, v154
	v_permlane16_swap_b32_e32 v153, v155
	global_store_dwordx4 v252, v[152:155], s[8:9] offset:256
	s_nop 1
	v_permlane16_swap_b32_e32 v156, v158
	v_permlane16_swap_b32_e32 v157, v159
	global_store_dwordx4 v253, v[156:159], s[8:9] offset:256
	s_waitcnt vmcnt(48)
	s_branch .LBB0_619
.LBB0_607:
	s_andn2_b64 vcc, exec, s[8:9]
	s_cbranch_vccnz .LBB0_609
	v_bfe_u32 v141, v184, 2, 2
	v_and_b32_e32 v143, 1, v141
	v_lshrrev_b32_e32 v187, 1, v141
	v_lshlrev_b32_e32 v143, 4, v143
	v_lshl_add_u32 v143, v187, 3, v143
	v_lshlrev_b32_e32 v141, 2, v141
	v_sub_u32_e32 v143, v143, v141
	v_add_u32_e32 v143, v140, v143
	v_and_b32_e32 v143, 0x3ff, v143
	v_lshlrev_b32_e32 v141, 11, v142
	v_lshl_add_u32 v250, v143, 1, v141
	v_add_u32_e32 v251, 0x8000, v250
	v_add_u32_e32 v252, 0x10000, v250
	v_add_u32_e32 v253, 0x18000, v250
	s_add_u32 s4, s2, 0xe7c0000
	s_addc_u32 s5, s3, 0
	s_add_u32 s6, s2, 0xe800000
	s_addc_u32 s7, s3, 0
	s_mov_b32 s18, 0x3e38aa3b
	v_mul_f32_e32 v160, s18, v126
	v_mul_f32_e32 v161, s18, v127
	v_mul_f32_e32 v162, s18, v128
	v_mul_f32_e32 v163, s18, v129
	v_mul_f32_e32 v164, s18, v122
	v_mul_f32_e32 v165, s18, v123
	v_mul_f32_e32 v166, s18, v124
	v_mul_f32_e32 v167, s18, v125
	v_cvt_pk_bf16_f32 v144, v160, v161
	v_cvt_pk_bf16_f32 v145, v162, v163
	v_cvt_pk_bf16_f32 v146, v164, v165
	v_cvt_pk_bf16_f32 v147, v166, v167
	v_mul_f32_e32 v168, s18, v118
	v_mul_f32_e32 v169, s18, v119
	v_mul_f32_e32 v170, s18, v120
	v_mul_f32_e32 v171, s18, v121
	v_mul_f32_e32 v172, s18, v114
	v_mul_f32_e32 v173, s18, v115
	v_mul_f32_e32 v174, s18, v116
	v_mul_f32_e32 v175, s18, v117
	v_cvt_pk_bf16_f32 v148, v168, v169
	v_cvt_pk_bf16_f32 v149, v170, v171
	v_cvt_pk_bf16_f32 v150, v172, v173
	v_cvt_pk_bf16_f32 v151, v174, v175
	v_permlane16_swap_b32_e32 v144, v146
	v_permlane16_swap_b32_e32 v145, v147
	global_store_dwordx4 v250, v[144:147], s[4:5]
	v_mul_f32_e32 v160, s18, v110
	v_mul_f32_e32 v161, s18, v111
	v_mul_f32_e32 v162, s18, v112
	v_mul_f32_e32 v163, s18, v113
	v_mul_f32_e32 v164, s18, v106
	v_mul_f32_e32 v165, s18, v107
	v_mul_f32_e32 v166, s18, v108
	v_mul_f32_e32 v167, s18, v109
	v_cvt_pk_bf16_f32 v152, v160, v161
	v_cvt_pk_bf16_f32 v153, v162, v163
	v_cvt_pk_bf16_f32 v154, v164, v165
	v_cvt_pk_bf16_f32 v155, v166, v167
	v_permlane16_swap_b32_e32 v148, v150
	v_permlane16_swap_b32_e32 v149, v151
	global_store_dwordx4 v251, v[148:151], s[4:5]
	v_mul_f32_e32 v168, s18, v102
	v_mul_f32_e32 v169, s18, v103
	v_mul_f32_e32 v170, s18, v104
	v_mul_f32_e32 v171, s18, v105
	v_mul_f32_e32 v172, s18, v98
	v_mul_f32_e32 v173, s18, v99
	v_mul_f32_e32 v174, s18, v100
	v_mul_f32_e32 v175, s18, v101
	v_cvt_pk_bf16_f32 v156, v168, v169
	v_cvt_pk_bf16_f32 v157, v170, v171
	v_cvt_pk_bf16_f32 v158, v172, v173
	v_cvt_pk_bf16_f32 v159, v174, v175
	v_permlane16_swap_b32_e32 v152, v154
	v_permlane16_swap_b32_e32 v153, v155
	global_store_dwordx4 v252, v[152:155], s[4:5]
	v_mul_f32_e32 v160, s18, v94
	v_mul_f32_e32 v161, s18, v95
	v_mul_f32_e32 v162, s18, v96
	v_mul_f32_e32 v163, s18, v97
	v_mul_f32_e32 v164, s18, v90
	v_mul_f32_e32 v165, s18, v91
	v_mul_f32_e32 v166, s18, v92
	v_mul_f32_e32 v167, s18, v93
	v_cvt_pk_bf16_f32 v144, v160, v161
	v_cvt_pk_bf16_f32 v145, v162, v163
	v_cvt_pk_bf16_f32 v146, v164, v165
	v_cvt_pk_bf16_f32 v147, v166, v167
	v_permlane16_swap_b32_e32 v156, v158
	v_permlane16_swap_b32_e32 v157, v159
	global_store_dwordx4 v253, v[156:159], s[4:5]
	v_mul_f32_e32 v168, s18, v86
	v_mul_f32_e32 v169, s18, v87
	v_mul_f32_e32 v170, s18, v88
	v_mul_f32_e32 v171, s18, v89
	v_mul_f32_e32 v172, s18, v82
	v_mul_f32_e32 v173, s18, v83
	v_mul_f32_e32 v174, s18, v84
	v_mul_f32_e32 v175, s18, v85
	v_cvt_pk_bf16_f32 v148, v168, v169
	v_cvt_pk_bf16_f32 v149, v170, v171
	v_cvt_pk_bf16_f32 v150, v172, v173
	v_cvt_pk_bf16_f32 v151, v174, v175
	v_permlane16_swap_b32_e32 v144, v146
	v_permlane16_swap_b32_e32 v145, v147
; #define GAS __attribute__((address_space(1)))
; __device__ __forceinline__ uint2 pack4(f32x4 v) { return make_uint2(pack2(v[0], v[1]), pack2(v[2], v[3])); }
; template <int MODE>
; __device__ __forceinline__ void epi_elem(char* ws, float* outp, const float* b_gate, int g0, int rl, int col, f32x4 v) {
;     ...
;   } else if (MODE == E_Q) {
;     int lc = col & 1023;
;     f32x4 o = v * 0.18033688011112042f;
;     *(GAS uint2*)((u16*)(ws + W_Q) + (size_t)rl * 1024 + lc) = pack4(o);
	global_store_dwordx4 v250, v[144:147], s[4:5] offset:256
	v_mul_f32_e32 v160, s18, v78
	v_mul_f32_e32 v161, s18, v79
	v_mul_f32_e32 v162, s18, v80
	v_mul_f32_e32 v163, s18, v81
	v_mul_f32_e32 v164, s18, v74
	v_mul_f32_e32 v165, s18, v75
	v_mul_f32_e32 v166, s18, v76
	v_mul_f32_e32 v167, s18, v77
	v_cvt_pk_bf16_f32 v152, v160, v161
	v_cvt_pk_bf16_f32 v153, v162, v163
	v_cvt_pk_bf16_f32 v154, v164, v165
	v_cvt_pk_bf16_f32 v155, v166, v167
	v_permlane16_swap_b32_e32 v148, v150
	v_permlane16_swap_b32_e32 v149, v151
	global_store_dwordx4 v251, v[148:151], s[4:5] offset:256
	v_mul_f32_e32 v168, s18, v70
	v_mul_f32_e32 v169, s18, v71
	v_mul_f32_e32 v170, s18, v72
	v_mul_f32_e32 v171, s18, v73
	v_mul_f32_e32 v172, s18, v66
	v_mul_f32_e32 v173, s18, v67
	v_mul_f32_e32 v174, s18, v68
	v_mul_f32_e32 v175, s18, v69
	v_cvt_pk_bf16_f32 v156, v168, v169
	v_cvt_pk_bf16_f32 v157, v170, v171
	v_cvt_pk_bf16_f32 v158, v172, v173
	v_cvt_pk_bf16_f32 v159, v174, v175
	v_permlane16_swap_b32_e32 v152, v154
	v_permlane16_swap_b32_e32 v153, v155
	global_store_dwordx4 v252, v[152:155], s[4:5] offset:256
	v_mul_f32_e32 v160, s18, v62
	v_mul_f32_e32 v161, s18, v63
	v_mul_f32_e32 v162, s18, v64
	v_mul_f32_e32 v163, s18, v65
	v_mul_f32_e32 v164, s18, v58
	v_mul_f32_e32 v165, s18, v59
	v_mul_f32_e32 v166, s18, v60
	v_mul_f32_e32 v167, s18, v61
	v_cvt_pk_bf16_f32 v144, v160, v161
	v_cvt_pk_bf16_f32 v145, v162, v163
	v_cvt_pk_bf16_f32 v146, v164, v165
	v_cvt_pk_bf16_f32 v147, v166, v167
	v_permlane16_swap_b32_e32 v156, v158
	v_permlane16_swap_b32_e32 v157, v159
	global_store_dwordx4 v253, v[156:159], s[4:5] offset:256
	v_mul_f32_e32 v168, s18, v54
	v_mul_f32_e32 v169, s18, v55
	v_mul_f32_e32 v170, s18, v56
	v_mul_f32_e32 v171, s18, v57
	v_mul_f32_e32 v172, s18, v50
	v_mul_f32_e32 v173, s18, v51
	v_mul_f32_e32 v174, s18, v52
	v_mul_f32_e32 v175, s18, v53
	v_cvt_pk_bf16_f32 v148, v168, v169
	v_cvt_pk_bf16_f32 v149, v170, v171
	v_cvt_pk_bf16_f32 v150, v172, v173
	v_cvt_pk_bf16_f32 v151, v174, v175
	v_permlane16_swap_b32_e32 v144, v146
	v_permlane16_swap_b32_e32 v145, v147
	global_store_dwordx4 v250, v[144:147], s[6:7]
	v_mul_f32_e32 v160, s18, v46
	v_mul_f32_e32 v161, s18, v47
	v_mul_f32_e32 v162, s18, v48
	v_mul_f32_e32 v163, s18, v49
	v_mul_f32_e32 v164, s18, v42
	v_mul_f32_e32 v165, s18, v43
	v_mul_f32_e32 v166, s18, v44
	v_mul_f32_e32 v167, s18, v45
	v_cvt_pk_bf16_f32 v152, v160, v161
	v_cvt_pk_bf16_f32 v153, v162, v163
	v_cvt_pk_bf16_f32 v154, v164, v165
	v_cvt_pk_bf16_f32 v155, v166, v167
	v_permlane16_swap_b32_e32 v148, v150
	v_permlane16_swap_b32_e32 v149, v151
	global_store_dwordx4 v251, v[148:151], s[6:7]
	v_mul_f32_e32 v168, s18, v38
	v_mul_f32_e32 v169, s18, v39
	v_mul_f32_e32 v170, s18, v40
	v_mul_f32_e32 v171, s18, v41
	v_mul_f32_e32 v172, s18, v34
	v_mul_f32_e32 v173, s18, v35
	v_mul_f32_e32 v174, s18, v36
	v_mul_f32_e32 v175, s18, v37
	v_cvt_pk_bf16_f32 v156, v168, v169
	v_cvt_pk_bf16_f32 v157, v170, v171
	v_cvt_pk_bf16_f32 v158, v172, v173
	v_cvt_pk_bf16_f32 v159, v174, v175
	v_permlane16_swap_b32_e32 v152, v154
	v_permlane16_swap_b32_e32 v153, v155
	global_store_dwordx4 v252, v[152:155], s[6:7]
	v_mul_f32_e32 v160, s18, v30
	v_mul_f32_e32 v161, s18, v31
	v_mul_f32_e32 v162, s18, v32
	v_mul_f32_e32 v163, s18, v33
	v_mul_f32_e32 v164, s18, v26
	v_mul_f32_e32 v165, s18, v27
	v_mul_f32_e32 v166, s18, v28
	v_mul_f32_e32 v167, s18, v29
	v_cvt_pk_bf16_f32 v144, v160, v161
	v_cvt_pk_bf16_f32 v145, v162, v163
	v_cvt_pk_bf16_f32 v146, v164, v165
	v_cvt_pk_bf16_f32 v147, v166, v167
	v_permlane16_swap_b32_e32 v156, v158
	v_permlane16_swap_b32_e32 v157, v159
	global_store_dwordx4 v253, v[156:159], s[6:7]
	v_mul_f32_e32 v168, s18, v22
	v_mul_f32_e32 v169, s18, v23
	v_mul_f32_e32 v170, s18, v24
	v_mul_f32_e32 v171, s18, v25
	v_mul_f32_e32 v172, s18, v18
	v_mul_f32_e32 v173, s18, v19
	v_mul_f32_e32 v174, s18, v20
	v_mul_f32_e32 v175, s18, v21
	v_cvt_pk_bf16_f32 v148, v168, v169
	v_cvt_pk_bf16_f32 v149, v170, v171
	v_cvt_pk_bf16_f32 v150, v172, v173
	v_cvt_pk_bf16_f32 v151, v174, v175
	v_permlane16_swap_b32_e32 v144, v146
	v_permlane16_swap_b32_e32 v145, v147
	global_store_dwordx4 v250, v[144:147], s[6:7] offset:256
	v_mul_f32_e32 v160, s18, v14
	v_mul_f32_e32 v161, s18, v15
	v_mul_f32_e32 v162, s18, v16
	v_mul_f32_e32 v163, s18, v17
	v_mul_f32_e32 v164, s18, v10
	v_mul_f32_e32 v165, s18, v11
	v_mul_f32_e32 v166, s18, v12
	v_mul_f32_e32 v167, s18, v13
	v_cvt_pk_bf16_f32 v152, v160, v161
	v_cvt_pk_bf16_f32 v153, v162, v163
	v_cvt_pk_bf16_f32 v154, v164, v165
	v_cvt_pk_bf16_f32 v155, v166, v167
	v_permlane16_swap_b32_e32 v148, v150
	v_permlane16_swap_b32_e32 v149, v151
	global_store_dwordx4 v251, v[148:151], s[6:7] offset:256
	v_mul_f32_e32 v168, s18, v6
	v_mul_f32_e32 v169, s18, v7
	v_mul_f32_e32 v170, s18, v8
	v_mul_f32_e32 v171, s18, v9
	v_mul_f32_e32 v172, s18, v2
	v_mul_f32_e32 v173, s18, v3
	v_mul_f32_e32 v174, s18, v4
	v_mul_f32_e32 v175, s18, v5
	v_cvt_pk_bf16_f32 v156, v168, v169
	v_cvt_pk_bf16_f32 v157, v170, v171
	v_cvt_pk_bf16_f32 v158, v172, v173
	v_cvt_pk_bf16_f32 v159, v174, v175
	v_permlane16_swap_b32_e32 v152, v154
	v_permlane16_swap_b32_e32 v153, v155
	global_store_dwordx4 v252, v[152:155], s[6:7] offset:256
	s_nop 1
	v_permlane16_swap_b32_e32 v156, v158
	v_permlane16_swap_b32_e32 v157, v159
	global_store_dwordx4 v253, v[156:159], s[6:7] offset:256
	s_waitcnt vmcnt(16)
	s_branch .LBB0_619

; #define GAS __attribute__((address_space(1)))
; __device__ __forceinline__ uint2 pack4(f32x4 v) { return make_uint2(pack2(v[0], v[1]), pack2(v[2], v[3])); }
; __device__ __forceinline__ float gelu_f(float x) {
;   const float c1 = -1.5957691216057308f * 1.4426950408889634f, c2 = c1 * 0.044715f;
;   float u = x * __builtin_fmaf(x * x, c2, c1);
;   return x * __builtin_amdgcn_rcpf(1.0f + __builtin_amdgcn_exp2f(u));
; }
; template <int MODE>
; __device__ __forceinline__ void epi_elem(char* ws, float* outp, const float* b_gate, int g0, int rl, int col, f32x4 v) {
;   if (MODE == E_U || MODE == E_GV) {
;     int lc = col & 1023;
;     f32x4 o; for (int i = 0; i < 4; ++i) o[i] = gelu_f(v[i]);
;     u16* dst = (u16*)(ws + (MODE == E_U ? W_U : W_GV));
;     *(GAS uint2*)(dst + (size_t)rl * 1024 + lc) = pack4(o);
.LBB0_610:
	s_andn2_b64 vcc, exec, s[8:9]
	s_mov_b64 s[8:9], 0
	s_cbranch_vccnz .LBB0_615
	s_cmp_gt_i32 s16, 0
	s_mov_b64 s[6:7], -1
	s_cbranch_scc0 .LBB0_613
	v_bfe_u32 v141, v184, 2, 2
	v_and_b32_e32 v143, 1, v141
	v_lshrrev_b32_e32 v187, 1, v141
	v_lshlrev_b32_e32 v143, 4, v143
	v_lshl_add_u32 v143, v187, 3, v143
	v_lshlrev_b32_e32 v141, 2, v141
	v_sub_u32_e32 v143, v143, v141
	v_add_u32_e32 v143, v140, v143
	v_and_b32_e32 v143, 0x3ff, v143
	v_lshlrev_b32_e32 v141, 11, v142
	v_lshl_add_u32 v250, v143, 1, v141
	v_add_u32_e32 v251, 0x8000, v250
	v_add_u32_e32 v252, 0x10000, v250
	v_add_u32_e32 v253, 0x18000, v250
	s_add_u32 s4, s2, 0xa6c0000
	s_addc_u32 s5, s3, 0
	s_add_u32 s6, s2, 0xa700000
	s_addc_u32 s7, s3, 0
	s_mov_b32 s18, 0xbdd2d3e7
	v_mul_f32_e32 v160, v126, v126
	v_mul_f32_e32 v161, v127, v127
	v_mul_f32_e32 v162, v128, v128
	v_mul_f32_e32 v163, v129, v129
	v_mul_f32_e32 v164, v122, v122
	v_mul_f32_e32 v165, v123, v123
	v_mul_f32_e32 v166, v124, v124
	v_mul_f32_e32 v167, v125, v125
	v_fma_f32 v160, v160, s18, v198
	v_fma_f32 v161, v161, s18, v198
	v_fma_f32 v162, v162, s18, v198
	v_fma_f32 v163, v163, s18, v198
	v_fma_f32 v164, v164, s18, v198
	v_fma_f32 v165, v165, s18, v198
	v_fma_f32 v166, v166, s18, v198
	v_fma_f32 v167, v167, s18, v198
	v_mul_f32_e32 v160, v126, v160
	v_mul_f32_e32 v161, v127, v161
	v_mul_f32_e32 v162, v128, v162
	v_mul_f32_e32 v163, v129, v163
	v_mul_f32_e32 v164, v122, v164
	v_mul_f32_e32 v165, v123, v165
	v_mul_f32_e32 v166, v124, v166
	v_mul_f32_e32 v167, v125, v167
	v_exp_f32_e32 v160, v160
	v_exp_f32_e32 v161, v161
	v_exp_f32_e32 v162, v162
	v_exp_f32_e32 v163, v163
	v_exp_f32_e32 v164, v164
	v_exp_f32_e32 v165, v165
	v_exp_f32_e32 v166, v166
	v_exp_f32_e32 v167, v167
	v_add_f32_e32 v160, 1.0, v160
	v_add_f32_e32 v161, 1.0, v161
	v_add_f32_e32 v162, 1.0, v162
	v_add_f32_e32 v163, 1.0, v163
	v_add_f32_e32 v164, 1.0, v164
	v_add_f32_e32 v165, 1.0, v165
	v_add_f32_e32 v166, 1.0, v166
	v_add_f32_e32 v167, 1.0, v167
	v_rcp_f32_e32 v160, v160
	v_rcp_f32_e32 v161, v161
	v_rcp_f32_e32 v162, v162
	v_rcp_f32_e32 v163, v163
	v_rcp_f32_e32 v164, v164
	v_rcp_f32_e32 v165, v165
	v_rcp_f32_e32 v166, v166
	v_rcp_f32_e32 v167, v167
	v_mul_f32_e32 v160, v126, v160
	v_mul_f32_e32 v161, v127, v161
	v_mul_f32_e32 v162, v128, v162
	v_mul_f32_e32 v163, v129, v163
	v_mul_f32_e32 v164, v122, v164
	v_mul_f32_e32 v165, v123, v165
	v_mul_f32_e32 v166, v124, v166
	v_mul_f32_e32 v167, v125, v167
	v_cvt_pk_bf16_f32 v144, v160, v161
	v_cvt_pk_bf16_f32 v145, v162, v163
	v_cvt_pk_bf16_f32 v146, v164, v165
	v_cvt_pk_bf16_f32 v147, v166, v167
	v_mul_f32_e32 v168, v118, v118
	v_mul_f32_e32 v169, v119, v119
	v_mul_f32_e32 v170, v120, v120
	v_mul_f32_e32 v171, v121, v121
	v_mul_f32_e32 v172, v114, v114
	v_mul_f32_e32 v173, v115, v115
	v_mul_f32_e32 v174, v116, v116
	v_mul_f32_e32 v175, v117, v117
	v_fma_f32 v168, v168, s18, v198
	v_fma_f32 v169, v169, s18, v198
	v_fma_f32 v170, v170, s18, v198
	v_fma_f32 v171, v171, s18, v198
	v_fma_f32 v172, v172, s18, v198
	v_fma_f32 v173, v173, s18, v198
	v_fma_f32 v174, v174, s18, v198
	v_fma_f32 v175, v175, s18, v198
	v_mul_f32_e32 v168, v118, v168
	v_mul_f32_e32 v169, v119, v169
	v_mul_f32_e32 v170, v120, v170
	v_mul_f32_e32 v171, v121, v171
	v_mul_f32_e32 v172, v114, v172
	v_mul_f32_e32 v173, v115, v173
	v_mul_f32_e32 v174, v116, v174
	v_mul_f32_e32 v175, v117, v175
	v_exp_f32_e32 v168, v168
	v_exp_f32_e32 v169, v169
	v_exp_f32_e32 v170, v170
	v_exp_f32_e32 v171, v171
	v_exp_f32_e32 v172, v172
	v_exp_f32_e32 v173, v173
	v_exp_f32_e32 v174, v174
	v_exp_f32_e32 v175, v175
	v_add_f32_e32 v168, 1.0, v168
	v_add_f32_e32 v169, 1.0, v169
	v_add_f32_e32 v170, 1.0, v170
	v_add_f32_e32 v171, 1.0, v171
	v_add_f32_e32 v172, 1.0, v172
	v_add_f32_e32 v173, 1.0, v173
	v_add_f32_e32 v174, 1.0, v174
	v_add_f32_e32 v175, 1.0, v175
	v_rcp_f32_e32 v168, v168
	v_rcp_f32_e32 v169, v169
	v_rcp_f32_e32 v170, v170
	v_rcp_f32_e32 v171, v171
	v_rcp_f32_e32 v172, v172
	v_rcp_f32_e32 v173, v173
	v_rcp_f32_e32 v174, v174
	v_rcp_f32_e32 v175, v175
	v_mul_f32_e32 v168, v118, v168
	v_mul_f32_e32 v169, v119, v169
	v_mul_f32_e32 v170, v120, v170
	v_mul_f32_e32 v171, v121, v171
	v_mul_f32_e32 v172, v114, v172
	v_mul_f32_e32 v173, v115, v173
	v_mul_f32_e32 v174, v116, v174
	v_mul_f32_e32 v175, v117, v175
	v_cvt_pk_bf16_f32 v148, v168, v169
	v_cvt_pk_bf16_f32 v149, v170, v171
	v_cvt_pk_bf16_f32 v150, v172, v173
	v_cvt_pk_bf16_f32 v151, v174, v175
	v_permlane16_swap_b32_e32 v144, v146
	v_permlane16_swap_b32_e32 v145, v147
	global_store_dwordx4 v250, v[144:147], s[4:5]
	v_mul_f32_e32 v160, v110, v110
	v_mul_f32_e32 v161, v111, v111
	v_mul_f32_e32 v162, v112, v112
	v_mul_f32_e32 v163, v113, v113
	v_mul_f32_e32 v164, v106, v106
	v_mul_f32_e32 v165, v107, v107
	v_mul_f32_e32 v166, v108, v108
	v_mul_f32_e32 v167, v109, v109
	v_fma_f32 v160, v160, s18, v198
	v_fma_f32 v161, v161, s18, v198
	v_fma_f32 v162, v162, s18, v198
	v_fma_f32 v163, v163, s18, v198
	v_fma_f32 v164, v164, s18, v198
	v_fma_f32 v165, v165, s18, v198
	v_fma_f32 v166, v166, s18, v198
	v_fma_f32 v167, v167, s18, v198
	v_mul_f32_e32 v160, v110, v160
	v_mul_f32_e32 v161, v111, v161
	v_mul_f32_e32 v162, v112, v162
	v_mul_f32_e32 v163, v113, v163
	v_mul_f32_e32 v164, v106, v164
	v_mul_f32_e32 v165, v107, v165
	v_mul_f32_e32 v166, v108, v166
	v_mul_f32_e32 v167, v109, v167
	v_exp_f32_e32 v160, v160
	v_exp_f32_e32 v161, v161
	v_exp_f32_e32 v162, v162
	v_exp_f32_e32 v163, v163
	v_exp_f32_e32 v164, v164
	v_exp_f32_e32 v165, v165
	v_exp_f32_e32 v166, v166
	v_exp_f32_e32 v167, v167
	v_add_f32_e32 v160, 1.0, v160
	v_add_f32_e32 v161, 1.0, v161
	v_add_f32_e32 v162, 1.0, v162
; #define GAS __attribute__((address_space(1)))
; __device__ __forceinline__ uint2 pack4(f32x4 v) { return make_uint2(pack2(v[0], v[1]), pack2(v[2], v[3])); }
; __device__ __forceinline__ float gelu_f(float x) {
;   const float c1 = -1.5957691216057308f * 1.4426950408889634f, c2 = c1 * 0.044715f;
;   float u = x * __builtin_fmaf(x * x, c2, c1);
;   return x * __builtin_amdgcn_rcpf(1.0f + __builtin_amdgcn_exp2f(u));
; }
; template <int MODE>
; __device__ __forceinline__ void epi_elem(char* ws, float* outp, const float* b_gate, int g0, int rl, int col, f32x4 v) {
;   if (MODE == E_U || MODE == E_GV) {
;     int lc = col & 1023;
;     f32x4 o; for (int i = 0; i < 4; ++i) o[i] = gelu_f(v[i]);
;     u16* dst = (u16*)(ws + (MODE == E_U ? W_U : W_GV));
;     *(GAS uint2*)(dst + (size_t)rl * 1024 + lc) = pack4(o);
	v_add_f32_e32 v163, 1.0, v163
	v_add_f32_e32 v164, 1.0, v164
	v_add_f32_e32 v165, 1.0, v165
	v_add_f32_e32 v166, 1.0, v166
	v_add_f32_e32 v167, 1.0, v167
	v_rcp_f32_e32 v160, v160
	v_rcp_f32_e32 v161, v161
	v_rcp_f32_e32 v162, v162
	v_rcp_f32_e32 v163, v163
	v_rcp_f32_e32 v164, v164
	v_rcp_f32_e32 v165, v165
	v_rcp_f32_e32 v166, v166
	v_rcp_f32_e32 v167, v167
	v_mul_f32_e32 v160, v110, v160
	v_mul_f32_e32 v161, v111, v161
	v_mul_f32_e32 v162, v112, v162
	v_mul_f32_e32 v163, v113, v163
	v_mul_f32_e32 v164, v106, v164
	v_mul_f32_e32 v165, v107, v165
	v_mul_f32_e32 v166, v108, v166
	v_mul_f32_e32 v167, v109, v167
	v_cvt_pk_bf16_f32 v152, v160, v161
	v_cvt_pk_bf16_f32 v153, v162, v163
	v_cvt_pk_bf16_f32 v154, v164, v165
	v_cvt_pk_bf16_f32 v155, v166, v167
	v_permlane16_swap_b32_e32 v148, v150
	v_permlane16_swap_b32_e32 v149, v151
	global_store_dwordx4 v251, v[148:151], s[4:5]
	v_mul_f32_e32 v168, v102, v102
	v_mul_f32_e32 v169, v103, v103
	v_mul_f32_e32 v170, v104, v104
	v_mul_f32_e32 v171, v105, v105
	v_mul_f32_e32 v172, v98, v98
	v_mul_f32_e32 v173, v99, v99
	v_mul_f32_e32 v174, v100, v100
	v_mul_f32_e32 v175, v101, v101
	v_fma_f32 v168, v168, s18, v198
	v_fma_f32 v169, v169, s18, v198
	v_fma_f32 v170, v170, s18, v198
	v_fma_f32 v171, v171, s18, v198
	v_fma_f32 v172, v172, s18, v198
	v_fma_f32 v173, v173, s18, v198
	v_fma_f32 v174, v174, s18, v198
	v_fma_f32 v175, v175, s18, v198
	v_mul_f32_e32 v168, v102, v168
	v_mul_f32_e32 v169, v103, v169
	v_mul_f32_e32 v170, v104, v170
	v_mul_f32_e32 v171, v105, v171
	v_mul_f32_e32 v172, v98, v172
	v_mul_f32_e32 v173, v99, v173
	v_mul_f32_e32 v174, v100, v174
	v_mul_f32_e32 v175, v101, v175
	v_exp_f32_e32 v168, v168
	v_exp_f32_e32 v169, v169
	v_exp_f32_e32 v170, v170
	v_exp_f32_e32 v171, v171
	v_exp_f32_e32 v172, v172
	v_exp_f32_e32 v173, v173
	v_exp_f32_e32 v174, v174
	v_exp_f32_e32 v175, v175
	v_add_f32_e32 v168, 1.0, v168
	v_add_f32_e32 v169, 1.0, v169
	v_add_f32_e32 v170, 1.0, v170
	v_add_f32_e32 v171, 1.0, v171
	v_add_f32_e32 v172, 1.0, v172
	v_add_f32_e32 v173, 1.0, v173
	v_add_f32_e32 v174, 1.0, v174
	v_add_f32_e32 v175, 1.0, v175
	v_rcp_f32_e32 v168, v168
	v_rcp_f32_e32 v169, v169
	v_rcp_f32_e32 v170, v170
	v_rcp_f32_e32 v171, v171
	v_rcp_f32_e32 v172, v172
	v_rcp_f32_e32 v173, v173
	v_rcp_f32_e32 v174, v174
	v_rcp_f32_e32 v175, v175
	v_mul_f32_e32 v168, v102, v168
	v_mul_f32_e32 v169, v103, v169
	v_mul_f32_e32 v170, v104, v170
	v_mul_f32_e32 v171, v105, v171
	v_mul_f32_e32 v172, v98, v172
	v_mul_f32_e32 v173, v99, v173
	v_mul_f32_e32 v174, v100, v174
	v_mul_f32_e32 v175, v101, v175
	v_cvt_pk_bf16_f32 v156, v168, v169
	v_cvt_pk_bf16_f32 v157, v170, v171
	v_cvt_pk_bf16_f32 v158, v172, v173
	v_cvt_pk_bf16_f32 v159, v174, v175
	v_permlane16_swap_b32_e32 v152, v154
	v_permlane16_swap_b32_e32 v153, v155
	global_store_dwordx4 v252, v[152:155], s[4:5]
	v_mul_f32_e32 v160, v94, v94
	v_mul_f32_e32 v161, v95, v95
	v_mul_f32_e32 v162, v96, v96
	v_mul_f32_e32 v163, v97, v97
	v_mul_f32_e32 v164, v90, v90
	v_mul_f32_e32 v165, v91, v91
	v_mul_f32_e32 v166, v92, v92
	v_mul_f32_e32 v167, v93, v93
	v_fma_f32 v160, v160, s18, v198
	v_fma_f32 v161, v161, s18, v198
	v_fma_f32 v162, v162, s18, v198
	v_fma_f32 v163, v163, s18, v198
	v_fma_f32 v164, v164, s18, v198
	v_fma_f32 v165, v165, s18, v198
	v_fma_f32 v166, v166, s18, v198
	v_fma_f32 v167, v167, s18, v198
	v_mul_f32_e32 v160, v94, v160
	v_mul_f32_e32 v161, v95, v161
	v_mul_f32_e32 v162, v96, v162
	v_mul_f32_e32 v163, v97, v163
	v_mul_f32_e32 v164, v90, v164
	v_mul_f32_e32 v165, v91, v165
	v_mul_f32_e32 v166, v92, v166
	v_mul_f32_e32 v167, v93, v167
	v_exp_f32_e32 v160, v160
	v_exp_f32_e32 v161, v161
	v_exp_f32_e32 v162, v162
	v_exp_f32_e32 v163, v163
	v_exp_f32_e32 v164, v164
	v_exp_f32_e32 v165, v165
	v_exp_f32_e32 v166, v166
	v_exp_f32_e32 v167, v167
	v_add_f32_e32 v160, 1.0, v160
	v_add_f32_e32 v161, 1.0, v161
	v_add_f32_e32 v162, 1.0, v162
	v_add_f32_e32 v163, 1.0, v163
	v_add_f32_e32 v164, 1.0, v164
	v_add_f32_e32 v165, 1.0, v165
	v_add_f32_e32 v166, 1.0, v166
	v_add_f32_e32 v167, 1.0, v167
	v_rcp_f32_e32 v160, v160
	v_rcp_f32_e32 v161, v161
	v_rcp_f32_e32 v162, v162
	v_rcp_f32_e32 v163, v163
	v_rcp_f32_e32 v164, v164
	v_rcp_f32_e32 v165, v165
	v_rcp_f32_e32 v166, v166
	v_rcp_f32_e32 v167, v167
	v_mul_f32_e32 v160, v94, v160
	v_mul_f32_e32 v161, v95, v161
	v_mul_f32_e32 v162, v96, v162
	v_mul_f32_e32 v163, v97, v163
	v_mul_f32_e32 v164, v90, v164
	v_mul_f32_e32 v165, v91, v165
	v_mul_f32_e32 v166, v92, v166
	v_mul_f32_e32 v167, v93, v167
	v_cvt_pk_bf16_f32 v144, v160, v161
	v_cvt_pk_bf16_f32 v145, v162, v163
	v_cvt_pk_bf16_f32 v146, v164, v165
	v_cvt_pk_bf16_f32 v147, v166, v167
	v_permlane16_swap_b32_e32 v156, v158
	v_permlane16_swap_b32_e32 v157, v159
	global_store_dwordx4 v253, v[156:159], s[4:5]
	v_mul_f32_e32 v168, v86, v86
	v_mul_f32_e32 v169, v87, v87
	v_mul_f32_e32 v170, v88, v88
	v_mul_f32_e32 v171, v89, v89
	v_mul_f32_e32 v172, v82, v82
	v_mul_f32_e32 v173, v83, v83
	v_mul_f32_e32 v174, v84, v84
	v_mul_f32_e32 v175, v85, v85
	v_fma_f32 v168, v168, s18, v198
	v_fma_f32 v169, v169, s18, v198
	v_fma_f32 v170, v170, s18, v198
	v_fma_f32 v171, v171, s18, v198
	v_fma_f32 v172, v172, s18, v198
	v_fma_f32 v173, v173, s18, v198
	v_fma_f32 v174, v174, s18, v198
	v_fma_f32 v175, v175, s18, v198
	v_mul_f32_e32 v168, v86, v168
	v_mul_f32_e32 v169, v87, v169
	v_mul_f32_e32 v170, v88, v170
	v_mul_f32_e32 v171, v89, v171
	v_mul_f32_e32 v172, v82, v172
	v_mul_f32_e32 v173, v83, v173
	v_mul_f32_e32 v174, v84, v174
	v_mul_f32_e32 v175, v85, v175
	v_exp_f32_e32 v168, v168
	v_exp_f32_e32 v169, v169
	v_exp_f32_e32 v170, v170
	v_exp_f32_e32 v171, v171
; #define GAS __attribute__((address_space(1)))
; __device__ __forceinline__ uint2 pack4(f32x4 v) { return make_uint2(pack2(v[0], v[1]), pack2(v[2], v[3])); }
; __device__ __forceinline__ float gelu_f(float x) {
;   const float c1 = -1.5957691216057308f * 1.4426950408889634f, c2 = c1 * 0.044715f;
;   float u = x * __builtin_fmaf(x * x, c2, c1);
;   return x * __builtin_amdgcn_rcpf(1.0f + __builtin_amdgcn_exp2f(u));
; }
; template <int MODE>
; __device__ __forceinline__ void epi_elem(char* ws, float* outp, const float* b_gate, int g0, int rl, int col, f32x4 v) {
;   if (MODE == E_U || MODE == E_GV) {
;     int lc = col & 1023;
;     f32x4 o; for (int i = 0; i < 4; ++i) o[i] = gelu_f(v[i]);
;     u16* dst = (u16*)(ws + (MODE == E_U ? W_U : W_GV));
;     *(GAS uint2*)(dst + (size_t)rl * 1024 + lc) = pack4(o);
	v_exp_f32_e32 v172, v172
	v_exp_f32_e32 v173, v173
	v_exp_f32_e32 v174, v174
	v_exp_f32_e32 v175, v175
	v_add_f32_e32 v168, 1.0, v168
	v_add_f32_e32 v169, 1.0, v169
	v_add_f32_e32 v170, 1.0, v170
	v_add_f32_e32 v171, 1.0, v171
	v_add_f32_e32 v172, 1.0, v172
	v_add_f32_e32 v173, 1.0, v173
	v_add_f32_e32 v174, 1.0, v174
	v_add_f32_e32 v175, 1.0, v175
	v_rcp_f32_e32 v168, v168
	v_rcp_f32_e32 v169, v169
	v_rcp_f32_e32 v170, v170
	v_rcp_f32_e32 v171, v171
	v_rcp_f32_e32 v172, v172
	v_rcp_f32_e32 v173, v173
	v_rcp_f32_e32 v174, v174
	v_rcp_f32_e32 v175, v175
	v_mul_f32_e32 v168, v86, v168
	v_mul_f32_e32 v169, v87, v169
	v_mul_f32_e32 v170, v88, v170
	v_mul_f32_e32 v171, v89, v171
	v_mul_f32_e32 v172, v82, v172
	v_mul_f32_e32 v173, v83, v173
	v_mul_f32_e32 v174, v84, v174
	v_mul_f32_e32 v175, v85, v175
	v_cvt_pk_bf16_f32 v148, v168, v169
	v_cvt_pk_bf16_f32 v149, v170, v171
	v_cvt_pk_bf16_f32 v150, v172, v173
	v_cvt_pk_bf16_f32 v151, v174, v175
	v_permlane16_swap_b32_e32 v144, v146
	v_permlane16_swap_b32_e32 v145, v147
	global_store_dwordx4 v250, v[144:147], s[4:5] offset:256
	v_mul_f32_e32 v160, v78, v78
	v_mul_f32_e32 v161, v79, v79
	v_mul_f32_e32 v162, v80, v80
	v_mul_f32_e32 v163, v81, v81
	v_mul_f32_e32 v164, v74, v74
	v_mul_f32_e32 v165, v75, v75
	v_mul_f32_e32 v166, v76, v76
	v_mul_f32_e32 v167, v77, v77
	v_fma_f32 v160, v160, s18, v198
	v_fma_f32 v161, v161, s18, v198
	v_fma_f32 v162, v162, s18, v198
	v_fma_f32 v163, v163, s18, v198
	v_fma_f32 v164, v164, s18, v198
	v_fma_f32 v165, v165, s18, v198
	v_fma_f32 v166, v166, s18, v198
	v_fma_f32 v167, v167, s18, v198
	v_mul_f32_e32 v160, v78, v160
	v_mul_f32_e32 v161, v79, v161
	v_mul_f32_e32 v162, v80, v162
	v_mul_f32_e32 v163, v81, v163
	v_mul_f32_e32 v164, v74, v164
	v_mul_f32_e32 v165, v75, v165
	v_mul_f32_e32 v166, v76, v166
	v_mul_f32_e32 v167, v77, v167
	v_exp_f32_e32 v160, v160
	v_exp_f32_e32 v161, v161
	v_exp_f32_e32 v162, v162
	v_exp_f32_e32 v163, v163
	v_exp_f32_e32 v164, v164
	v_exp_f32_e32 v165, v165
	v_exp_f32_e32 v166, v166
	v_exp_f32_e32 v167, v167
	v_add_f32_e32 v160, 1.0, v160
	v_add_f32_e32 v161, 1.0, v161
	v_add_f32_e32 v162, 1.0, v162
	v_add_f32_e32 v163, 1.0, v163
	v_add_f32_e32 v164, 1.0, v164
	v_add_f32_e32 v165, 1.0, v165
	v_add_f32_e32 v166, 1.0, v166
	v_add_f32_e32 v167, 1.0, v167
	v_rcp_f32_e32 v160, v160
	v_rcp_f32_e32 v161, v161
	v_rcp_f32_e32 v162, v162
	v_rcp_f32_e32 v163, v163
	v_rcp_f32_e32 v164, v164
	v_rcp_f32_e32 v165, v165
	v_rcp_f32_e32 v166, v166
	v_rcp_f32_e32 v167, v167
	v_mul_f32_e32 v160, v78, v160
	v_mul_f32_e32 v161, v79, v161
	v_mul_f32_e32 v162, v80, v162
	v_mul_f32_e32 v163, v81, v163
	v_mul_f32_e32 v164, v74, v164
	v_mul_f32_e32 v165, v75, v165
	v_mul_f32_e32 v166, v76, v166
	v_mul_f32_e32 v167, v77, v167
	v_cvt_pk_bf16_f32 v152, v160, v161
	v_cvt_pk_bf16_f32 v153, v162, v163
	v_cvt_pk_bf16_f32 v154, v164, v165
	v_cvt_pk_bf16_f32 v155, v166, v167
	v_permlane16_swap_b32_e32 v148, v150
	v_permlane16_swap_b32_e32 v149, v151
	global_store_dwordx4 v251, v[148:151], s[4:5] offset:256
	v_mul_f32_e32 v168, v70, v70
	v_mul_f32_e32 v169, v71, v71
	v_mul_f32_e32 v170, v72, v72
	v_mul_f32_e32 v171, v73, v73
	v_mul_f32_e32 v172, v66, v66
	v_mul_f32_e32 v173, v67, v67
	v_mul_f32_e32 v174, v68, v68
	v_mul_f32_e32 v175, v69, v69
	v_fma_f32 v168, v168, s18, v198
	v_fma_f32 v169, v169, s18, v198
	v_fma_f32 v170, v170, s18, v198
	v_fma_f32 v171, v171, s18, v198
	v_fma_f32 v172, v172, s18, v198
	v_fma_f32 v173, v173, s18, v198
	v_fma_f32 v174, v174, s18, v198
	v_fma_f32 v175, v175, s18, v198
	v_mul_f32_e32 v168, v70, v168
	v_mul_f32_e32 v169, v71, v169
	v_mul_f32_e32 v170, v72, v170
	v_mul_f32_e32 v171, v73, v171
	v_mul_f32_e32 v172, v66, v172
	v_mul_f32_e32 v173, v67, v173
	v_mul_f32_e32 v174, v68, v174
	v_mul_f32_e32 v175, v69, v175
	v_exp_f32_e32 v168, v168
	v_exp_f32_e32 v169, v169
	v_exp_f32_e32 v170, v170
	v_exp_f32_e32 v171, v171
	v_exp_f32_e32 v172, v172
	v_exp_f32_e32 v173, v173
	v_exp_f32_e32 v174, v174
	v_exp_f32_e32 v175, v175
	v_add_f32_e32 v168, 1.0, v168
	v_add_f32_e32 v169, 1.0, v169
	v_add_f32_e32 v170, 1.0, v170
	v_add_f32_e32 v171, 1.0, v171
	v_add_f32_e32 v172, 1.0, v172
	v_add_f32_e32 v173, 1.0, v173
	v_add_f32_e32 v174, 1.0, v174
	v_add_f32_e32 v175, 1.0, v175
	v_rcp_f32_e32 v168, v168
	v_rcp_f32_e32 v169, v169
	v_rcp_f32_e32 v170, v170
	v_rcp_f32_e32 v171, v171
	v_rcp_f32_e32 v172, v172
	v_rcp_f32_e32 v173, v173
	v_rcp_f32_e32 v174, v174
	v_rcp_f32_e32 v175, v175
	v_mul_f32_e32 v168, v70, v168
	v_mul_f32_e32 v169, v71, v169
	v_mul_f32_e32 v170, v72, v170
	v_mul_f32_e32 v171, v73, v171
	v_mul_f32_e32 v172, v66, v172
	v_mul_f32_e32 v173, v67, v173
	v_mul_f32_e32 v174, v68, v174
	v_mul_f32_e32 v175, v69, v175
	v_cvt_pk_bf16_f32 v156, v168, v169
	v_cvt_pk_bf16_f32 v157, v170, v171
	v_cvt_pk_bf16_f32 v158, v172, v173
	v_cvt_pk_bf16_f32 v159, v174, v175
	v_permlane16_swap_b32_e32 v152, v154
	v_permlane16_swap_b32_e32 v153, v155
	global_store_dwordx4 v252, v[152:155], s[4:5] offset:256
	v_mul_f32_e32 v160, v62, v62
	v_mul_f32_e32 v161, v63, v63
	v_mul_f32_e32 v162, v64, v64
	v_mul_f32_e32 v163, v65, v65
	v_mul_f32_e32 v164, v58, v58
	v_mul_f32_e32 v165, v59, v59
	v_mul_f32_e32 v166, v60, v60
	v_mul_f32_e32 v167, v61, v61
	v_fma_f32 v160, v160, s18, v198
	v_fma_f32 v161, v161, s18, v198
	v_fma_f32 v162, v162, s18, v198
	v_fma_f32 v163, v163, s18, v198
	v_fma_f32 v164, v164, s18, v198
	v_fma_f32 v165, v165, s18, v198
	v_fma_f32 v166, v166, s18, v198
	v_fma_f32 v167, v167, s18, v198
	v_mul_f32_e32 v160, v62, v160
	v_mul_f32_e32 v161, v63, v161
	v_mul_f32_e32 v162, v64, v162
	v_mul_f32_e32 v163, v65, v163
	v_mul_f32_e32 v164, v58, v164
; #define GAS __attribute__((address_space(1)))
; __device__ __forceinline__ uint2 pack4(f32x4 v) { return make_uint2(pack2(v[0], v[1]), pack2(v[2], v[3])); }
; __device__ __forceinline__ float gelu_f(float x) {
;   const float c1 = -1.5957691216057308f * 1.4426950408889634f, c2 = c1 * 0.044715f;
;   float u = x * __builtin_fmaf(x * x, c2, c1);
;   return x * __builtin_amdgcn_rcpf(1.0f + __builtin_amdgcn_exp2f(u));
; }
; template <int MODE>
; __device__ __forceinline__ void epi_elem(char* ws, float* outp, const float* b_gate, int g0, int rl, int col, f32x4 v) {
;   if (MODE == E_U || MODE == E_GV) {
;     int lc = col & 1023;
;     f32x4 o; for (int i = 0; i < 4; ++i) o[i] = gelu_f(v[i]);
;     u16* dst = (u16*)(ws + (MODE == E_U ? W_U : W_GV));
;     *(GAS uint2*)(dst + (size_t)rl * 1024 + lc) = pack4(o);
	v_mul_f32_e32 v165, v59, v165
	v_mul_f32_e32 v166, v60, v166
	v_mul_f32_e32 v167, v61, v167
	v_exp_f32_e32 v160, v160
	v_exp_f32_e32 v161, v161
	v_exp_f32_e32 v162, v162
	v_exp_f32_e32 v163, v163
	v_exp_f32_e32 v164, v164
	v_exp_f32_e32 v165, v165
	v_exp_f32_e32 v166, v166
	v_exp_f32_e32 v167, v167
	v_add_f32_e32 v160, 1.0, v160
	v_add_f32_e32 v161, 1.0, v161
	v_add_f32_e32 v162, 1.0, v162
	v_add_f32_e32 v163, 1.0, v163
	v_add_f32_e32 v164, 1.0, v164
	v_add_f32_e32 v165, 1.0, v165
	v_add_f32_e32 v166, 1.0, v166
	v_add_f32_e32 v167, 1.0, v167
	v_rcp_f32_e32 v160, v160
	v_rcp_f32_e32 v161, v161
	v_rcp_f32_e32 v162, v162
	v_rcp_f32_e32 v163, v163
	v_rcp_f32_e32 v164, v164
	v_rcp_f32_e32 v165, v165
	v_rcp_f32_e32 v166, v166
	v_rcp_f32_e32 v167, v167
	v_mul_f32_e32 v160, v62, v160
	v_mul_f32_e32 v161, v63, v161
	v_mul_f32_e32 v162, v64, v162
	v_mul_f32_e32 v163, v65, v163
	v_mul_f32_e32 v164, v58, v164
	v_mul_f32_e32 v165, v59, v165
	v_mul_f32_e32 v166, v60, v166
	v_mul_f32_e32 v167, v61, v167
	v_cvt_pk_bf16_f32 v144, v160, v161
	v_cvt_pk_bf16_f32 v145, v162, v163
	v_cvt_pk_bf16_f32 v146, v164, v165
	v_cvt_pk_bf16_f32 v147, v166, v167
	v_permlane16_swap_b32_e32 v156, v158
	v_permlane16_swap_b32_e32 v157, v159
	global_store_dwordx4 v253, v[156:159], s[4:5] offset:256
	v_mul_f32_e32 v168, v54, v54
	v_mul_f32_e32 v169, v55, v55
	v_mul_f32_e32 v170, v56, v56
	v_mul_f32_e32 v171, v57, v57
	v_mul_f32_e32 v172, v50, v50
	v_mul_f32_e32 v173, v51, v51
	v_mul_f32_e32 v174, v52, v52
	v_mul_f32_e32 v175, v53, v53
	v_fma_f32 v168, v168, s18, v198
	v_fma_f32 v169, v169, s18, v198
	v_fma_f32 v170, v170, s18, v198
	v_fma_f32 v171, v171, s18, v198
	v_fma_f32 v172, v172, s18, v198
	v_fma_f32 v173, v173, s18, v198
	v_fma_f32 v174, v174, s18, v198
	v_fma_f32 v175, v175, s18, v198
	v_mul_f32_e32 v168, v54, v168
	v_mul_f32_e32 v169, v55, v169
	v_mul_f32_e32 v170, v56, v170
	v_mul_f32_e32 v171, v57, v171
	v_mul_f32_e32 v172, v50, v172
	v_mul_f32_e32 v173, v51, v173
	v_mul_f32_e32 v174, v52, v174
	v_mul_f32_e32 v175, v53, v175
	v_exp_f32_e32 v168, v168
	v_exp_f32_e32 v169, v169
	v_exp_f32_e32 v170, v170
	v_exp_f32_e32 v171, v171
	v_exp_f32_e32 v172, v172
	v_exp_f32_e32 v173, v173
	v_exp_f32_e32 v174, v174
	v_exp_f32_e32 v175, v175
	v_add_f32_e32 v168, 1.0, v168
	v_add_f32_e32 v169, 1.0, v169
	v_add_f32_e32 v170, 1.0, v170
	v_add_f32_e32 v171, 1.0, v171
	v_add_f32_e32 v172, 1.0, v172
	v_add_f32_e32 v173, 1.0, v173
	v_add_f32_e32 v174, 1.0, v174
	v_add_f32_e32 v175, 1.0, v175
	v_rcp_f32_e32 v168, v168
	v_rcp_f32_e32 v169, v169
	v_rcp_f32_e32 v170, v170
	v_rcp_f32_e32 v171, v171
	v_rcp_f32_e32 v172, v172
	v_rcp_f32_e32 v173, v173
	v_rcp_f32_e32 v174, v174
	v_rcp_f32_e32 v175, v175
	v_mul_f32_e32 v168, v54, v168
	v_mul_f32_e32 v169, v55, v169
	v_mul_f32_e32 v170, v56, v170
	v_mul_f32_e32 v171, v57, v171
	v_mul_f32_e32 v172, v50, v172
	v_mul_f32_e32 v173, v51, v173
	v_mul_f32_e32 v174, v52, v174
	v_mul_f32_e32 v175, v53, v175
	v_cvt_pk_bf16_f32 v148, v168, v169
	v_cvt_pk_bf16_f32 v149, v170, v171
	v_cvt_pk_bf16_f32 v150, v172, v173
	v_cvt_pk_bf16_f32 v151, v174, v175
	v_permlane16_swap_b32_e32 v144, v146
	v_permlane16_swap_b32_e32 v145, v147
	global_store_dwordx4 v250, v[144:147], s[6:7]
	v_mul_f32_e32 v160, v46, v46
	v_mul_f32_e32 v161, v47, v47
	v_mul_f32_e32 v162, v48, v48
	v_mul_f32_e32 v163, v49, v49
	v_mul_f32_e32 v164, v42, v42
	v_mul_f32_e32 v165, v43, v43
	v_mul_f32_e32 v166, v44, v44
	v_mul_f32_e32 v167, v45, v45
	v_fma_f32 v160, v160, s18, v198
	v_fma_f32 v161, v161, s18, v198
	v_fma_f32 v162, v162, s18, v198
	v_fma_f32 v163, v163, s18, v198
	v_fma_f32 v164, v164, s18, v198
	v_fma_f32 v165, v165, s18, v198
	v_fma_f32 v166, v166, s18, v198
	v_fma_f32 v167, v167, s18, v198
	v_mul_f32_e32 v160, v46, v160
	v_mul_f32_e32 v161, v47, v161
	v_mul_f32_e32 v162, v48, v162
	v_mul_f32_e32 v163, v49, v163
	v_mul_f32_e32 v164, v42, v164
	v_mul_f32_e32 v165, v43, v165
	v_mul_f32_e32 v166, v44, v166
	v_mul_f32_e32 v167, v45, v167
	v_exp_f32_e32 v160, v160
	v_exp_f32_e32 v161, v161
	v_exp_f32_e32 v162, v162
	v_exp_f32_e32 v163, v163
	v_exp_f32_e32 v164, v164
	v_exp_f32_e32 v165, v165
	v_exp_f32_e32 v166, v166
	v_exp_f32_e32 v167, v167
	v_add_f32_e32 v160, 1.0, v160
	v_add_f32_e32 v161, 1.0, v161
	v_add_f32_e32 v162, 1.0, v162
	v_add_f32_e32 v163, 1.0, v163
	v_add_f32_e32 v164, 1.0, v164
	v_add_f32_e32 v165, 1.0, v165
	v_add_f32_e32 v166, 1.0, v166
	v_add_f32_e32 v167, 1.0, v167
	v_rcp_f32_e32 v160, v160
	v_rcp_f32_e32 v161, v161
	v_rcp_f32_e32 v162, v162
	v_rcp_f32_e32 v163, v163
	v_rcp_f32_e32 v164, v164
	v_rcp_f32_e32 v165, v165
	v_rcp_f32_e32 v166, v166
	v_rcp_f32_e32 v167, v167
	v_mul_f32_e32 v160, v46, v160
	v_mul_f32_e32 v161, v47, v161
	v_mul_f32_e32 v162, v48, v162
	v_mul_f32_e32 v163, v49, v163
	v_mul_f32_e32 v164, v42, v164
	v_mul_f32_e32 v165, v43, v165
	v_mul_f32_e32 v166, v44, v166
	v_mul_f32_e32 v167, v45, v167
	v_cvt_pk_bf16_f32 v152, v160, v161
	v_cvt_pk_bf16_f32 v153, v162, v163
	v_cvt_pk_bf16_f32 v154, v164, v165
	v_cvt_pk_bf16_f32 v155, v166, v167
	v_permlane16_swap_b32_e32 v148, v150
	v_permlane16_swap_b32_e32 v149, v151
	global_store_dwordx4 v251, v[148:151], s[6:7]
	v_mul_f32_e32 v168, v38, v38
	v_mul_f32_e32 v169, v39, v39
	v_mul_f32_e32 v170, v40, v40
	v_mul_f32_e32 v171, v41, v41
	v_mul_f32_e32 v172, v34, v34
	v_mul_f32_e32 v173, v35, v35
	v_mul_f32_e32 v174, v36, v36
	v_mul_f32_e32 v175, v37, v37
	v_fma_f32 v168, v168, s18, v198
	v_fma_f32 v169, v169, s18, v198
	v_fma_f32 v170, v170, s18, v198
	v_fma_f32 v171, v171, s18, v198
	v_fma_f32 v172, v172, s18, v198
	v_fma_f32 v173, v173, s18, v198
	v_fma_f32 v174, v174, s18, v198
	v_fma_f32 v175, v175, s18, v198
; #define GAS __attribute__((address_space(1)))
; __device__ __forceinline__ uint2 pack4(f32x4 v) { return make_uint2(pack2(v[0], v[1]), pack2(v[2], v[3])); }
; __device__ __forceinline__ float gelu_f(float x) {
;   const float c1 = -1.5957691216057308f * 1.4426950408889634f, c2 = c1 * 0.044715f;
;   float u = x * __builtin_fmaf(x * x, c2, c1);
;   return x * __builtin_amdgcn_rcpf(1.0f + __builtin_amdgcn_exp2f(u));
; }
; template <int MODE>
; __device__ __forceinline__ void epi_elem(char* ws, float* outp, const float* b_gate, int g0, int rl, int col, f32x4 v) {
;   if (MODE == E_U || MODE == E_GV) {
;     int lc = col & 1023;
;     f32x4 o; for (int i = 0; i < 4; ++i) o[i] = gelu_f(v[i]);
;     u16* dst = (u16*)(ws + (MODE == E_U ? W_U : W_GV));
;     *(GAS uint2*)(dst + (size_t)rl * 1024 + lc) = pack4(o);
	v_mul_f32_e32 v168, v38, v168
	v_mul_f32_e32 v169, v39, v169
	v_mul_f32_e32 v170, v40, v170
	v_mul_f32_e32 v171, v41, v171
	v_mul_f32_e32 v172, v34, v172
	v_mul_f32_e32 v173, v35, v173
	v_mul_f32_e32 v174, v36, v174
	v_mul_f32_e32 v175, v37, v175
	v_exp_f32_e32 v168, v168
	v_exp_f32_e32 v169, v169
	v_exp_f32_e32 v170, v170
	v_exp_f32_e32 v171, v171
	v_exp_f32_e32 v172, v172
	v_exp_f32_e32 v173, v173
	v_exp_f32_e32 v174, v174
	v_exp_f32_e32 v175, v175
	v_add_f32_e32 v168, 1.0, v168
	v_add_f32_e32 v169, 1.0, v169
	v_add_f32_e32 v170, 1.0, v170
	v_add_f32_e32 v171, 1.0, v171
	v_add_f32_e32 v172, 1.0, v172
	v_add_f32_e32 v173, 1.0, v173
	v_add_f32_e32 v174, 1.0, v174
	v_add_f32_e32 v175, 1.0, v175
	v_rcp_f32_e32 v168, v168
	v_rcp_f32_e32 v169, v169
	v_rcp_f32_e32 v170, v170
	v_rcp_f32_e32 v171, v171
	v_rcp_f32_e32 v172, v172
	v_rcp_f32_e32 v173, v173
	v_rcp_f32_e32 v174, v174
	v_rcp_f32_e32 v175, v175
	v_mul_f32_e32 v168, v38, v168
	v_mul_f32_e32 v169, v39, v169
	v_mul_f32_e32 v170, v40, v170
	v_mul_f32_e32 v171, v41, v171
	v_mul_f32_e32 v172, v34, v172
	v_mul_f32_e32 v173, v35, v173
	v_mul_f32_e32 v174, v36, v174
	v_mul_f32_e32 v175, v37, v175
	v_cvt_pk_bf16_f32 v156, v168, v169
	v_cvt_pk_bf16_f32 v157, v170, v171
	v_cvt_pk_bf16_f32 v158, v172, v173
	v_cvt_pk_bf16_f32 v159, v174, v175
	v_permlane16_swap_b32_e32 v152, v154
	v_permlane16_swap_b32_e32 v153, v155
	global_store_dwordx4 v252, v[152:155], s[6:7]
	v_mul_f32_e32 v160, v30, v30
	v_mul_f32_e32 v161, v31, v31
	v_mul_f32_e32 v162, v32, v32
	v_mul_f32_e32 v163, v33, v33
	v_mul_f32_e32 v164, v26, v26
	v_mul_f32_e32 v165, v27, v27
	v_mul_f32_e32 v166, v28, v28
	v_mul_f32_e32 v167, v29, v29
	v_fma_f32 v160, v160, s18, v198
	v_fma_f32 v161, v161, s18, v198
	v_fma_f32 v162, v162, s18, v198
	v_fma_f32 v163, v163, s18, v198
	v_fma_f32 v164, v164, s18, v198
	v_fma_f32 v165, v165, s18, v198
	v_fma_f32 v166, v166, s18, v198
	v_fma_f32 v167, v167, s18, v198
	v_mul_f32_e32 v160, v30, v160
	v_mul_f32_e32 v161, v31, v161
	v_mul_f32_e32 v162, v32, v162
	v_mul_f32_e32 v163, v33, v163
	v_mul_f32_e32 v164, v26, v164
	v_mul_f32_e32 v165, v27, v165
	v_mul_f32_e32 v166, v28, v166
	v_mul_f32_e32 v167, v29, v167
	v_exp_f32_e32 v160, v160
	v_exp_f32_e32 v161, v161
	v_exp_f32_e32 v162, v162
	v_exp_f32_e32 v163, v163
	v_exp_f32_e32 v164, v164
	v_exp_f32_e32 v165, v165
	v_exp_f32_e32 v166, v166
	v_exp_f32_e32 v167, v167
	v_add_f32_e32 v160, 1.0, v160
	v_add_f32_e32 v161, 1.0, v161
	v_add_f32_e32 v162, 1.0, v162
	v_add_f32_e32 v163, 1.0, v163
	v_add_f32_e32 v164, 1.0, v164
	v_add_f32_e32 v165, 1.0, v165
	v_add_f32_e32 v166, 1.0, v166
	v_add_f32_e32 v167, 1.0, v167
	v_rcp_f32_e32 v160, v160
	v_rcp_f32_e32 v161, v161
	v_rcp_f32_e32 v162, v162
	v_rcp_f32_e32 v163, v163
	v_rcp_f32_e32 v164, v164
	v_rcp_f32_e32 v165, v165
	v_rcp_f32_e32 v166, v166
	v_rcp_f32_e32 v167, v167
	v_mul_f32_e32 v160, v30, v160
	v_mul_f32_e32 v161, v31, v161
	v_mul_f32_e32 v162, v32, v162
	v_mul_f32_e32 v163, v33, v163
	v_mul_f32_e32 v164, v26, v164
	v_mul_f32_e32 v165, v27, v165
	v_mul_f32_e32 v166, v28, v166
	v_mul_f32_e32 v167, v29, v167
	v_cvt_pk_bf16_f32 v144, v160, v161
	v_cvt_pk_bf16_f32 v145, v162, v163
	v_cvt_pk_bf16_f32 v146, v164, v165
	v_cvt_pk_bf16_f32 v147, v166, v167
	v_permlane16_swap_b32_e32 v156, v158
	v_permlane16_swap_b32_e32 v157, v159
	global_store_dwordx4 v253, v[156:159], s[6:7]
	v_mul_f32_e32 v168, v22, v22
	v_mul_f32_e32 v169, v23, v23
	v_mul_f32_e32 v170, v24, v24
	v_mul_f32_e32 v171, v25, v25
	v_mul_f32_e32 v172, v18, v18
	v_mul_f32_e32 v173, v19, v19
	v_mul_f32_e32 v174, v20, v20
	v_mul_f32_e32 v175, v21, v21
	v_fma_f32 v168, v168, s18, v198
	v_fma_f32 v169, v169, s18, v198
	v_fma_f32 v170, v170, s18, v198
	v_fma_f32 v171, v171, s18, v198
	v_fma_f32 v172, v172, s18, v198
	v_fma_f32 v173, v173, s18, v198
	v_fma_f32 v174, v174, s18, v198
	v_fma_f32 v175, v175, s18, v198
	v_mul_f32_e32 v168, v22, v168
	v_mul_f32_e32 v169, v23, v169
	v_mul_f32_e32 v170, v24, v170
	v_mul_f32_e32 v171, v25, v171
	v_mul_f32_e32 v172, v18, v172
	v_mul_f32_e32 v173, v19, v173
	v_mul_f32_e32 v174, v20, v174
	v_mul_f32_e32 v175, v21, v175
	v_exp_f32_e32 v168, v168
	v_exp_f32_e32 v169, v169
	v_exp_f32_e32 v170, v170
	v_exp_f32_e32 v171, v171
	v_exp_f32_e32 v172, v172
	v_exp_f32_e32 v173, v173
	v_exp_f32_e32 v174, v174
	v_exp_f32_e32 v175, v175
	v_add_f32_e32 v168, 1.0, v168
	v_add_f32_e32 v169, 1.0, v169
	v_add_f32_e32 v170, 1.0, v170
	v_add_f32_e32 v171, 1.0, v171
	v_add_f32_e32 v172, 1.0, v172
	v_add_f32_e32 v173, 1.0, v173
	v_add_f32_e32 v174, 1.0, v174
	v_add_f32_e32 v175, 1.0, v175
	v_rcp_f32_e32 v168, v168
	v_rcp_f32_e32 v169, v169
	v_rcp_f32_e32 v170, v170
	v_rcp_f32_e32 v171, v171
; #define GAS __attribute__((address_space(1)))
; __device__ __forceinline__ uint2 pack4(f32x4 v) { return make_uint2(pack2(v[0], v[1]), pack2(v[2], v[3])); }
; __device__ __forceinline__ float gelu_f(float x) {
;   const float c1 = -1.5957691216057308f * 1.4426950408889634f, c2 = c1 * 0.044715f;
;   float u = x * __builtin_fmaf(x * x, c2, c1);
;   return x * __builtin_amdgcn_rcpf(1.0f + __builtin_amdgcn_exp2f(u));
; }
; template <int MODE>
; __device__ __forceinline__ void epi_elem(char* ws, float* outp, const float* b_gate, int g0, int rl, int col, f32x4 v) {
;   if (MODE == E_U || MODE == E_GV) {
;     int lc = col & 1023;
;     f32x4 o; for (int i = 0; i < 4; ++i) o[i] = gelu_f(v[i]);
;     u16* dst = (u16*)(ws + (MODE == E_U ? W_U : W_GV));
;     *(GAS uint2*)(dst + (size_t)rl * 1024 + lc) = pack4(o);
	v_rcp_f32_e32 v172, v172
	v_rcp_f32_e32 v173, v173
	v_rcp_f32_e32 v174, v174
	v_rcp_f32_e32 v175, v175
	v_mul_f32_e32 v168, v22, v168
	v_mul_f32_e32 v169, v23, v169
	v_mul_f32_e32 v170, v24, v170
	v_mul_f32_e32 v171, v25, v171
	v_mul_f32_e32 v172, v18, v172
	v_mul_f32_e32 v173, v19, v173
	v_mul_f32_e32 v174, v20, v174
	v_mul_f32_e32 v175, v21, v175
	v_cvt_pk_bf16_f32 v148, v168, v169
	v_cvt_pk_bf16_f32 v149, v170, v171
	v_cvt_pk_bf16_f32 v150, v172, v173
	v_cvt_pk_bf16_f32 v151, v174, v175
	v_permlane16_swap_b32_e32 v144, v146
	v_permlane16_swap_b32_e32 v145, v147
	global_store_dwordx4 v250, v[144:147], s[6:7] offset:256
	v_mul_f32_e32 v160, v14, v14
	v_mul_f32_e32 v161, v15, v15
	v_mul_f32_e32 v162, v16, v16
	v_mul_f32_e32 v163, v17, v17
	v_mul_f32_e32 v164, v10, v10
	v_mul_f32_e32 v165, v11, v11
	v_mul_f32_e32 v166, v12, v12
	v_mul_f32_e32 v167, v13, v13
	v_fma_f32 v160, v160, s18, v198
	v_fma_f32 v161, v161, s18, v198
	v_fma_f32 v162, v162, s18, v198
	v_fma_f32 v163, v163, s18, v198
	v_fma_f32 v164, v164, s18, v198
	v_fma_f32 v165, v165, s18, v198
	v_fma_f32 v166, v166, s18, v198
	v_fma_f32 v167, v167, s18, v198
	v_mul_f32_e32 v160, v14, v160
	v_mul_f32_e32 v161, v15, v161
	v_mul_f32_e32 v162, v16, v162
	v_mul_f32_e32 v163, v17, v163
	v_mul_f32_e32 v164, v10, v164
	v_mul_f32_e32 v165, v11, v165
	v_mul_f32_e32 v166, v12, v166
	v_mul_f32_e32 v167, v13, v167
	v_exp_f32_e32 v160, v160
	v_exp_f32_e32 v161, v161
	v_exp_f32_e32 v162, v162
	v_exp_f32_e32 v163, v163
	v_exp_f32_e32 v164, v164
	v_exp_f32_e32 v165, v165
	v_exp_f32_e32 v166, v166
	v_exp_f32_e32 v167, v167
	v_add_f32_e32 v160, 1.0, v160
	v_add_f32_e32 v161, 1.0, v161
	v_add_f32_e32 v162, 1.0, v162
	v_add_f32_e32 v163, 1.0, v163
	v_add_f32_e32 v164, 1.0, v164
	v_add_f32_e32 v165, 1.0, v165
	v_add_f32_e32 v166, 1.0, v166
	v_add_f32_e32 v167, 1.0, v167
	v_rcp_f32_e32 v160, v160
	v_rcp_f32_e32 v161, v161
	v_rcp_f32_e32 v162, v162
	v_rcp_f32_e32 v163, v163
	v_rcp_f32_e32 v164, v164
	v_rcp_f32_e32 v165, v165
	v_rcp_f32_e32 v166, v166
	v_rcp_f32_e32 v167, v167
	v_mul_f32_e32 v160, v14, v160
	v_mul_f32_e32 v161, v15, v161
	v_mul_f32_e32 v162, v16, v162
	v_mul_f32_e32 v163, v17, v163
	v_mul_f32_e32 v164, v10, v164
	v_mul_f32_e32 v165, v11, v165
	v_mul_f32_e32 v166, v12, v166
	v_mul_f32_e32 v167, v13, v167
	v_cvt_pk_bf16_f32 v152, v160, v161
	v_cvt_pk_bf16_f32 v153, v162, v163
	v_cvt_pk_bf16_f32 v154, v164, v165
	v_cvt_pk_bf16_f32 v155, v166, v167
	v_permlane16_swap_b32_e32 v148, v150
	v_permlane16_swap_b32_e32 v149, v151
	global_store_dwordx4 v251, v[148:151], s[6:7] offset:256
	v_mul_f32_e32 v168, v6, v6
	v_mul_f32_e32 v169, v7, v7
	v_mul_f32_e32 v170, v8, v8
	v_mul_f32_e32 v171, v9, v9
	v_mul_f32_e32 v172, v2, v2
	v_mul_f32_e32 v173, v3, v3
	v_mul_f32_e32 v174, v4, v4
	v_mul_f32_e32 v175, v5, v5
	v_fma_f32 v168, v168, s18, v198
	v_fma_f32 v169, v169, s18, v198
	v_fma_f32 v170, v170, s18, v198
	v_fma_f32 v171, v171, s18, v198
	v_fma_f32 v172, v172, s18, v198
	v_fma_f32 v173, v173, s18, v198
	v_fma_f32 v174, v174, s18, v198
	v_fma_f32 v175, v175, s18, v198
	v_mul_f32_e32 v168, v6, v168
	v_mul_f32_e32 v169, v7, v169
	v_mul_f32_e32 v170, v8, v170
	v_mul_f32_e32 v171, v9, v171
	v_mul_f32_e32 v172, v2, v172
	v_mul_f32_e32 v173, v3, v173
	v_mul_f32_e32 v174, v4, v174
	v_mul_f32_e32 v175, v5, v175
	v_exp_f32_e32 v168, v168
	v_exp_f32_e32 v169, v169
	v_exp_f32_e32 v170, v170
	v_exp_f32_e32 v171, v171
	v_exp_f32_e32 v172, v172
	v_exp_f32_e32 v173, v173
	v_exp_f32_e32 v174, v174
	v_exp_f32_e32 v175, v175
	v_add_f32_e32 v168, 1.0, v168
	v_add_f32_e32 v169, 1.0, v169
	v_add_f32_e32 v170, 1.0, v170
	v_add_f32_e32 v171, 1.0, v171
	v_add_f32_e32 v172, 1.0, v172
	v_add_f32_e32 v173, 1.0, v173
	v_add_f32_e32 v174, 1.0, v174
	v_add_f32_e32 v175, 1.0, v175
	v_rcp_f32_e32 v168, v168
	v_rcp_f32_e32 v169, v169
	v_rcp_f32_e32 v170, v170
	v_rcp_f32_e32 v171, v171
	v_rcp_f32_e32 v172, v172
	v_rcp_f32_e32 v173, v173
	v_rcp_f32_e32 v174, v174
	v_rcp_f32_e32 v175, v175
	v_mul_f32_e32 v168, v6, v168
	v_mul_f32_e32 v169, v7, v169
	v_mul_f32_e32 v170, v8, v170
	v_mul_f32_e32 v171, v9, v171
	v_mul_f32_e32 v172, v2, v172
	v_mul_f32_e32 v173, v3, v173
	v_mul_f32_e32 v174, v4, v174
	v_mul_f32_e32 v175, v5, v175
	v_cvt_pk_bf16_f32 v156, v168, v169
	v_cvt_pk_bf16_f32 v157, v170, v171
	v_cvt_pk_bf16_f32 v158, v172, v173
	v_cvt_pk_bf16_f32 v159, v174, v175
	v_permlane16_swap_b32_e32 v152, v154
	v_permlane16_swap_b32_e32 v153, v155
	global_store_dwordx4 v252, v[152:155], s[6:7] offset:256
	s_nop 1
	v_permlane16_swap_b32_e32 v156, v158
	v_permlane16_swap_b32_e32 v157, v159
	global_store_dwordx4 v253, v[156:159], s[6:7] offset:256
	s_waitcnt vmcnt(16)
	s_branch .LBB0_619

; #define GAS __attribute__((address_space(1)))
; __device__ __forceinline__ uint2 pack4(f32x4 v) { return make_uint2(pack2(v[0], v[1]), pack2(v[2], v[3])); }
; template <int MODE>
; __device__ __forceinline__ void epi_elem(char* ws, float* outp, const float* b_gate, int g0, int rl, int col, f32x4 v) {
;     ...
;   } else if (MODE == E_T || MODE == E_FF) {
;     *(GAS uint2*)((u16*)(ws + (MODE == E_T ? W_T : W_FF)) + (size_t)rl * 1024 + col) = pack4(v);
;     ...
;     int rbase = cur_brow + wr * 64 + fr;
;     int cbase = cur_bcol + wc * 32 + fq * 4;
;     asm volatile("" : "+v"(rbase), "+v"(cbase));
.LBB0_615:
	s_and_b64 vcc, exec, s[4:5]
	v_ashrrev_i32_e32 v143, 31, v142
	s_cbranch_vccz .LBB0_617
	v_bfe_u32 v141, v184, 2, 2
	v_and_b32_e32 v143, 1, v141
	v_lshrrev_b32_e32 v187, 1, v141
	v_lshlrev_b32_e32 v143, 4, v143
	v_lshl_add_u32 v143, v187, 3, v143
	v_lshlrev_b32_e32 v141, 2, v141
	v_sub_u32_e32 v143, v143, v141
	v_add_u32_e32 v143, v140, v143
	v_lshlrev_b32_e32 v141, 11, v142
	v_lshl_add_u32 v250, v143, 1, v141
	v_add_u32_e32 v251, 0x8000, v250
	v_add_u32_e32 v252, 0x10000, v250
	v_add_u32_e32 v253, 0x18000, v250
	s_add_u32 s4, s2, 0x26dc0000
	s_addc_u32 s5, s3, 0
	s_add_u32 s6, s2, 0x26e00000
	s_addc_u32 s7, s3, 0
	v_cvt_pk_bf16_f32 v144, v126, v127
	v_cvt_pk_bf16_f32 v145, v128, v129
	v_cvt_pk_bf16_f32 v146, v122, v123
	v_cvt_pk_bf16_f32 v147, v124, v125
	v_cvt_pk_bf16_f32 v148, v118, v119
	v_cvt_pk_bf16_f32 v149, v120, v121
	v_cvt_pk_bf16_f32 v150, v114, v115
	v_cvt_pk_bf16_f32 v151, v116, v117
	v_permlane16_swap_b32_e32 v144, v146
	v_permlane16_swap_b32_e32 v145, v147
	global_store_dwordx4 v250, v[144:147], s[4:5]
	v_cvt_pk_bf16_f32 v152, v110, v111
	v_cvt_pk_bf16_f32 v153, v112, v113
	v_cvt_pk_bf16_f32 v154, v106, v107
	v_cvt_pk_bf16_f32 v155, v108, v109
	v_permlane16_swap_b32_e32 v148, v150
	v_permlane16_swap_b32_e32 v149, v151
	global_store_dwordx4 v251, v[148:151], s[4:5]
	v_cvt_pk_bf16_f32 v156, v102, v103
	v_cvt_pk_bf16_f32 v157, v104, v105
	v_cvt_pk_bf16_f32 v158, v98, v99
	v_cvt_pk_bf16_f32 v159, v100, v101
	v_permlane16_swap_b32_e32 v152, v154
	v_permlane16_swap_b32_e32 v153, v155
	global_store_dwordx4 v252, v[152:155], s[4:5]
	v_cvt_pk_bf16_f32 v144, v94, v95
	v_cvt_pk_bf16_f32 v145, v96, v97
	v_cvt_pk_bf16_f32 v146, v90, v91
	v_cvt_pk_bf16_f32 v147, v92, v93
	v_permlane16_swap_b32_e32 v156, v158
	v_permlane16_swap_b32_e32 v157, v159
	global_store_dwordx4 v253, v[156:159], s[4:5]
	v_cvt_pk_bf16_f32 v148, v86, v87
	v_cvt_pk_bf16_f32 v149, v88, v89
	v_cvt_pk_bf16_f32 v150, v82, v83
	v_cvt_pk_bf16_f32 v151, v84, v85
	v_permlane16_swap_b32_e32 v144, v146
	v_permlane16_swap_b32_e32 v145, v147
	global_store_dwordx4 v250, v[144:147], s[4:5] offset:256
	v_cvt_pk_bf16_f32 v152, v78, v79
	v_cvt_pk_bf16_f32 v153, v80, v81
	v_cvt_pk_bf16_f32 v154, v74, v75
	v_cvt_pk_bf16_f32 v155, v76, v77
	v_permlane16_swap_b32_e32 v148, v150
	v_permlane16_swap_b32_e32 v149, v151
	global_store_dwordx4 v251, v[148:151], s[4:5] offset:256
	v_cvt_pk_bf16_f32 v156, v70, v71
	v_cvt_pk_bf16_f32 v157, v72, v73
	v_cvt_pk_bf16_f32 v158, v66, v67
	v_cvt_pk_bf16_f32 v159, v68, v69
	v_permlane16_swap_b32_e32 v152, v154
	v_permlane16_swap_b32_e32 v153, v155
	global_store_dwordx4 v252, v[152:155], s[4:5] offset:256
	v_cvt_pk_bf16_f32 v144, v62, v63
	v_cvt_pk_bf16_f32 v145, v64, v65
	v_cvt_pk_bf16_f32 v146, v58, v59
	v_cvt_pk_bf16_f32 v147, v60, v61
	v_permlane16_swap_b32_e32 v156, v158
	v_permlane16_swap_b32_e32 v157, v159
	global_store_dwordx4 v253, v[156:159], s[4:5] offset:256
	v_cvt_pk_bf16_f32 v148, v54, v55
	v_cvt_pk_bf16_f32 v149, v56, v57
	v_cvt_pk_bf16_f32 v150, v50, v51
	v_cvt_pk_bf16_f32 v151, v52, v53
	v_permlane16_swap_b32_e32 v144, v146
	v_permlane16_swap_b32_e32 v145, v147
	global_store_dwordx4 v250, v[144:147], s[6:7]
	v_cvt_pk_bf16_f32 v152, v46, v47
	v_cvt_pk_bf16_f32 v153, v48, v49
	v_cvt_pk_bf16_f32 v154, v42, v43
	v_cvt_pk_bf16_f32 v155, v44, v45
	v_permlane16_swap_b32_e32 v148, v150
	v_permlane16_swap_b32_e32 v149, v151
	global_store_dwordx4 v251, v[148:151], s[6:7]
	v_cvt_pk_bf16_f32 v156, v38, v39
	v_cvt_pk_bf16_f32 v157, v40, v41
	v_cvt_pk_bf16_f32 v158, v34, v35
	v_cvt_pk_bf16_f32 v159, v36, v37
	v_permlane16_swap_b32_e32 v152, v154
	v_permlane16_swap_b32_e32 v153, v155
	global_store_dwordx4 v252, v[152:155], s[6:7]
	v_cvt_pk_bf16_f32 v144, v30, v31
	v_cvt_pk_bf16_f32 v145, v32, v33
	v_cvt_pk_bf16_f32 v146, v26, v27
	v_cvt_pk_bf16_f32 v147, v28, v29
	v_permlane16_swap_b32_e32 v156, v158
	v_permlane16_swap_b32_e32 v157, v159
	global_store_dwordx4 v253, v[156:159], s[6:7]
	v_cvt_pk_bf16_f32 v148, v22, v23
	v_cvt_pk_bf16_f32 v149, v24, v25
	v_cvt_pk_bf16_f32 v150, v18, v19
	v_cvt_pk_bf16_f32 v151, v20, v21
	v_permlane16_swap_b32_e32 v144, v146
	v_permlane16_swap_b32_e32 v145, v147
	global_store_dwordx4 v250, v[144:147], s[6:7] offset:256
	v_cvt_pk_bf16_f32 v152, v14, v15
	v_cvt_pk_bf16_f32 v153, v16, v17
	v_cvt_pk_bf16_f32 v154, v10, v11
	v_cvt_pk_bf16_f32 v155, v12, v13
	v_permlane16_swap_b32_e32 v148, v150
	v_permlane16_swap_b32_e32 v149, v151
	global_store_dwordx4 v251, v[148:151], s[6:7] offset:256
	v_cvt_pk_bf16_f32 v156, v6, v7
	v_cvt_pk_bf16_f32 v157, v8, v9
	v_cvt_pk_bf16_f32 v158, v2, v3
	v_cvt_pk_bf16_f32 v159, v4, v5
	v_permlane16_swap_b32_e32 v152, v154
	v_permlane16_swap_b32_e32 v153, v155
	global_store_dwordx4 v252, v[152:155], s[6:7] offset:256
	s_nop 1
	v_permlane16_swap_b32_e32 v156, v158
	v_permlane16_swap_b32_e32 v157, v159
	global_store_dwordx4 v253, v[156:159], s[6:7] offset:256
	s_waitcnt vmcnt(16)
	s_branch .LBB0_619
; #define GAS __attribute__((address_space(1)))
; __device__ __forceinline__ uint2 pack4(f32x4 v) { return make_uint2(pack2(v[0], v[1]), pack2(v[2], v[3])); }
; __device__ __forceinline__ float gelu_f(float x) {
;   const float c1 = -1.5957691216057308f * 1.4426950408889634f, c2 = c1 * 0.044715f;
;   float u = x * __builtin_fmaf(x * x, c2, c1);
;   return x * __builtin_amdgcn_rcpf(1.0f + __builtin_amdgcn_exp2f(u));
; }
; template <int MODE>
; __device__ __forceinline__ void epi_elem(char* ws, float* outp, const float* b_gate, int g0, int rl, int col, f32x4 v) {
;   if (MODE == E_U || MODE == E_GV) {
;     int lc = col & 1023;
;     f32x4 o; for (int i = 0; i < 4; ++i) o[i] = gelu_f(v[i]);
;     u16* dst = (u16*)(ws + (MODE == E_U ? W_U : W_GV));
;     *(GAS uint2*)(dst + (size_t)rl * 1024 + lc) = pack4(o);
.LBB0_617:
	s_andn2_b64 vcc, exec, s[8:9]
	s_cbranch_vccnz .LBB0_619
	v_bfe_u32 v141, v184, 2, 2
	v_and_b32_e32 v143, 1, v141
	v_lshrrev_b32_e32 v187, 1, v141
	v_lshlrev_b32_e32 v143, 4, v143
	v_lshl_add_u32 v143, v187, 3, v143
	v_lshlrev_b32_e32 v141, 2, v141
	v_sub_u32_e32 v143, v143, v141
	v_add_u32_e32 v143, v140, v143
	v_and_b32_e32 v143, 0x3ff, v143
	v_lshlrev_b32_e32 v141, 11, v142
	v_lshl_add_u32 v250, v143, 1, v141
	v_add_u32_e32 v251, 0x8000, v250
	v_add_u32_e32 v252, 0x10000, v250
	v_add_u32_e32 v253, 0x18000, v250
	s_add_u32 s4, s2, 0x65c0000
	s_addc_u32 s5, s3, 0
	s_add_u32 s6, s2, 0x6600000
	s_addc_u32 s7, s3, 0
	s_mov_b32 s18, 0xbdd2d3e7
	v_mul_f32_e32 v160, v126, v126
	v_mul_f32_e32 v161, v127, v127
	v_mul_f32_e32 v162, v128, v128
	v_mul_f32_e32 v163, v129, v129
	v_mul_f32_e32 v164, v122, v122
	v_mul_f32_e32 v165, v123, v123
	v_mul_f32_e32 v166, v124, v124
	v_mul_f32_e32 v167, v125, v125
	v_fma_f32 v160, v160, s18, v198
	v_fma_f32 v161, v161, s18, v198
	v_fma_f32 v162, v162, s18, v198
	v_fma_f32 v163, v163, s18, v198
	v_fma_f32 v164, v164, s18, v198
	v_fma_f32 v165, v165, s18, v198
	v_fma_f32 v166, v166, s18, v198
	v_fma_f32 v167, v167, s18, v198
	v_mul_f32_e32 v160, v126, v160
	v_mul_f32_e32 v161, v127, v161
	v_mul_f32_e32 v162, v128, v162
	v_mul_f32_e32 v163, v129, v163
	v_mul_f32_e32 v164, v122, v164
	v_mul_f32_e32 v165, v123, v165
	v_mul_f32_e32 v166, v124, v166
	v_mul_f32_e32 v167, v125, v167
	v_exp_f32_e32 v160, v160
	v_exp_f32_e32 v161, v161
	v_exp_f32_e32 v162, v162
	v_exp_f32_e32 v163, v163
	v_exp_f32_e32 v164, v164
	v_exp_f32_e32 v165, v165
	v_exp_f32_e32 v166, v166
	v_exp_f32_e32 v167, v167
	v_add_f32_e32 v160, 1.0, v160
	v_add_f32_e32 v161, 1.0, v161
	v_add_f32_e32 v162, 1.0, v162
	v_add_f32_e32 v163, 1.0, v163
	v_add_f32_e32 v164, 1.0, v164
	v_add_f32_e32 v165, 1.0, v165
	v_add_f32_e32 v166, 1.0, v166
	v_add_f32_e32 v167, 1.0, v167
	v_rcp_f32_e32 v160, v160
	v_rcp_f32_e32 v161, v161
	v_rcp_f32_e32 v162, v162
	v_rcp_f32_e32 v163, v163
	v_rcp_f32_e32 v164, v164
	v_rcp_f32_e32 v165, v165
	v_rcp_f32_e32 v166, v166
	v_rcp_f32_e32 v167, v167
	v_mul_f32_e32 v160, v126, v160
	v_mul_f32_e32 v161, v127, v161
	v_mul_f32_e32 v162, v128, v162
	v_mul_f32_e32 v163, v129, v163
	v_mul_f32_e32 v164, v122, v164
	v_mul_f32_e32 v165, v123, v165
	v_mul_f32_e32 v166, v124, v166
	v_mul_f32_e32 v167, v125, v167
	v_cvt_pk_bf16_f32 v144, v160, v161
	v_cvt_pk_bf16_f32 v145, v162, v163
	v_cvt_pk_bf16_f32 v146, v164, v165
	v_cvt_pk_bf16_f32 v147, v166, v167
	v_mul_f32_e32 v168, v118, v118
	v_mul_f32_e32 v169, v119, v119
	v_mul_f32_e32 v170, v120, v120
	v_mul_f32_e32 v171, v121, v121
	v_mul_f32_e32 v172, v114, v114
	v_mul_f32_e32 v173, v115, v115
	v_mul_f32_e32 v174, v116, v116
	v_mul_f32_e32 v175, v117, v117
	v_fma_f32 v168, v168, s18, v198
	v_fma_f32 v169, v169, s18, v198
	v_fma_f32 v170, v170, s18, v198
	v_fma_f32 v171, v171, s18, v198
	v_fma_f32 v172, v172, s18, v198
	v_fma_f32 v173, v173, s18, v198
	v_fma_f32 v174, v174, s18, v198
	v_fma_f32 v175, v175, s18, v198
	v_mul_f32_e32 v168, v118, v168
	v_mul_f32_e32 v169, v119, v169
	v_mul_f32_e32 v170, v120, v170
	v_mul_f32_e32 v171, v121, v171
	v_mul_f32_e32 v172, v114, v172
	v_mul_f32_e32 v173, v115, v173
	v_mul_f32_e32 v174, v116, v174
	v_mul_f32_e32 v175, v117, v175
	v_exp_f32_e32 v168, v168
	v_exp_f32_e32 v169, v169
	v_exp_f32_e32 v170, v170
	v_exp_f32_e32 v171, v171
	v_exp_f32_e32 v172, v172
	v_exp_f32_e32 v173, v173
	v_exp_f32_e32 v174, v174
	v_exp_f32_e32 v175, v175
	v_add_f32_e32 v168, 1.0, v168
	v_add_f32_e32 v169, 1.0, v169
	v_add_f32_e32 v170, 1.0, v170
	v_add_f32_e32 v171, 1.0, v171
	v_add_f32_e32 v172, 1.0, v172
	v_add_f32_e32 v173, 1.0, v173
	v_add_f32_e32 v174, 1.0, v174
	v_add_f32_e32 v175, 1.0, v175
	v_rcp_f32_e32 v168, v168
	v_rcp_f32_e32 v169, v169
	v_rcp_f32_e32 v170, v170
	v_rcp_f32_e32 v171, v171
	v_rcp_f32_e32 v172, v172
	v_rcp_f32_e32 v173, v173
	v_rcp_f32_e32 v174, v174
	v_rcp_f32_e32 v175, v175
	v_mul_f32_e32 v168, v118, v168
	v_mul_f32_e32 v169, v119, v169
	v_mul_f32_e32 v170, v120, v170
	v_mul_f32_e32 v171, v121, v171
	v_mul_f32_e32 v172, v114, v172
	v_mul_f32_e32 v173, v115, v173
	v_mul_f32_e32 v174, v116, v174
	v_mul_f32_e32 v175, v117, v175
	v_cvt_pk_bf16_f32 v148, v168, v169
	v_cvt_pk_bf16_f32 v149, v170, v171
	v_cvt_pk_bf16_f32 v150, v172, v173
	v_cvt_pk_bf16_f32 v151, v174, v175
	v_permlane16_swap_b32_e32 v144, v146
	v_permlane16_swap_b32_e32 v145, v147
	global_store_dwordx4 v250, v[144:147], s[4:5]
	v_mul_f32_e32 v160, v110, v110
	v_mul_f32_e32 v161, v111, v111
	v_mul_f32_e32 v162, v112, v112
	v_mul_f32_e32 v163, v113, v113
	v_mul_f32_e32 v164, v106, v106
	v_mul_f32_e32 v165, v107, v107
	v_mul_f32_e32 v166, v108, v108
	v_mul_f32_e32 v167, v109, v109
	v_fma_f32 v160, v160, s18, v198
	v_fma_f32 v161, v161, s18, v198
	v_fma_f32 v162, v162, s18, v198
	v_fma_f32 v163, v163, s18, v198
	v_fma_f32 v164, v164, s18, v198
	v_fma_f32 v165, v165, s18, v198
	v_fma_f32 v166, v166, s18, v198
	v_fma_f32 v167, v167, s18, v198
	v_mul_f32_e32 v160, v110, v160
	v_mul_f32_e32 v161, v111, v161
	v_mul_f32_e32 v162, v112, v162
	v_mul_f32_e32 v163, v113, v163
	v_mul_f32_e32 v164, v106, v164
	v_mul_f32_e32 v165, v107, v165
	v_mul_f32_e32 v166, v108, v166
	v_mul_f32_e32 v167, v109, v167
	v_exp_f32_e32 v160, v160
	v_exp_f32_e32 v161, v161
	v_exp_f32_e32 v162, v162
	v_exp_f32_e32 v163, v163
	v_exp_f32_e32 v164, v164
	v_exp_f32_e32 v165, v165
	v_exp_f32_e32 v166, v166
	v_exp_f32_e32 v167, v167
	v_add_f32_e32 v160, 1.0, v160
	v_add_f32_e32 v161, 1.0, v161
	v_add_f32_e32 v162, 1.0, v162
	v_add_f32_e32 v163, 1.0, v163
	v_add_f32_e32 v164, 1.0, v164
	v_add_f32_e32 v165, 1.0, v165
; #define GAS __attribute__((address_space(1)))
; __device__ __forceinline__ uint2 pack4(f32x4 v) { return make_uint2(pack2(v[0], v[1]), pack2(v[2], v[3])); }
; __device__ __forceinline__ float gelu_f(float x) {
;   const float c1 = -1.5957691216057308f * 1.4426950408889634f, c2 = c1 * 0.044715f;
;   float u = x * __builtin_fmaf(x * x, c2, c1);
;   return x * __builtin_amdgcn_rcpf(1.0f + __builtin_amdgcn_exp2f(u));
; }
; template <int MODE>
; __device__ __forceinline__ void epi_elem(char* ws, float* outp, const float* b_gate, int g0, int rl, int col, f32x4 v) {
;   if (MODE == E_U || MODE == E_GV) {
;     int lc = col & 1023;
;     f32x4 o; for (int i = 0; i < 4; ++i) o[i] = gelu_f(v[i]);
;     u16* dst = (u16*)(ws + (MODE == E_U ? W_U : W_GV));
;     *(GAS uint2*)(dst + (size_t)rl * 1024 + lc) = pack4(o);
	v_add_f32_e32 v166, 1.0, v166
	v_add_f32_e32 v167, 1.0, v167
	v_rcp_f32_e32 v160, v160
	v_rcp_f32_e32 v161, v161
	v_rcp_f32_e32 v162, v162
	v_rcp_f32_e32 v163, v163
	v_rcp_f32_e32 v164, v164
	v_rcp_f32_e32 v165, v165
	v_rcp_f32_e32 v166, v166
	v_rcp_f32_e32 v167, v167
	v_mul_f32_e32 v160, v110, v160
	v_mul_f32_e32 v161, v111, v161
	v_mul_f32_e32 v162, v112, v162
	v_mul_f32_e32 v163, v113, v163
	v_mul_f32_e32 v164, v106, v164
	v_mul_f32_e32 v165, v107, v165
	v_mul_f32_e32 v166, v108, v166
	v_mul_f32_e32 v167, v109, v167
	v_cvt_pk_bf16_f32 v152, v160, v161
	v_cvt_pk_bf16_f32 v153, v162, v163
	v_cvt_pk_bf16_f32 v154, v164, v165
	v_cvt_pk_bf16_f32 v155, v166, v167
	v_permlane16_swap_b32_e32 v148, v150
	v_permlane16_swap_b32_e32 v149, v151
	global_store_dwordx4 v251, v[148:151], s[4:5]
	v_mul_f32_e32 v168, v102, v102
	v_mul_f32_e32 v169, v103, v103
	v_mul_f32_e32 v170, v104, v104
	v_mul_f32_e32 v171, v105, v105
	v_mul_f32_e32 v172, v98, v98
	v_mul_f32_e32 v173, v99, v99
	v_mul_f32_e32 v174, v100, v100
	v_mul_f32_e32 v175, v101, v101
	v_fma_f32 v168, v168, s18, v198
	v_fma_f32 v169, v169, s18, v198
	v_fma_f32 v170, v170, s18, v198
	v_fma_f32 v171, v171, s18, v198
	v_fma_f32 v172, v172, s18, v198
	v_fma_f32 v173, v173, s18, v198
	v_fma_f32 v174, v174, s18, v198
	v_fma_f32 v175, v175, s18, v198
	v_mul_f32_e32 v168, v102, v168
	v_mul_f32_e32 v169, v103, v169
	v_mul_f32_e32 v170, v104, v170
	v_mul_f32_e32 v171, v105, v171
	v_mul_f32_e32 v172, v98, v172
	v_mul_f32_e32 v173, v99, v173
	v_mul_f32_e32 v174, v100, v174
	v_mul_f32_e32 v175, v101, v175
	v_exp_f32_e32 v168, v168
	v_exp_f32_e32 v169, v169
	v_exp_f32_e32 v170, v170
	v_exp_f32_e32 v171, v171
	v_exp_f32_e32 v172, v172
	v_exp_f32_e32 v173, v173
	v_exp_f32_e32 v174, v174
	v_exp_f32_e32 v175, v175
	v_add_f32_e32 v168, 1.0, v168
	v_add_f32_e32 v169, 1.0, v169
	v_add_f32_e32 v170, 1.0, v170
	v_add_f32_e32 v171, 1.0, v171
	v_add_f32_e32 v172, 1.0, v172
	v_add_f32_e32 v173, 1.0, v173
	v_add_f32_e32 v174, 1.0, v174
	v_add_f32_e32 v175, 1.0, v175
	v_rcp_f32_e32 v168, v168
	v_rcp_f32_e32 v169, v169
	v_rcp_f32_e32 v170, v170
	v_rcp_f32_e32 v171, v171
	v_rcp_f32_e32 v172, v172
	v_rcp_f32_e32 v173, v173
	v_rcp_f32_e32 v174, v174
	v_rcp_f32_e32 v175, v175
	v_mul_f32_e32 v168, v102, v168
	v_mul_f32_e32 v169, v103, v169
	v_mul_f32_e32 v170, v104, v170
	v_mul_f32_e32 v171, v105, v171
	v_mul_f32_e32 v172, v98, v172
	v_mul_f32_e32 v173, v99, v173
	v_mul_f32_e32 v174, v100, v174
	v_mul_f32_e32 v175, v101, v175
	v_cvt_pk_bf16_f32 v156, v168, v169
	v_cvt_pk_bf16_f32 v157, v170, v171
	v_cvt_pk_bf16_f32 v158, v172, v173
	v_cvt_pk_bf16_f32 v159, v174, v175
	v_permlane16_swap_b32_e32 v152, v154
	v_permlane16_swap_b32_e32 v153, v155
	global_store_dwordx4 v252, v[152:155], s[4:5]
	v_mul_f32_e32 v160, v94, v94
	v_mul_f32_e32 v161, v95, v95
	v_mul_f32_e32 v162, v96, v96
	v_mul_f32_e32 v163, v97, v97
	v_mul_f32_e32 v164, v90, v90
	v_mul_f32_e32 v165, v91, v91
	v_mul_f32_e32 v166, v92, v92
	v_mul_f32_e32 v167, v93, v93
	v_fma_f32 v160, v160, s18, v198
	v_fma_f32 v161, v161, s18, v198
	v_fma_f32 v162, v162, s18, v198
	v_fma_f32 v163, v163, s18, v198
	v_fma_f32 v164, v164, s18, v198
	v_fma_f32 v165, v165, s18, v198
	v_fma_f32 v166, v166, s18, v198
	v_fma_f32 v167, v167, s18, v198
	v_mul_f32_e32 v160, v94, v160
	v_mul_f32_e32 v161, v95, v161
	v_mul_f32_e32 v162, v96, v162
	v_mul_f32_e32 v163, v97, v163
	v_mul_f32_e32 v164, v90, v164
	v_mul_f32_e32 v165, v91, v165
	v_mul_f32_e32 v166, v92, v166
	v_mul_f32_e32 v167, v93, v167
	v_exp_f32_e32 v160, v160
	v_exp_f32_e32 v161, v161
	v_exp_f32_e32 v162, v162
	v_exp_f32_e32 v163, v163
	v_exp_f32_e32 v164, v164
	v_exp_f32_e32 v165, v165
	v_exp_f32_e32 v166, v166
	v_exp_f32_e32 v167, v167
	v_add_f32_e32 v160, 1.0, v160
	v_add_f32_e32 v161, 1.0, v161
	v_add_f32_e32 v162, 1.0, v162
	v_add_f32_e32 v163, 1.0, v163
	v_add_f32_e32 v164, 1.0, v164
	v_add_f32_e32 v165, 1.0, v165
	v_add_f32_e32 v166, 1.0, v166
	v_add_f32_e32 v167, 1.0, v167
	v_rcp_f32_e32 v160, v160
	v_rcp_f32_e32 v161, v161
	v_rcp_f32_e32 v162, v162
	v_rcp_f32_e32 v163, v163
	v_rcp_f32_e32 v164, v164
	v_rcp_f32_e32 v165, v165
	v_rcp_f32_e32 v166, v166
	v_rcp_f32_e32 v167, v167
	v_mul_f32_e32 v160, v94, v160
	v_mul_f32_e32 v161, v95, v161
	v_mul_f32_e32 v162, v96, v162
	v_mul_f32_e32 v163, v97, v163
	v_mul_f32_e32 v164, v90, v164
	v_mul_f32_e32 v165, v91, v165
	v_mul_f32_e32 v166, v92, v166
	v_mul_f32_e32 v167, v93, v167
	v_cvt_pk_bf16_f32 v144, v160, v161
	v_cvt_pk_bf16_f32 v145, v162, v163
	v_cvt_pk_bf16_f32 v146, v164, v165
	v_cvt_pk_bf16_f32 v147, v166, v167
	v_permlane16_swap_b32_e32 v156, v158
	v_permlane16_swap_b32_e32 v157, v159
	global_store_dwordx4 v253, v[156:159], s[4:5]
	v_mul_f32_e32 v168, v86, v86
	v_mul_f32_e32 v169, v87, v87
	v_mul_f32_e32 v170, v88, v88
	v_mul_f32_e32 v171, v89, v89
	v_mul_f32_e32 v172, v82, v82
	v_mul_f32_e32 v173, v83, v83
	v_mul_f32_e32 v174, v84, v84
	v_mul_f32_e32 v175, v85, v85
	v_fma_f32 v168, v168, s18, v198
	v_fma_f32 v169, v169, s18, v198
	v_fma_f32 v170, v170, s18, v198
	v_fma_f32 v171, v171, s18, v198
	v_fma_f32 v172, v172, s18, v198
	v_fma_f32 v173, v173, s18, v198
	v_fma_f32 v174, v174, s18, v198
	v_fma_f32 v175, v175, s18, v198
	v_mul_f32_e32 v168, v86, v168
	v_mul_f32_e32 v169, v87, v169
	v_mul_f32_e32 v170, v88, v170
	v_mul_f32_e32 v171, v89, v171
	v_mul_f32_e32 v172, v82, v172
	v_mul_f32_e32 v173, v83, v173
	v_mul_f32_e32 v174, v84, v174
	v_mul_f32_e32 v175, v85, v175
	v_exp_f32_e32 v168, v168
	v_exp_f32_e32 v169, v169
	v_exp_f32_e32 v170, v170
	v_exp_f32_e32 v171, v171
	v_exp_f32_e32 v172, v172
	v_exp_f32_e32 v173, v173
	v_exp_f32_e32 v174, v174
	v_exp_f32_e32 v175, v175
; #define GAS __attribute__((address_space(1)))
; __device__ __forceinline__ uint2 pack4(f32x4 v) { return make_uint2(pack2(v[0], v[1]), pack2(v[2], v[3])); }
; __device__ __forceinline__ float gelu_f(float x) {
;   const float c1 = -1.5957691216057308f * 1.4426950408889634f, c2 = c1 * 0.044715f;
;   float u = x * __builtin_fmaf(x * x, c2, c1);
;   return x * __builtin_amdgcn_rcpf(1.0f + __builtin_amdgcn_exp2f(u));
; }
; template <int MODE>
; __device__ __forceinline__ void epi_elem(char* ws, float* outp, const float* b_gate, int g0, int rl, int col, f32x4 v) {
;   if (MODE == E_U || MODE == E_GV) {
;     int lc = col & 1023;
;     f32x4 o; for (int i = 0; i < 4; ++i) o[i] = gelu_f(v[i]);
;     u16* dst = (u16*)(ws + (MODE == E_U ? W_U : W_GV));
;     *(GAS uint2*)(dst + (size_t)rl * 1024 + lc) = pack4(o);
	v_add_f32_e32 v168, 1.0, v168
	v_add_f32_e32 v169, 1.0, v169
	v_add_f32_e32 v170, 1.0, v170
	v_add_f32_e32 v171, 1.0, v171
	v_add_f32_e32 v172, 1.0, v172
	v_add_f32_e32 v173, 1.0, v173
	v_add_f32_e32 v174, 1.0, v174
	v_add_f32_e32 v175, 1.0, v175
	v_rcp_f32_e32 v168, v168
	v_rcp_f32_e32 v169, v169
	v_rcp_f32_e32 v170, v170
	v_rcp_f32_e32 v171, v171
	v_rcp_f32_e32 v172, v172
	v_rcp_f32_e32 v173, v173
	v_rcp_f32_e32 v174, v174
	v_rcp_f32_e32 v175, v175
	v_mul_f32_e32 v168, v86, v168
	v_mul_f32_e32 v169, v87, v169
	v_mul_f32_e32 v170, v88, v170
	v_mul_f32_e32 v171, v89, v171
	v_mul_f32_e32 v172, v82, v172
	v_mul_f32_e32 v173, v83, v173
	v_mul_f32_e32 v174, v84, v174
	v_mul_f32_e32 v175, v85, v175
	v_cvt_pk_bf16_f32 v148, v168, v169
	v_cvt_pk_bf16_f32 v149, v170, v171
	v_cvt_pk_bf16_f32 v150, v172, v173
	v_cvt_pk_bf16_f32 v151, v174, v175
	v_permlane16_swap_b32_e32 v144, v146
	v_permlane16_swap_b32_e32 v145, v147
	global_store_dwordx4 v250, v[144:147], s[4:5] offset:256
	v_mul_f32_e32 v160, v78, v78
	v_mul_f32_e32 v161, v79, v79
	v_mul_f32_e32 v162, v80, v80
	v_mul_f32_e32 v163, v81, v81
	v_mul_f32_e32 v164, v74, v74
	v_mul_f32_e32 v165, v75, v75
	v_mul_f32_e32 v166, v76, v76
	v_mul_f32_e32 v167, v77, v77
	v_fma_f32 v160, v160, s18, v198
	v_fma_f32 v161, v161, s18, v198
	v_fma_f32 v162, v162, s18, v198
	v_fma_f32 v163, v163, s18, v198
	v_fma_f32 v164, v164, s18, v198
	v_fma_f32 v165, v165, s18, v198
	v_fma_f32 v166, v166, s18, v198
	v_fma_f32 v167, v167, s18, v198
	v_mul_f32_e32 v160, v78, v160
	v_mul_f32_e32 v161, v79, v161
	v_mul_f32_e32 v162, v80, v162
	v_mul_f32_e32 v163, v81, v163
	v_mul_f32_e32 v164, v74, v164
	v_mul_f32_e32 v165, v75, v165
	v_mul_f32_e32 v166, v76, v166
	v_mul_f32_e32 v167, v77, v167
	v_exp_f32_e32 v160, v160
	v_exp_f32_e32 v161, v161
	v_exp_f32_e32 v162, v162
	v_exp_f32_e32 v163, v163
	v_exp_f32_e32 v164, v164
	v_exp_f32_e32 v165, v165
	v_exp_f32_e32 v166, v166
	v_exp_f32_e32 v167, v167
	v_add_f32_e32 v160, 1.0, v160
	v_add_f32_e32 v161, 1.0, v161
	v_add_f32_e32 v162, 1.0, v162
	v_add_f32_e32 v163, 1.0, v163
	v_add_f32_e32 v164, 1.0, v164
	v_add_f32_e32 v165, 1.0, v165
	v_add_f32_e32 v166, 1.0, v166
	v_add_f32_e32 v167, 1.0, v167
	v_rcp_f32_e32 v160, v160
	v_rcp_f32_e32 v161, v161
	v_rcp_f32_e32 v162, v162
	v_rcp_f32_e32 v163, v163
	v_rcp_f32_e32 v164, v164
	v_rcp_f32_e32 v165, v165
	v_rcp_f32_e32 v166, v166
	v_rcp_f32_e32 v167, v167
	v_mul_f32_e32 v160, v78, v160
	v_mul_f32_e32 v161, v79, v161
	v_mul_f32_e32 v162, v80, v162
	v_mul_f32_e32 v163, v81, v163
	v_mul_f32_e32 v164, v74, v164
	v_mul_f32_e32 v165, v75, v165
	v_mul_f32_e32 v166, v76, v166
	v_mul_f32_e32 v167, v77, v167
	v_cvt_pk_bf16_f32 v152, v160, v161
	v_cvt_pk_bf16_f32 v153, v162, v163
	v_cvt_pk_bf16_f32 v154, v164, v165
	v_cvt_pk_bf16_f32 v155, v166, v167
	v_permlane16_swap_b32_e32 v148, v150
	v_permlane16_swap_b32_e32 v149, v151
	global_store_dwordx4 v251, v[148:151], s[4:5] offset:256
	v_mul_f32_e32 v168, v70, v70
	v_mul_f32_e32 v169, v71, v71
	v_mul_f32_e32 v170, v72, v72
	v_mul_f32_e32 v171, v73, v73
	v_mul_f32_e32 v172, v66, v66
	v_mul_f32_e32 v173, v67, v67
	v_mul_f32_e32 v174, v68, v68
	v_mul_f32_e32 v175, v69, v69
	v_fma_f32 v168, v168, s18, v198
	v_fma_f32 v169, v169, s18, v198
	v_fma_f32 v170, v170, s18, v198
	v_fma_f32 v171, v171, s18, v198
	v_fma_f32 v172, v172, s18, v198
	v_fma_f32 v173, v173, s18, v198
	v_fma_f32 v174, v174, s18, v198
	v_fma_f32 v175, v175, s18, v198
	v_mul_f32_e32 v168, v70, v168
	v_mul_f32_e32 v169, v71, v169
	v_mul_f32_e32 v170, v72, v170
	v_mul_f32_e32 v171, v73, v171
	v_mul_f32_e32 v172, v66, v172
	v_mul_f32_e32 v173, v67, v173
	v_mul_f32_e32 v174, v68, v174
	v_mul_f32_e32 v175, v69, v175
	v_exp_f32_e32 v168, v168
	v_exp_f32_e32 v169, v169
	v_exp_f32_e32 v170, v170
	v_exp_f32_e32 v171, v171
	v_exp_f32_e32 v172, v172
	v_exp_f32_e32 v173, v173
	v_exp_f32_e32 v174, v174
	v_exp_f32_e32 v175, v175
	v_add_f32_e32 v168, 1.0, v168
	v_add_f32_e32 v169, 1.0, v169
	v_add_f32_e32 v170, 1.0, v170
	v_add_f32_e32 v171, 1.0, v171
	v_add_f32_e32 v172, 1.0, v172
	v_add_f32_e32 v173, 1.0, v173
	v_add_f32_e32 v174, 1.0, v174
	v_add_f32_e32 v175, 1.0, v175
	v_rcp_f32_e32 v168, v168
	v_rcp_f32_e32 v169, v169
	v_rcp_f32_e32 v170, v170
	v_rcp_f32_e32 v171, v171
	v_rcp_f32_e32 v172, v172
	v_rcp_f32_e32 v173, v173
	v_rcp_f32_e32 v174, v174
	v_rcp_f32_e32 v175, v175
	v_mul_f32_e32 v168, v70, v168
	v_mul_f32_e32 v169, v71, v169
	v_mul_f32_e32 v170, v72, v170
	v_mul_f32_e32 v171, v73, v171
	v_mul_f32_e32 v172, v66, v172
	v_mul_f32_e32 v173, v67, v173
	v_mul_f32_e32 v174, v68, v174
	v_mul_f32_e32 v175, v69, v175
	v_cvt_pk_bf16_f32 v156, v168, v169
	v_cvt_pk_bf16_f32 v157, v170, v171
	v_cvt_pk_bf16_f32 v158, v172, v173
	v_cvt_pk_bf16_f32 v159, v174, v175
	v_permlane16_swap_b32_e32 v152, v154
	v_permlane16_swap_b32_e32 v153, v155
	global_store_dwordx4 v252, v[152:155], s[4:5] offset:256
	v_mul_f32_e32 v160, v62, v62
	v_mul_f32_e32 v161, v63, v63
	v_mul_f32_e32 v162, v64, v64
	v_mul_f32_e32 v163, v65, v65
	v_mul_f32_e32 v164, v58, v58
	v_mul_f32_e32 v165, v59, v59
	v_mul_f32_e32 v166, v60, v60
	v_mul_f32_e32 v167, v61, v61
	v_fma_f32 v160, v160, s18, v198
	v_fma_f32 v161, v161, s18, v198
	v_fma_f32 v162, v162, s18, v198
	v_fma_f32 v163, v163, s18, v198
	v_fma_f32 v164, v164, s18, v198
	v_fma_f32 v165, v165, s18, v198
	v_fma_f32 v166, v166, s18, v198
	v_fma_f32 v167, v167, s18, v198
	v_mul_f32_e32 v160, v62, v160
	v_mul_f32_e32 v161, v63, v161
	v_mul_f32_e32 v162, v64, v162
	v_mul_f32_e32 v163, v65, v163
	v_mul_f32_e32 v164, v58, v164
	v_mul_f32_e32 v165, v59, v165
	v_mul_f32_e32 v166, v60, v166
	v_mul_f32_e32 v167, v61, v167
	v_exp_f32_e32 v160, v160
; #define GAS __attribute__((address_space(1)))
; __device__ __forceinline__ uint2 pack4(f32x4 v) { return make_uint2(pack2(v[0], v[1]), pack2(v[2], v[3])); }
; __device__ __forceinline__ float gelu_f(float x) {
;   const float c1 = -1.5957691216057308f * 1.4426950408889634f, c2 = c1 * 0.044715f;
;   float u = x * __builtin_fmaf(x * x, c2, c1);
;   return x * __builtin_amdgcn_rcpf(1.0f + __builtin_amdgcn_exp2f(u));
; }
; template <int MODE>
; __device__ __forceinline__ void epi_elem(char* ws, float* outp, const float* b_gate, int g0, int rl, int col, f32x4 v) {
;   if (MODE == E_U || MODE == E_GV) {
;     int lc = col & 1023;
;     f32x4 o; for (int i = 0; i < 4; ++i) o[i] = gelu_f(v[i]);
;     u16* dst = (u16*)(ws + (MODE == E_U ? W_U : W_GV));
;     *(GAS uint2*)(dst + (size_t)rl * 1024 + lc) = pack4(o);
	v_exp_f32_e32 v161, v161
	v_exp_f32_e32 v162, v162
	v_exp_f32_e32 v163, v163
	v_exp_f32_e32 v164, v164
	v_exp_f32_e32 v165, v165
	v_exp_f32_e32 v166, v166
	v_exp_f32_e32 v167, v167
	v_add_f32_e32 v160, 1.0, v160
	v_add_f32_e32 v161, 1.0, v161
	v_add_f32_e32 v162, 1.0, v162
	v_add_f32_e32 v163, 1.0, v163
	v_add_f32_e32 v164, 1.0, v164
	v_add_f32_e32 v165, 1.0, v165
	v_add_f32_e32 v166, 1.0, v166
	v_add_f32_e32 v167, 1.0, v167
	v_rcp_f32_e32 v160, v160
	v_rcp_f32_e32 v161, v161
	v_rcp_f32_e32 v162, v162
	v_rcp_f32_e32 v163, v163
	v_rcp_f32_e32 v164, v164
	v_rcp_f32_e32 v165, v165
	v_rcp_f32_e32 v166, v166
	v_rcp_f32_e32 v167, v167
	v_mul_f32_e32 v160, v62, v160
	v_mul_f32_e32 v161, v63, v161
	v_mul_f32_e32 v162, v64, v162
	v_mul_f32_e32 v163, v65, v163
	v_mul_f32_e32 v164, v58, v164
	v_mul_f32_e32 v165, v59, v165
	v_mul_f32_e32 v166, v60, v166
	v_mul_f32_e32 v167, v61, v167
	v_cvt_pk_bf16_f32 v144, v160, v161
	v_cvt_pk_bf16_f32 v145, v162, v163
	v_cvt_pk_bf16_f32 v146, v164, v165
	v_cvt_pk_bf16_f32 v147, v166, v167
	v_permlane16_swap_b32_e32 v156, v158
	v_permlane16_swap_b32_e32 v157, v159
	global_store_dwordx4 v253, v[156:159], s[4:5] offset:256
	v_mul_f32_e32 v168, v54, v54
	v_mul_f32_e32 v169, v55, v55
	v_mul_f32_e32 v170, v56, v56
	v_mul_f32_e32 v171, v57, v57
	v_mul_f32_e32 v172, v50, v50
	v_mul_f32_e32 v173, v51, v51
	v_mul_f32_e32 v174, v52, v52
	v_mul_f32_e32 v175, v53, v53
	v_fma_f32 v168, v168, s18, v198
	v_fma_f32 v169, v169, s18, v198
	v_fma_f32 v170, v170, s18, v198
	v_fma_f32 v171, v171, s18, v198
	v_fma_f32 v172, v172, s18, v198
	v_fma_f32 v173, v173, s18, v198
	v_fma_f32 v174, v174, s18, v198
	v_fma_f32 v175, v175, s18, v198
	v_mul_f32_e32 v168, v54, v168
	v_mul_f32_e32 v169, v55, v169
	v_mul_f32_e32 v170, v56, v170
	v_mul_f32_e32 v171, v57, v171
	v_mul_f32_e32 v172, v50, v172
	v_mul_f32_e32 v173, v51, v173
	v_mul_f32_e32 v174, v52, v174
	v_mul_f32_e32 v175, v53, v175
	v_exp_f32_e32 v168, v168
	v_exp_f32_e32 v169, v169
	v_exp_f32_e32 v170, v170
	v_exp_f32_e32 v171, v171
	v_exp_f32_e32 v172, v172
	v_exp_f32_e32 v173, v173
	v_exp_f32_e32 v174, v174
	v_exp_f32_e32 v175, v175
	v_add_f32_e32 v168, 1.0, v168
	v_add_f32_e32 v169, 1.0, v169
	v_add_f32_e32 v170, 1.0, v170
	v_add_f32_e32 v171, 1.0, v171
	v_add_f32_e32 v172, 1.0, v172
	v_add_f32_e32 v173, 1.0, v173
	v_add_f32_e32 v174, 1.0, v174
	v_add_f32_e32 v175, 1.0, v175
	v_rcp_f32_e32 v168, v168
	v_rcp_f32_e32 v169, v169
	v_rcp_f32_e32 v170, v170
	v_rcp_f32_e32 v171, v171
	v_rcp_f32_e32 v172, v172
	v_rcp_f32_e32 v173, v173
	v_rcp_f32_e32 v174, v174
	v_rcp_f32_e32 v175, v175
	v_mul_f32_e32 v168, v54, v168
	v_mul_f32_e32 v169, v55, v169
	v_mul_f32_e32 v170, v56, v170
	v_mul_f32_e32 v171, v57, v171
	v_mul_f32_e32 v172, v50, v172
	v_mul_f32_e32 v173, v51, v173
	v_mul_f32_e32 v174, v52, v174
	v_mul_f32_e32 v175, v53, v175
	v_cvt_pk_bf16_f32 v148, v168, v169
	v_cvt_pk_bf16_f32 v149, v170, v171
	v_cvt_pk_bf16_f32 v150, v172, v173
	v_cvt_pk_bf16_f32 v151, v174, v175
	v_permlane16_swap_b32_e32 v144, v146
	v_permlane16_swap_b32_e32 v145, v147
	global_store_dwordx4 v250, v[144:147], s[6:7]
	v_mul_f32_e32 v160, v46, v46
	v_mul_f32_e32 v161, v47, v47
	v_mul_f32_e32 v162, v48, v48
	v_mul_f32_e32 v163, v49, v49
	v_mul_f32_e32 v164, v42, v42
	v_mul_f32_e32 v165, v43, v43
	v_mul_f32_e32 v166, v44, v44
	v_mul_f32_e32 v167, v45, v45
	v_fma_f32 v160, v160, s18, v198
	v_fma_f32 v161, v161, s18, v198
	v_fma_f32 v162, v162, s18, v198
	v_fma_f32 v163, v163, s18, v198
	v_fma_f32 v164, v164, s18, v198
	v_fma_f32 v165, v165, s18, v198
	v_fma_f32 v166, v166, s18, v198
	v_fma_f32 v167, v167, s18, v198
	v_mul_f32_e32 v160, v46, v160
	v_mul_f32_e32 v161, v47, v161
	v_mul_f32_e32 v162, v48, v162
	v_mul_f32_e32 v163, v49, v163
	v_mul_f32_e32 v164, v42, v164
	v_mul_f32_e32 v165, v43, v165
	v_mul_f32_e32 v166, v44, v166
	v_mul_f32_e32 v167, v45, v167
	v_exp_f32_e32 v160, v160
	v_exp_f32_e32 v161, v161
	v_exp_f32_e32 v162, v162
	v_exp_f32_e32 v163, v163
	v_exp_f32_e32 v164, v164
	v_exp_f32_e32 v165, v165
	v_exp_f32_e32 v166, v166
	v_exp_f32_e32 v167, v167
	v_add_f32_e32 v160, 1.0, v160
	v_add_f32_e32 v161, 1.0, v161
	v_add_f32_e32 v162, 1.0, v162
	v_add_f32_e32 v163, 1.0, v163
	v_add_f32_e32 v164, 1.0, v164
	v_add_f32_e32 v165, 1.0, v165
	v_add_f32_e32 v166, 1.0, v166
	v_add_f32_e32 v167, 1.0, v167
	v_rcp_f32_e32 v160, v160
	v_rcp_f32_e32 v161, v161
	v_rcp_f32_e32 v162, v162
	v_rcp_f32_e32 v163, v163
	v_rcp_f32_e32 v164, v164
	v_rcp_f32_e32 v165, v165
	v_rcp_f32_e32 v166, v166
	v_rcp_f32_e32 v167, v167
	v_mul_f32_e32 v160, v46, v160
	v_mul_f32_e32 v161, v47, v161
	v_mul_f32_e32 v162, v48, v162
	v_mul_f32_e32 v163, v49, v163
	v_mul_f32_e32 v164, v42, v164
	v_mul_f32_e32 v165, v43, v165
	v_mul_f32_e32 v166, v44, v166
	v_mul_f32_e32 v167, v45, v167
	v_cvt_pk_bf16_f32 v152, v160, v161
	v_cvt_pk_bf16_f32 v153, v162, v163
	v_cvt_pk_bf16_f32 v154, v164, v165
	v_cvt_pk_bf16_f32 v155, v166, v167
	v_permlane16_swap_b32_e32 v148, v150
	v_permlane16_swap_b32_e32 v149, v151
	global_store_dwordx4 v251, v[148:151], s[6:7]
	v_mul_f32_e32 v168, v38, v38
	v_mul_f32_e32 v169, v39, v39
	v_mul_f32_e32 v170, v40, v40
	v_mul_f32_e32 v171, v41, v41
	v_mul_f32_e32 v172, v34, v34
	v_mul_f32_e32 v173, v35, v35
	v_mul_f32_e32 v174, v36, v36
	v_mul_f32_e32 v175, v37, v37
	v_fma_f32 v168, v168, s18, v198
	v_fma_f32 v169, v169, s18, v198
	v_fma_f32 v170, v170, s18, v198
	v_fma_f32 v171, v171, s18, v198
	v_fma_f32 v172, v172, s18, v198
	v_fma_f32 v173, v173, s18, v198
	v_fma_f32 v174, v174, s18, v198
	v_fma_f32 v175, v175, s18, v198
	v_mul_f32_e32 v168, v38, v168
	v_mul_f32_e32 v169, v39, v169
	v_mul_f32_e32 v170, v40, v170
	v_mul_f32_e32 v171, v41, v171
; #define GAS __attribute__((address_space(1)))
; __device__ __forceinline__ uint2 pack4(f32x4 v) { return make_uint2(pack2(v[0], v[1]), pack2(v[2], v[3])); }
; __device__ __forceinline__ float gelu_f(float x) {
;   const float c1 = -1.5957691216057308f * 1.4426950408889634f, c2 = c1 * 0.044715f;
;   float u = x * __builtin_fmaf(x * x, c2, c1);
;   return x * __builtin_amdgcn_rcpf(1.0f + __builtin_amdgcn_exp2f(u));
; }
; template <int MODE>
; __device__ __forceinline__ void epi_elem(char* ws, float* outp, const float* b_gate, int g0, int rl, int col, f32x4 v) {
;   if (MODE == E_U || MODE == E_GV) {
;     int lc = col & 1023;
;     f32x4 o; for (int i = 0; i < 4; ++i) o[i] = gelu_f(v[i]);
;     u16* dst = (u16*)(ws + (MODE == E_U ? W_U : W_GV));
;     *(GAS uint2*)(dst + (size_t)rl * 1024 + lc) = pack4(o);
	v_mul_f32_e32 v172, v34, v172
	v_mul_f32_e32 v173, v35, v173
	v_mul_f32_e32 v174, v36, v174
	v_mul_f32_e32 v175, v37, v175
	v_exp_f32_e32 v168, v168
	v_exp_f32_e32 v169, v169
	v_exp_f32_e32 v170, v170
	v_exp_f32_e32 v171, v171
	v_exp_f32_e32 v172, v172
	v_exp_f32_e32 v173, v173
	v_exp_f32_e32 v174, v174
	v_exp_f32_e32 v175, v175
	v_add_f32_e32 v168, 1.0, v168
	v_add_f32_e32 v169, 1.0, v169
	v_add_f32_e32 v170, 1.0, v170
	v_add_f32_e32 v171, 1.0, v171
	v_add_f32_e32 v172, 1.0, v172
	v_add_f32_e32 v173, 1.0, v173
	v_add_f32_e32 v174, 1.0, v174
	v_add_f32_e32 v175, 1.0, v175
	v_rcp_f32_e32 v168, v168
	v_rcp_f32_e32 v169, v169
	v_rcp_f32_e32 v170, v170
	v_rcp_f32_e32 v171, v171
	v_rcp_f32_e32 v172, v172
	v_rcp_f32_e32 v173, v173
	v_rcp_f32_e32 v174, v174
	v_rcp_f32_e32 v175, v175
	v_mul_f32_e32 v168, v38, v168
	v_mul_f32_e32 v169, v39, v169
	v_mul_f32_e32 v170, v40, v170
	v_mul_f32_e32 v171, v41, v171
	v_mul_f32_e32 v172, v34, v172
	v_mul_f32_e32 v173, v35, v173
	v_mul_f32_e32 v174, v36, v174
	v_mul_f32_e32 v175, v37, v175
	v_cvt_pk_bf16_f32 v156, v168, v169
	v_cvt_pk_bf16_f32 v157, v170, v171
	v_cvt_pk_bf16_f32 v158, v172, v173
	v_cvt_pk_bf16_f32 v159, v174, v175
	v_permlane16_swap_b32_e32 v152, v154
	v_permlane16_swap_b32_e32 v153, v155
	global_store_dwordx4 v252, v[152:155], s[6:7]
	v_mul_f32_e32 v160, v30, v30
	v_mul_f32_e32 v161, v31, v31
	v_mul_f32_e32 v162, v32, v32
	v_mul_f32_e32 v163, v33, v33
	v_mul_f32_e32 v164, v26, v26
	v_mul_f32_e32 v165, v27, v27
	v_mul_f32_e32 v166, v28, v28
	v_mul_f32_e32 v167, v29, v29
	v_fma_f32 v160, v160, s18, v198
	v_fma_f32 v161, v161, s18, v198
	v_fma_f32 v162, v162, s18, v198
	v_fma_f32 v163, v163, s18, v198
	v_fma_f32 v164, v164, s18, v198
	v_fma_f32 v165, v165, s18, v198
	v_fma_f32 v166, v166, s18, v198
	v_fma_f32 v167, v167, s18, v198
	v_mul_f32_e32 v160, v30, v160
	v_mul_f32_e32 v161, v31, v161
	v_mul_f32_e32 v162, v32, v162
	v_mul_f32_e32 v163, v33, v163
	v_mul_f32_e32 v164, v26, v164
	v_mul_f32_e32 v165, v27, v165
	v_mul_f32_e32 v166, v28, v166
	v_mul_f32_e32 v167, v29, v167
	v_exp_f32_e32 v160, v160
	v_exp_f32_e32 v161, v161
	v_exp_f32_e32 v162, v162
	v_exp_f32_e32 v163, v163
	v_exp_f32_e32 v164, v164
	v_exp_f32_e32 v165, v165
	v_exp_f32_e32 v166, v166
	v_exp_f32_e32 v167, v167
	v_add_f32_e32 v160, 1.0, v160
	v_add_f32_e32 v161, 1.0, v161
	v_add_f32_e32 v162, 1.0, v162
	v_add_f32_e32 v163, 1.0, v163
	v_add_f32_e32 v164, 1.0, v164
	v_add_f32_e32 v165, 1.0, v165
	v_add_f32_e32 v166, 1.0, v166
	v_add_f32_e32 v167, 1.0, v167
	v_rcp_f32_e32 v160, v160
	v_rcp_f32_e32 v161, v161
	v_rcp_f32_e32 v162, v162
	v_rcp_f32_e32 v163, v163
	v_rcp_f32_e32 v164, v164
	v_rcp_f32_e32 v165, v165
	v_rcp_f32_e32 v166, v166
	v_rcp_f32_e32 v167, v167
	v_mul_f32_e32 v160, v30, v160
	v_mul_f32_e32 v161, v31, v161
	v_mul_f32_e32 v162, v32, v162
	v_mul_f32_e32 v163, v33, v163
	v_mul_f32_e32 v164, v26, v164
	v_mul_f32_e32 v165, v27, v165
	v_mul_f32_e32 v166, v28, v166
	v_mul_f32_e32 v167, v29, v167
	v_cvt_pk_bf16_f32 v144, v160, v161
	v_cvt_pk_bf16_f32 v145, v162, v163
	v_cvt_pk_bf16_f32 v146, v164, v165
	v_cvt_pk_bf16_f32 v147, v166, v167
	v_permlane16_swap_b32_e32 v156, v158
	v_permlane16_swap_b32_e32 v157, v159
	global_store_dwordx4 v253, v[156:159], s[6:7]
	v_mul_f32_e32 v168, v22, v22
	v_mul_f32_e32 v169, v23, v23
	v_mul_f32_e32 v170, v24, v24
	v_mul_f32_e32 v171, v25, v25
	v_mul_f32_e32 v172, v18, v18
	v_mul_f32_e32 v173, v19, v19
	v_mul_f32_e32 v174, v20, v20
	v_mul_f32_e32 v175, v21, v21
	v_fma_f32 v168, v168, s18, v198
	v_fma_f32 v169, v169, s18, v198
	v_fma_f32 v170, v170, s18, v198
	v_fma_f32 v171, v171, s18, v198
	v_fma_f32 v172, v172, s18, v198
	v_fma_f32 v173, v173, s18, v198
	v_fma_f32 v174, v174, s18, v198
	v_fma_f32 v175, v175, s18, v198
	v_mul_f32_e32 v168, v22, v168
	v_mul_f32_e32 v169, v23, v169
	v_mul_f32_e32 v170, v24, v170
	v_mul_f32_e32 v171, v25, v171
	v_mul_f32_e32 v172, v18, v172
	v_mul_f32_e32 v173, v19, v173
	v_mul_f32_e32 v174, v20, v174
	v_mul_f32_e32 v175, v21, v175
	v_exp_f32_e32 v168, v168
	v_exp_f32_e32 v169, v169
	v_exp_f32_e32 v170, v170
	v_exp_f32_e32 v171, v171
	v_exp_f32_e32 v172, v172
	v_exp_f32_e32 v173, v173
	v_exp_f32_e32 v174, v174
	v_exp_f32_e32 v175, v175
	v_add_f32_e32 v168, 1.0, v168
	v_add_f32_e32 v169, 1.0, v169
	v_add_f32_e32 v170, 1.0, v170
	v_add_f32_e32 v171, 1.0, v171
	v_add_f32_e32 v172, 1.0, v172
	v_add_f32_e32 v173, 1.0, v173
	v_add_f32_e32 v174, 1.0, v174
	v_add_f32_e32 v175, 1.0, v175
	v_rcp_f32_e32 v168, v168
	v_rcp_f32_e32 v169, v169
	v_rcp_f32_e32 v170, v170
	v_rcp_f32_e32 v171, v171
	v_rcp_f32_e32 v172, v172
	v_rcp_f32_e32 v173, v173
; #define GAS __attribute__((address_space(1)))
; __device__ __forceinline__ uint2 pack4(f32x4 v) { return make_uint2(pack2(v[0], v[1]), pack2(v[2], v[3])); }
; __device__ __forceinline__ float gelu_f(float x) {
;   const float c1 = -1.5957691216057308f * 1.4426950408889634f, c2 = c1 * 0.044715f;
;   float u = x * __builtin_fmaf(x * x, c2, c1);
;   return x * __builtin_amdgcn_rcpf(1.0f + __builtin_amdgcn_exp2f(u));
; }
; template <int MODE>
; __device__ __forceinline__ void epi_elem(char* ws, float* outp, const float* b_gate, int g0, int rl, int col, f32x4 v) {
;   if (MODE == E_U || MODE == E_GV) {
;     int lc = col & 1023;
;     f32x4 o; for (int i = 0; i < 4; ++i) o[i] = gelu_f(v[i]);
;     u16* dst = (u16*)(ws + (MODE == E_U ? W_U : W_GV));
;     *(GAS uint2*)(dst + (size_t)rl * 1024 + lc) = pack4(o);
	v_rcp_f32_e32 v174, v174
	v_rcp_f32_e32 v175, v175
	v_mul_f32_e32 v168, v22, v168
	v_mul_f32_e32 v169, v23, v169
	v_mul_f32_e32 v170, v24, v170
	v_mul_f32_e32 v171, v25, v171
	v_mul_f32_e32 v172, v18, v172
	v_mul_f32_e32 v173, v19, v173
	v_mul_f32_e32 v174, v20, v174
	v_mul_f32_e32 v175, v21, v175
	v_cvt_pk_bf16_f32 v148, v168, v169
	v_cvt_pk_bf16_f32 v149, v170, v171
	v_cvt_pk_bf16_f32 v150, v172, v173
	v_cvt_pk_bf16_f32 v151, v174, v175
	v_permlane16_swap_b32_e32 v144, v146
	v_permlane16_swap_b32_e32 v145, v147
	global_store_dwordx4 v250, v[144:147], s[6:7] offset:256
	v_mul_f32_e32 v160, v14, v14
	v_mul_f32_e32 v161, v15, v15
	v_mul_f32_e32 v162, v16, v16
	v_mul_f32_e32 v163, v17, v17
	v_mul_f32_e32 v164, v10, v10
	v_mul_f32_e32 v165, v11, v11
	v_mul_f32_e32 v166, v12, v12
	v_mul_f32_e32 v167, v13, v13
	v_fma_f32 v160, v160, s18, v198
	v_fma_f32 v161, v161, s18, v198
	v_fma_f32 v162, v162, s18, v198
	v_fma_f32 v163, v163, s18, v198
	v_fma_f32 v164, v164, s18, v198
	v_fma_f32 v165, v165, s18, v198
	v_fma_f32 v166, v166, s18, v198
	v_fma_f32 v167, v167, s18, v198
	v_mul_f32_e32 v160, v14, v160
	v_mul_f32_e32 v161, v15, v161
	v_mul_f32_e32 v162, v16, v162
	v_mul_f32_e32 v163, v17, v163
	v_mul_f32_e32 v164, v10, v164
	v_mul_f32_e32 v165, v11, v165
	v_mul_f32_e32 v166, v12, v166
	v_mul_f32_e32 v167, v13, v167
	v_exp_f32_e32 v160, v160
	v_exp_f32_e32 v161, v161
	v_exp_f32_e32 v162, v162
	v_exp_f32_e32 v163, v163
	v_exp_f32_e32 v164, v164
	v_exp_f32_e32 v165, v165
	v_exp_f32_e32 v166, v166
	v_exp_f32_e32 v167, v167
	v_add_f32_e32 v160, 1.0, v160
	v_add_f32_e32 v161, 1.0, v161
	v_add_f32_e32 v162, 1.0, v162
	v_add_f32_e32 v163, 1.0, v163
	v_add_f32_e32 v164, 1.0, v164
	v_add_f32_e32 v165, 1.0, v165
	v_add_f32_e32 v166, 1.0, v166
	v_add_f32_e32 v167, 1.0, v167
	v_rcp_f32_e32 v160, v160
	v_rcp_f32_e32 v161, v161
	v_rcp_f32_e32 v162, v162
	v_rcp_f32_e32 v163, v163
	v_rcp_f32_e32 v164, v164
	v_rcp_f32_e32 v165, v165
	v_rcp_f32_e32 v166, v166
	v_rcp_f32_e32 v167, v167
	v_mul_f32_e32 v160, v14, v160
	v_mul_f32_e32 v161, v15, v161
	v_mul_f32_e32 v162, v16, v162
	v_mul_f32_e32 v163, v17, v163
	v_mul_f32_e32 v164, v10, v164
	v_mul_f32_e32 v165, v11, v165
	v_mul_f32_e32 v166, v12, v166
	v_mul_f32_e32 v167, v13, v167
	v_cvt_pk_bf16_f32 v152, v160, v161
	v_cvt_pk_bf16_f32 v153, v162, v163
	v_cvt_pk_bf16_f32 v154, v164, v165
	v_cvt_pk_bf16_f32 v155, v166, v167
	v_permlane16_swap_b32_e32 v148, v150
	v_permlane16_swap_b32_e32 v149, v151
	global_store_dwordx4 v251, v[148:151], s[6:7] offset:256
	v_mul_f32_e32 v168, v6, v6
	v_mul_f32_e32 v169, v7, v7
	v_mul_f32_e32 v170, v8, v8
	v_mul_f32_e32 v171, v9, v9
	v_mul_f32_e32 v172, v2, v2
	v_mul_f32_e32 v173, v3, v3
	v_mul_f32_e32 v174, v4, v4
	v_mul_f32_e32 v175, v5, v5
	v_fma_f32 v168, v168, s18, v198
	v_fma_f32 v169, v169, s18, v198
	v_fma_f32 v170, v170, s18, v198
	v_fma_f32 v171, v171, s18, v198
	v_fma_f32 v172, v172, s18, v198
	v_fma_f32 v173, v173, s18, v198
	v_fma_f32 v174, v174, s18, v198
	v_fma_f32 v175, v175, s18, v198
	v_mul_f32_e32 v168, v6, v168
	v_mul_f32_e32 v169, v7, v169
	v_mul_f32_e32 v170, v8, v170
	v_mul_f32_e32 v171, v9, v171
	v_mul_f32_e32 v172, v2, v172
	v_mul_f32_e32 v173, v3, v173
	v_mul_f32_e32 v174, v4, v174
	v_mul_f32_e32 v175, v5, v175
	v_exp_f32_e32 v168, v168
	v_exp_f32_e32 v169, v169
	v_exp_f32_e32 v170, v170
	v_exp_f32_e32 v171, v171
	v_exp_f32_e32 v172, v172
	v_exp_f32_e32 v173, v173
	v_exp_f32_e32 v174, v174
	v_exp_f32_e32 v175, v175
	v_add_f32_e32 v168, 1.0, v168
	v_add_f32_e32 v169, 1.0, v169
	v_add_f32_e32 v170, 1.0, v170
	v_add_f32_e32 v171, 1.0, v171
	v_add_f32_e32 v172, 1.0, v172
	v_add_f32_e32 v173, 1.0, v173
	v_add_f32_e32 v174, 1.0, v174
	v_add_f32_e32 v175, 1.0, v175
	v_rcp_f32_e32 v168, v168
	v_rcp_f32_e32 v169, v169
	v_rcp_f32_e32 v170, v170
	v_rcp_f32_e32 v171, v171
	v_rcp_f32_e32 v172, v172
	v_rcp_f32_e32 v173, v173
	v_rcp_f32_e32 v174, v174
	v_rcp_f32_e32 v175, v175
	v_mul_f32_e32 v168, v6, v168
	v_mul_f32_e32 v169, v7, v169
	v_mul_f32_e32 v170, v8, v170
	v_mul_f32_e32 v171, v9, v171
	v_mul_f32_e32 v172, v2, v172
	v_mul_f32_e32 v173, v3, v173
	v_mul_f32_e32 v174, v4, v174
	v_mul_f32_e32 v175, v5, v175
	v_cvt_pk_bf16_f32 v156, v168, v169
	v_cvt_pk_bf16_f32 v157, v170, v171
	v_cvt_pk_bf16_f32 v158, v172, v173
	v_cvt_pk_bf16_f32 v159, v174, v175
	v_permlane16_swap_b32_e32 v152, v154
	v_permlane16_swap_b32_e32 v153, v155
	global_store_dwordx4 v252, v[152:155], s[6:7] offset:256
	s_nop 1
	v_permlane16_swap_b32_e32 v156, v158
	v_permlane16_swap_b32_e32 v157, v159
	global_store_dwordx4 v253, v[156:159], s[6:7] offset:256
	s_waitcnt vmcnt(16)
	s_branch .LBB0_619

; #define WAIT_V(n) asm volatile("s_waitcnt vmcnt(" #n ")" ::: "memory")
; #define BAR __builtin_amdgcn_s_barrier()
;     ...
;   while (true) {
;     f32x4 acc[2][2][4][2] = {};
;     bf16x8 At[4][2], B0[2][2], B1[2][2];
;     if (wr_s == 1) BAR;
;     if (first) WAIT_V(6); else WAIT_V(0);
;     BAR; BAR;
.LBB0_934:
	s_waitcnt vmcnt(0)
	s_xor_b64 s[2:3], s[56:57], -1
	s_and_b64 s[2:3], s[2:3], s[50:51]

; #define STAGE(P, BASE, br, kt) do { const char* _gp = (const char*)((BASE) + (long)(br) * K + (long)(kt) * BK); \
;     __builtin_amdgcn_global_load_lds((const unsigned*)(_gp + sob0), (unsigned*)((char*)(P) + wbase), 16, 0, 0); \
;     __builtin_amdgcn_global_load_lds((const unsigned*)(_gp + sob1), (unsigned*)((char*)(P) + wbase + 8192), 16, 0, 0); } while (0)
; #define LDA(dst, b, h) for (int m = 0; m < 4; ++m) for (int k = 0; k < 2; ++k) \
;     dst[m][k] = *reinterpret_cast<const bf16x8*>(aptr + (((b) * 2 + (h)) * HT * 2 + m * 2048 + k * 1024))
; #define LDB(dst, b, h) for (int n = 0; n < 2; ++n) for (int k = 0; k < 2; ++k) \
;     dst[n][k] = *reinterpret_cast<const bf16x8*>(bptr + (((b) * 2 + (h)) * HT * 2 + n * 2048 + k * 1024))
; #define MMA(ai, bj, At, Bt_) do { __builtin_amdgcn_s_setprio(1); \
;     for (int m = 0; m < 4; ++m) for (int n = 0; n < 2; ++n) for (int k = 0; k < 2; ++k) \
;       acc[ai][bj][m][n] = __builtin_amdgcn_mfma_f32_16x16x32_bf16(Bt_[n][k], At[m][k], acc[ai][bj][m][n], 0, 0, 0); \
;     __builtin_amdgcn_s_setprio(0); } while (0)
; #define WAIT_V(n) asm volatile("s_waitcnt vmcnt(" #n ")" ::: "memory")
; #define WAIT_L(n) asm volatile("s_waitcnt lgkmcnt(" #n ")" ::: "memory")
; #define BAR __builtin_amdgcn_s_barrier()
; #define SCHED __builtin_amdgcn_sched_barrier(0)
;     ...
;     f32x4 acc[2][2][4][2] = {};
;     bf16x8 At[4][2], B0[2][2], B1[2][2];
;     if (wr_s == 1) BAR;
;     if (first) WAIT_V(6); else WAIT_V(0);
;     BAR; BAR;
;     for (int t = 0; t < nt - 2; t += 2) {
;       LDB(B0, 0, 0); SCHED; LDA(At, 0, 0); STAGE(SA(1, 1), A, brow + HALF, t + 1);
;       WAIT_L(8); BAR; WAIT_L(0); MMA(0, 0, At, B0); BAR; SCHED;
.LBB0_938:
	s_andn2_b64 vcc, exec, s[2:3]
	s_cbranch_vccnz .LBB0_940
.LBB0_939:
	s_waitcnt vmcnt(0)
.LBB0_940:
	s_add_i32 s18, s70, 0x80
	v_lshl_add_u64 v[2:3], s[54:55], 0, v[136:137]
	v_mov_b32_e32 v6, s18
	v_lshl_add_u64 v[4:5], s[54:55], 0, v[138:139]
	v_mad_i64_i32 v[140:141], s[2:3], s83, v6, v[2:3]
	v_mad_i64_i32 v[142:143], s[2:3], s83, v6, v[4:5]
	v_lshl_add_u64 v[6:7], s[52:53], 0, v[136:137]
	v_mov_b32_e32 v10, s86
	v_lshl_add_u64 v[8:9], s[52:53], 0, v[138:139]
	s_add_i32 s4, s86, 0x80
	v_mad_i64_i32 v[144:145], s[2:3], s83, v10, v[6:7]
	v_mad_i64_i32 v[146:147], s[2:3], s83, v10, v[8:9]
	v_mov_b32_e32 v10, s70
	v_mad_i64_i32 v[148:149], s[2:3], s83, v10, v[2:3]
	v_mov_b32_e32 v2, s4
	v_mad_i64_i32 v[150:151], s[2:3], s83, v10, v[4:5]
	v_mad_i64_i32 v[152:153], s[2:3], s83, v2, v[6:7]
	v_mad_i64_i32 v[154:155], s[2:3], s83, v2, v[8:9]
	v_mov_b32_e32 v2, 0
	s_ashr_i32 s71, s70, 31
	s_mov_b32 s5, 0
	s_mov_b64 s[2:3], 0
	v_mov_b32_e32 v3, v2
	v_mov_b32_e32 v4, v2
	v_mov_b32_e32 v5, v2
	v_mov_b32_e32 v6, v2
	v_mov_b32_e32 v7, v2
	v_mov_b32_e32 v8, v2
	v_mov_b32_e32 v9, v2
	v_mov_b32_e32 v10, v2
	v_mov_b32_e32 v11, v2
	v_mov_b32_e32 v12, v2
	v_mov_b32_e32 v13, v2
	v_mov_b32_e32 v14, v2
	v_mov_b32_e32 v15, v2
	v_mov_b32_e32 v16, v2
	v_mov_b32_e32 v17, v2
	v_mov_b32_e32 v18, v2
	v_mov_b32_e32 v19, v2
	v_mov_b32_e32 v20, v2
	v_mov_b32_e32 v21, v2
	v_mov_b32_e32 v22, v2
	v_mov_b32_e32 v23, v2
	v_mov_b32_e32 v24, v2
	v_mov_b32_e32 v25, v2
	v_mov_b32_e32 v26, v2
	v_mov_b32_e32 v27, v2
	v_mov_b32_e32 v28, v2
	v_mov_b32_e32 v29, v2
	v_mov_b32_e32 v30, v2
	v_mov_b32_e32 v31, v2
	v_mov_b32_e32 v32, v2
	v_mov_b32_e32 v33, v2
	v_mov_b32_e32 v34, v2
	v_mov_b32_e32 v35, v2
	v_mov_b32_e32 v36, v2
	v_mov_b32_e32 v37, v2
	v_mov_b32_e32 v38, v2
	v_mov_b32_e32 v39, v2
	v_mov_b32_e32 v40, v2
	v_mov_b32_e32 v41, v2
	v_mov_b32_e32 v42, v2
	v_mov_b32_e32 v43, v2
	v_mov_b32_e32 v44, v2
	v_mov_b32_e32 v45, v2
	v_mov_b32_e32 v46, v2
	v_mov_b32_e32 v47, v2
	v_mov_b32_e32 v48, v2
	v_mov_b32_e32 v49, v2
	v_mov_b32_e32 v50, v2
	v_mov_b32_e32 v51, v2
	v_mov_b32_e32 v52, v2
	v_mov_b32_e32 v53, v2
	v_mov_b32_e32 v54, v2
	v_mov_b32_e32 v55, v2
	v_mov_b32_e32 v56, v2
	v_mov_b32_e32 v57, v2
	v_mov_b32_e32 v58, v2
	v_mov_b32_e32 v59, v2
	v_mov_b32_e32 v60, v2
	v_mov_b32_e32 v61, v2
	v_mov_b32_e32 v62, v2
	v_mov_b32_e32 v63, v2
	v_mov_b32_e32 v64, v2
	v_mov_b32_e32 v65, v2
	v_mov_b32_e32 v66, v2
	v_mov_b32_e32 v67, v2
	v_mov_b32_e32 v68, v2
	v_mov_b32_e32 v69, v2
	v_mov_b32_e32 v70, v2
	v_mov_b32_e32 v71, v2
	v_mov_b32_e32 v72, v2
	v_mov_b32_e32 v73, v2
	v_mov_b32_e32 v74, v2
	v_mov_b32_e32 v75, v2
	v_mov_b32_e32 v76, v2
	v_mov_b32_e32 v77, v2
	v_mov_b32_e32 v78, v2
	v_mov_b32_e32 v79, v2
	v_mov_b32_e32 v80, v2
	v_mov_b32_e32 v81, v2
	v_mov_b32_e32 v82, v2
	v_mov_b32_e32 v83, v2
	v_mov_b32_e32 v84, v2
	v_mov_b32_e32 v85, v2
	v_mov_b32_e32 v86, v2
	v_mov_b32_e32 v87, v2
	v_mov_b32_e32 v88, v2
	v_mov_b32_e32 v89, v2
	v_mov_b32_e32 v90, v2
	v_mov_b32_e32 v91, v2
	v_mov_b32_e32 v92, v2
	v_mov_b32_e32 v93, v2
	v_mov_b32_e32 v94, v2
	v_mov_b32_e32 v95, v2
	v_mov_b32_e32 v96, v2
	v_mov_b32_e32 v97, v2
	v_mov_b32_e32 v98, v2
	v_mov_b32_e32 v99, v2
	v_mov_b32_e32 v100, v2
	v_mov_b32_e32 v101, v2
	v_mov_b32_e32 v102, v2
	v_mov_b32_e32 v103, v2
	v_mov_b32_e32 v104, v2
	v_mov_b32_e32 v105, v2
	v_mov_b32_e32 v106, v2
	v_mov_b32_e32 v107, v2
	v_mov_b32_e32 v108, v2
	v_mov_b32_e32 v109, v2
	v_mov_b32_e32 v110, v2
	v_mov_b32_e32 v111, v2
	v_mov_b32_e32 v112, v2
	v_mov_b32_e32 v113, v2
	v_mov_b32_e32 v114, v2
	v_mov_b32_e32 v115, v2
	v_mov_b32_e32 v116, v2
	v_mov_b32_e32 v117, v2
	v_mov_b32_e32 v118, v2
	v_mov_b32_e32 v119, v2
	v_mov_b32_e32 v120, v2
	v_mov_b32_e32 v121, v2
	v_mov_b32_e32 v122, v2
	v_mov_b32_e32 v123, v2
	v_mov_b32_e32 v124, v2
	v_mov_b32_e32 v125, v2
	v_mov_b32_e32 v126, v2
	v_mov_b32_e32 v127, v2
	v_mov_b32_e32 v128, v2
	v_mov_b32_e32 v129, v2
	s_barrier
	s_barrier
.LBB0_941:
	ds_read_b128 v[156:159], v185
	ds_read_b128 v[160:163], v185 offset:1024
	ds_read_b128 v[164:167], v185 offset:2048
	ds_read_b128 v[168:171], v185 offset:3072
	v_lshl_add_u64 v[196:197], v[154:155], 0, s[2:3]
	s_add_i32 s7, s24, 0xc000
	v_lshl_add_u64 v[200:201], v[196:197], 0, s[90:91]
	s_mov_b32 m0, s7
	ds_read_b128 v[172:175], v186
	ds_read_b128 v[176:179], v186 offset:1024
	ds_read_b128 v[180:183], v186 offset:2048
	ds_read_b128 v[188:191], v186 offset:3072
	ds_read_b128 v[192:195], v186 offset:4096
	ds_read_b128 v[214:217], v186 offset:5120
	ds_read_b128 v[218:221], v186 offset:6144
	ds_read_b128 v[222:225], v186 offset:7168
	global_load_lds_dwordx4 v[200:201], off
	v_lshl_add_u64 v[200:201], v[152:153], 0, s[2:3]
	s_add_i32 s6, s24, 0xe000
	v_lshl_add_u64 v[226:227], v[200:201], 0, s[90:91]
	s_mov_b32 m0, s6
	s_nop 0
	global_load_lds_dwordx4 v[226:227], off
	s_waitcnt lgkmcnt(8)
	s_barrier
	s_waitcnt lgkmcnt(0)
	s_setprio 1
	s_waitcnt lgkmcnt(0)
	v_mfma_f32_16x16x32_bf16 v[126:129], v[156:159], v[172:175], v[126:129]
	v_mfma_f32_16x16x32_bf16 v[122:125], v[164:167], v[172:175], v[122:125]
	v_mfma_f32_16x16x32_bf16 v[118:121], v[156:159], v[180:183], v[118:121]
	v_mfma_f32_16x16x32_bf16 v[114:117], v[164:167], v[180:183], v[114:117]
	v_mfma_f32_16x16x32_bf16 v[110:113], v[156:159], v[192:195], v[110:113]
	v_mfma_f32_16x16x32_bf16 v[106:109], v[164:167], v[192:195], v[106:109]
	v_mfma_f32_16x16x32_bf16 v[102:105], v[156:159], v[218:221], v[102:105]
	v_mfma_f32_16x16x32_bf16 v[98:101], v[164:167], v[218:221], v[98:101]
	v_mfma_f32_16x16x32_bf16 v[126:129], v[160:163], v[176:179], v[126:129]
	v_mfma_f32_16x16x32_bf16 v[122:125], v[168:171], v[176:179], v[122:125]
	v_mfma_f32_16x16x32_bf16 v[118:121], v[160:163], v[188:191], v[118:121]
	v_mfma_f32_16x16x32_bf16 v[114:117], v[168:171], v[188:191], v[114:117]
	v_mfma_f32_16x16x32_bf16 v[110:113], v[160:163], v[214:217], v[110:113]
	v_mfma_f32_16x16x32_bf16 v[106:109], v[168:171], v[214:217], v[106:109]
	v_mfma_f32_16x16x32_bf16 v[102:105], v[160:163], v[222:225], v[102:105]
	v_mfma_f32_16x16x32_bf16 v[98:101], v[168:171], v[222:225], v[98:101]
	s_setprio 0
	s_barrier
; #define STAGE(P, BASE, br, kt) do { const char* _gp = (const char*)((BASE) + (long)(br) * K + (long)(kt) * BK); \
;     __builtin_amdgcn_global_load_lds((const unsigned*)(_gp + sob0), (unsigned*)((char*)(P) + wbase), 16, 0, 0); \
;     __builtin_amdgcn_global_load_lds((const unsigned*)(_gp + sob1), (unsigned*)((char*)(P) + wbase + 8192), 16, 0, 0); } while (0)
; #define LDA(dst, b, h) for (int m = 0; m < 4; ++m) for (int k = 0; k < 2; ++k) \
;     dst[m][k] = *reinterpret_cast<const bf16x8*>(aptr + (((b) * 2 + (h)) * HT * 2 + m * 2048 + k * 1024))
; #define LDB(dst, b, h) for (int n = 0; n < 2; ++n) for (int k = 0; k < 2; ++k) \
;     dst[n][k] = *reinterpret_cast<const bf16x8*>(bptr + (((b) * 2 + (h)) * HT * 2 + n * 2048 + k * 1024))
; #define MMA(ai, bj, At, Bt_) do { __builtin_amdgcn_s_setprio(1); \
;     for (int m = 0; m < 4; ++m) for (int n = 0; n < 2; ++n) for (int k = 0; k < 2; ++k) \
;       acc[ai][bj][m][n] = __builtin_amdgcn_mfma_f32_16x16x32_bf16(Bt_[n][k], At[m][k], acc[ai][bj][m][n], 0, 0, 0); \
;     __builtin_amdgcn_s_setprio(0); } while (0)
; #define WAIT_V(n) asm volatile("s_waitcnt vmcnt(" #n ")" ::: "memory")
; #define WAIT_L(n) asm volatile("s_waitcnt lgkmcnt(" #n ")" ::: "memory")
; #define BAR __builtin_amdgcn_s_barrier()
; #define SCHED __builtin_amdgcn_sched_barrier(0)
;     ...
;       LDB(B0, 0, 0); SCHED; LDA(At, 0, 0); STAGE(SA(1, 1), A, brow + HALF, t + 1);
;       WAIT_L(8); BAR; WAIT_L(0); MMA(0, 0, At, B0); BAR; SCHED;
;       LDB(B1, 0, 1); STAGE(SB(0, 0), Bt, bcol, t + 2);
;       BAR; WAIT_L(0); MMA(0, 1, At, B1); BAR;
;       LDA(At, 0, 1); STAGE(SA(0, 0), A, brow, t + 2);
;       BAR; WAIT_L(0); MMA(1, 0, At, B0); BAR; SCHED;
;       STAGE(SB(0, 1), Bt, bcol + HALF, t + 2);
;       WAIT_V(6); BAR; MMA(1, 1, At, B1); BAR;
;       LDB(B0, 1, 0); SCHED; LDA(At, 1, 0); STAGE(SA(0, 1), A, brow + HALF, t + 2);
	v_lshl_add_u64 v[242:243], v[150:151], 0, s[2:3]
	s_mov_b32 m0, s39
	v_lshl_add_u64 v[244:245], v[242:243], 0, s[76:77]
	ds_read_b128 v[226:229], v185 offset:16384
	ds_read_b128 v[230:233], v185 offset:17408
	ds_read_b128 v[234:237], v185 offset:18432
	ds_read_b128 v[238:241], v185 offset:19456
	global_load_lds_dwordx4 v[244:245], off
	v_lshl_add_u64 v[244:245], v[148:149], 0, s[2:3]
	v_lshl_add_u64 v[246:247], v[244:245], 0, s[76:77]
	s_mov_b32 m0, s40
	s_add_i32 s5, s5, 2
	global_load_lds_dwordx4 v[246:247], off
	s_barrier
	s_waitcnt lgkmcnt(0)
	s_setprio 1
	s_waitcnt lgkmcnt(0)
	v_mfma_f32_16x16x32_bf16 v[94:97], v[226:229], v[172:175], v[94:97]
	v_mfma_f32_16x16x32_bf16 v[90:93], v[234:237], v[172:175], v[90:93]
	v_mfma_f32_16x16x32_bf16 v[86:89], v[226:229], v[180:183], v[86:89]
	v_mfma_f32_16x16x32_bf16 v[82:85], v[234:237], v[180:183], v[82:85]
	v_mfma_f32_16x16x32_bf16 v[78:81], v[226:229], v[192:195], v[78:81]
	v_mfma_f32_16x16x32_bf16 v[74:77], v[234:237], v[192:195], v[74:77]
	v_mfma_f32_16x16x32_bf16 v[70:73], v[226:229], v[218:221], v[70:73]
	v_mfma_f32_16x16x32_bf16 v[66:69], v[234:237], v[218:221], v[66:69]
	v_mfma_f32_16x16x32_bf16 v[94:97], v[230:233], v[176:179], v[94:97]
	v_mfma_f32_16x16x32_bf16 v[90:93], v[238:241], v[176:179], v[90:93]
	v_mfma_f32_16x16x32_bf16 v[86:89], v[230:233], v[188:191], v[86:89]
	v_mfma_f32_16x16x32_bf16 v[82:85], v[238:241], v[188:191], v[82:85]
	v_mfma_f32_16x16x32_bf16 v[78:81], v[230:233], v[214:217], v[78:81]
	v_mfma_f32_16x16x32_bf16 v[74:77], v[238:241], v[214:217], v[74:77]
	v_mfma_f32_16x16x32_bf16 v[70:73], v[230:233], v[222:225], v[70:73]
	v_mfma_f32_16x16x32_bf16 v[66:69], v[238:241], v[222:225], v[66:69]
	s_setprio 0
	v_lshl_add_u64 v[246:247], v[146:147], 0, s[2:3]
	s_mov_b32 m0, s24
	v_lshl_add_u64 v[248:249], v[246:247], 0, s[76:77]
	s_barrier
	ds_read_b128 v[172:175], v186 offset:16384
	ds_read_b128 v[176:179], v186 offset:17408
	ds_read_b128 v[180:183], v186 offset:18432
	ds_read_b128 v[188:191], v186 offset:19456
	ds_read_b128 v[192:195], v186 offset:20480
	ds_read_b128 v[214:217], v186 offset:21504
	ds_read_b128 v[218:221], v186 offset:22528
	ds_read_b128 v[222:225], v186 offset:23552
	global_load_lds_dwordx4 v[248:249], off
	v_lshl_add_u64 v[248:249], v[144:145], 0, s[2:3]
	v_lshl_add_u64 v[250:251], v[248:249], 0, s[76:77]
	s_mov_b32 m0, s41
	s_nop 0
	global_load_lds_dwordx4 v[250:251], off
	s_barrier
	s_waitcnt lgkmcnt(0)
	s_setprio 1
	s_waitcnt lgkmcnt(0)
	v_mfma_f32_16x16x32_bf16 v[62:65], v[156:159], v[172:175], v[62:65]
	v_mfma_f32_16x16x32_bf16 v[58:61], v[164:167], v[172:175], v[58:61]
	v_mfma_f32_16x16x32_bf16 v[54:57], v[156:159], v[180:183], v[54:57]
	v_mfma_f32_16x16x32_bf16 v[50:53], v[164:167], v[180:183], v[50:53]
	v_mfma_f32_16x16x32_bf16 v[46:49], v[156:159], v[192:195], v[46:49]
	v_mfma_f32_16x16x32_bf16 v[42:45], v[164:167], v[192:195], v[42:45]
	v_mfma_f32_16x16x32_bf16 v[38:41], v[156:159], v[218:221], v[38:41]
	v_mfma_f32_16x16x32_bf16 v[34:37], v[164:167], v[218:221], v[34:37]
	v_mfma_f32_16x16x32_bf16 v[62:65], v[160:163], v[176:179], v[62:65]
	v_mfma_f32_16x16x32_bf16 v[58:61], v[168:171], v[176:179], v[58:61]
	v_mfma_f32_16x16x32_bf16 v[54:57], v[160:163], v[188:191], v[54:57]
	v_mfma_f32_16x16x32_bf16 v[50:53], v[168:171], v[188:191], v[50:53]
	v_mfma_f32_16x16x32_bf16 v[46:49], v[160:163], v[214:217], v[46:49]
	v_mfma_f32_16x16x32_bf16 v[42:45], v[168:171], v[214:217], v[42:45]
	v_mfma_f32_16x16x32_bf16 v[38:41], v[160:163], v[222:225], v[38:41]
	v_mfma_f32_16x16x32_bf16 v[34:37], v[168:171], v[222:225], v[34:37]
	s_setprio 0
	s_barrier
	v_lshl_add_u64 v[250:251], v[142:143], 0, s[2:3]
	s_mov_b32 m0, s62
	v_lshl_add_u64 v[156:157], v[250:251], 0, s[76:77]
	v_lshl_add_u64 v[252:253], v[140:141], 0, s[2:3]
	global_load_lds_dwordx4 v[156:157], off
	v_lshl_add_u64 v[156:157], v[252:253], 0, s[76:77]
	s_mov_b32 m0, s44
	s_nop 0
	global_load_lds_dwordx4 v[156:157], off
	s_barrier
	s_setprio 1
	v_mfma_f32_16x16x32_bf16 v[30:33], v[226:229], v[172:175], v[30:33]
	v_mfma_f32_16x16x32_bf16 v[26:29], v[234:237], v[172:175], v[26:29]
	v_mfma_f32_16x16x32_bf16 v[22:25], v[226:229], v[180:183], v[22:25]
	v_mfma_f32_16x16x32_bf16 v[18:21], v[234:237], v[180:183], v[18:21]
	v_mfma_f32_16x16x32_bf16 v[14:17], v[226:229], v[192:195], v[14:17]
	v_mfma_f32_16x16x32_bf16 v[10:13], v[234:237], v[192:195], v[10:13]
	v_mfma_f32_16x16x32_bf16 v[6:9], v[226:229], v[218:221], v[6:9]
	v_mfma_f32_16x16x32_bf16 v[2:5], v[234:237], v[218:221], v[2:5]
	v_mfma_f32_16x16x32_bf16 v[30:33], v[230:233], v[176:179], v[30:33]
	v_mfma_f32_16x16x32_bf16 v[26:29], v[238:241], v[176:179], v[26:29]
	v_mfma_f32_16x16x32_bf16 v[22:25], v[230:233], v[188:191], v[22:25]
	v_mfma_f32_16x16x32_bf16 v[18:21], v[238:241], v[188:191], v[18:21]
	v_mfma_f32_16x16x32_bf16 v[14:17], v[230:233], v[214:217], v[14:17]
	v_mfma_f32_16x16x32_bf16 v[10:13], v[238:241], v[214:217], v[10:13]
	v_mfma_f32_16x16x32_bf16 v[6:9], v[230:233], v[222:225], v[6:9]
	v_mfma_f32_16x16x32_bf16 v[2:5], v[238:241], v[222:225], v[2:5]
	s_setprio 0
	s_barrier
	ds_read_b128 v[156:159], v185 offset:32768
	ds_read_b128 v[160:163], v185 offset:33792
	ds_read_b128 v[164:167], v185 offset:34816
	ds_read_b128 v[168:171], v185 offset:35840
	s_mov_b32 m0, s45
	v_lshl_add_u64 v[196:197], v[196:197], 0, s[76:77]
	ds_read_b128 v[172:175], v186 offset:32768
	ds_read_b128 v[176:179], v186 offset:33792
	ds_read_b128 v[180:183], v186 offset:34816
	ds_read_b128 v[188:191], v186 offset:35840
	ds_read_b128 v[192:195], v186 offset:36864
	ds_read_b128 v[214:217], v186 offset:37888
	ds_read_b128 v[218:221], v186 offset:38912
	ds_read_b128 v[222:225], v186 offset:39936
	global_load_lds_dwordx4 v[196:197], off
	v_lshl_add_u64 v[196:197], v[200:201], 0, s[76:77]
	s_mov_b32 m0, s38
	s_nop 0
	global_load_lds_dwordx4 v[196:197], off
	s_waitcnt lgkmcnt(8)
	s_barrier
; #define STAGE(P, BASE, br, kt) do { const char* _gp = (const char*)((BASE) + (long)(br) * K + (long)(kt) * BK); \
;     __builtin_amdgcn_global_load_lds((const unsigned*)(_gp + sob0), (unsigned*)((char*)(P) + wbase), 16, 0, 0); \
;     __builtin_amdgcn_global_load_lds((const unsigned*)(_gp + sob1), (unsigned*)((char*)(P) + wbase + 8192), 16, 0, 0); } while (0)
; #define LDA(dst, b, h) for (int m = 0; m < 4; ++m) for (int k = 0; k < 2; ++k) \
;     dst[m][k] = *reinterpret_cast<const bf16x8*>(aptr + (((b) * 2 + (h)) * HT * 2 + m * 2048 + k * 1024))
; #define LDB(dst, b, h) for (int n = 0; n < 2; ++n) for (int k = 0; k < 2; ++k) \
;     dst[n][k] = *reinterpret_cast<const bf16x8*>(bptr + (((b) * 2 + (h)) * HT * 2 + n * 2048 + k * 1024))
; #define MMA(ai, bj, At, Bt_) do { __builtin_amdgcn_s_setprio(1); \
;     for (int m = 0; m < 4; ++m) for (int n = 0; n < 2; ++n) for (int k = 0; k < 2; ++k) \
;       acc[ai][bj][m][n] = __builtin_amdgcn_mfma_f32_16x16x32_bf16(Bt_[n][k], At[m][k], acc[ai][bj][m][n], 0, 0, 0); \
;     __builtin_amdgcn_s_setprio(0); } while (0)
; #define WAIT_V(n) asm volatile("s_waitcnt vmcnt(" #n ")" ::: "memory")
; #define WAIT_L(n) asm volatile("s_waitcnt lgkmcnt(" #n ")" ::: "memory")
; #define BAR __builtin_amdgcn_s_barrier()
; #define SCHED __builtin_amdgcn_sched_barrier(0)
;     ...
;       LDB(B0, 1, 0); SCHED; LDA(At, 1, 0); STAGE(SA(0, 1), A, brow + HALF, t + 2);
;       WAIT_L(8); BAR; WAIT_L(0); MMA(0, 0, At, B0); BAR; SCHED;
;       LDB(B1, 1, 1); STAGE(SB(1, 0), Bt, bcol, t + 3);
;       BAR; WAIT_L(0); MMA(0, 1, At, B1); BAR;
;       LDA(At, 1, 1); STAGE(SA(1, 0), A, brow, t + 3);
;       BAR; WAIT_L(0); MMA(1, 0, At, B0); BAR; SCHED;
;       STAGE(SB(1, 1), Bt, bcol + HALF, t + 3);
;       WAIT_V(6); BAR; MMA(1, 1, At, B1); BAR;
	s_waitcnt lgkmcnt(0)
	s_setprio 1
	s_waitcnt lgkmcnt(0)
	v_mfma_f32_16x16x32_bf16 v[126:129], v[156:159], v[172:175], v[126:129]
	v_mfma_f32_16x16x32_bf16 v[122:125], v[164:167], v[172:175], v[122:125]
	v_mfma_f32_16x16x32_bf16 v[118:121], v[156:159], v[180:183], v[118:121]
	v_mfma_f32_16x16x32_bf16 v[114:117], v[164:167], v[180:183], v[114:117]
	v_mfma_f32_16x16x32_bf16 v[110:113], v[156:159], v[192:195], v[110:113]
	v_mfma_f32_16x16x32_bf16 v[106:109], v[164:167], v[192:195], v[106:109]
	v_mfma_f32_16x16x32_bf16 v[102:105], v[156:159], v[218:221], v[102:105]
	v_mfma_f32_16x16x32_bf16 v[98:101], v[164:167], v[218:221], v[98:101]
	v_mfma_f32_16x16x32_bf16 v[126:129], v[160:163], v[176:179], v[126:129]
	v_mfma_f32_16x16x32_bf16 v[122:125], v[168:171], v[176:179], v[122:125]
	v_mfma_f32_16x16x32_bf16 v[118:121], v[160:163], v[188:191], v[118:121]
	v_mfma_f32_16x16x32_bf16 v[114:117], v[168:171], v[188:191], v[114:117]
	v_mfma_f32_16x16x32_bf16 v[110:113], v[160:163], v[214:217], v[110:113]
	v_mfma_f32_16x16x32_bf16 v[106:109], v[168:171], v[214:217], v[106:109]
	v_mfma_f32_16x16x32_bf16 v[102:105], v[160:163], v[222:225], v[102:105]
	v_mfma_f32_16x16x32_bf16 v[98:101], v[168:171], v[222:225], v[98:101]
	s_setprio 0
	s_barrier
	s_mov_b32 m0, s28
	v_lshl_add_u64 v[196:197], v[242:243], 0, s[92:93]
	ds_read_b128 v[226:229], v185 offset:49152
	ds_read_b128 v[230:233], v185 offset:50176
	ds_read_b128 v[234:237], v185 offset:51200
	ds_read_b128 v[238:241], v185 offset:52224
	global_load_lds_dwordx4 v[196:197], off
	v_lshl_add_u64 v[196:197], v[244:245], 0, s[92:93]
	s_mov_b32 m0, s29
	s_nop 0
	global_load_lds_dwordx4 v[196:197], off
	s_barrier
	s_waitcnt lgkmcnt(0)
	s_setprio 1
	s_waitcnt lgkmcnt(0)
	v_mfma_f32_16x16x32_bf16 v[94:97], v[226:229], v[172:175], v[94:97]
	v_mfma_f32_16x16x32_bf16 v[90:93], v[234:237], v[172:175], v[90:93]
	v_mfma_f32_16x16x32_bf16 v[86:89], v[226:229], v[180:183], v[86:89]
	v_mfma_f32_16x16x32_bf16 v[82:85], v[234:237], v[180:183], v[82:85]
	v_mfma_f32_16x16x32_bf16 v[78:81], v[226:229], v[192:195], v[78:81]
	v_mfma_f32_16x16x32_bf16 v[74:77], v[234:237], v[192:195], v[74:77]
	v_mfma_f32_16x16x32_bf16 v[70:73], v[226:229], v[218:221], v[70:73]
	v_mfma_f32_16x16x32_bf16 v[66:69], v[234:237], v[218:221], v[66:69]
	v_mfma_f32_16x16x32_bf16 v[94:97], v[230:233], v[176:179], v[94:97]
	v_mfma_f32_16x16x32_bf16 v[90:93], v[238:241], v[176:179], v[90:93]
	v_mfma_f32_16x16x32_bf16 v[86:89], v[230:233], v[188:191], v[86:89]
	v_mfma_f32_16x16x32_bf16 v[82:85], v[238:241], v[188:191], v[82:85]
	v_mfma_f32_16x16x32_bf16 v[78:81], v[230:233], v[214:217], v[78:81]
	v_mfma_f32_16x16x32_bf16 v[74:77], v[238:241], v[214:217], v[74:77]
	v_mfma_f32_16x16x32_bf16 v[70:73], v[230:233], v[222:225], v[70:73]
	v_mfma_f32_16x16x32_bf16 v[66:69], v[238:241], v[222:225], v[66:69]
	s_setprio 0
	s_mov_b32 m0, s36
	v_lshl_add_u64 v[196:197], v[246:247], 0, s[92:93]
	s_waitcnt vmcnt(10)
	s_barrier
	ds_read_b128 v[172:175], v186 offset:49152
	ds_read_b128 v[176:179], v186 offset:50176
	ds_read_b128 v[180:183], v186 offset:51200
	ds_read_b128 v[188:191], v186 offset:52224
	ds_read_b128 v[192:195], v186 offset:53248
	ds_read_b128 v[214:217], v186 offset:54272
	ds_read_b128 v[218:221], v186 offset:55296
	ds_read_b128 v[222:225], v186 offset:56320
	global_load_lds_dwordx4 v[196:197], off
	v_lshl_add_u64 v[196:197], v[248:249], 0, s[92:93]
	s_mov_b32 m0, s37
	s_nop 0
	global_load_lds_dwordx4 v[196:197], off
	s_barrier
	s_waitcnt lgkmcnt(0)
	s_setprio 1
	s_waitcnt lgkmcnt(0)
	v_mfma_f32_16x16x32_bf16 v[62:65], v[156:159], v[172:175], v[62:65]
	v_mfma_f32_16x16x32_bf16 v[58:61], v[164:167], v[172:175], v[58:61]
	v_mfma_f32_16x16x32_bf16 v[54:57], v[156:159], v[180:183], v[54:57]
	v_mfma_f32_16x16x32_bf16 v[50:53], v[164:167], v[180:183], v[50:53]
	v_mfma_f32_16x16x32_bf16 v[46:49], v[156:159], v[192:195], v[46:49]
	v_mfma_f32_16x16x32_bf16 v[42:45], v[164:167], v[192:195], v[42:45]
	v_mfma_f32_16x16x32_bf16 v[38:41], v[156:159], v[218:221], v[38:41]
	v_mfma_f32_16x16x32_bf16 v[34:37], v[164:167], v[218:221], v[34:37]
	v_mfma_f32_16x16x32_bf16 v[62:65], v[160:163], v[176:179], v[62:65]
	v_mfma_f32_16x16x32_bf16 v[58:61], v[168:171], v[176:179], v[58:61]
	v_mfma_f32_16x16x32_bf16 v[54:57], v[160:163], v[188:191], v[54:57]
	v_mfma_f32_16x16x32_bf16 v[50:53], v[168:171], v[188:191], v[50:53]
	v_mfma_f32_16x16x32_bf16 v[46:49], v[160:163], v[214:217], v[46:49]
	v_mfma_f32_16x16x32_bf16 v[42:45], v[168:171], v[214:217], v[42:45]
	v_mfma_f32_16x16x32_bf16 v[38:41], v[160:163], v[222:225], v[38:41]
	v_mfma_f32_16x16x32_bf16 v[34:37], v[168:171], v[222:225], v[34:37]
	s_setprio 0
	s_barrier
	s_mov_b32 m0, s26
	v_lshl_add_u64 v[156:157], v[250:251], 0, s[92:93]
	global_load_lds_dwordx4 v[156:157], off
	v_lshl_add_u64 v[156:157], v[252:253], 0, s[92:93]
	s_mov_b32 m0, s27
	s_nop 0
	global_load_lds_dwordx4 v[156:157], off
	s_waitcnt vmcnt(6)
	s_barrier
	s_setprio 1
	v_mfma_f32_16x16x32_bf16 v[30:33], v[226:229], v[172:175], v[30:33]
	v_mfma_f32_16x16x32_bf16 v[26:29], v[234:237], v[172:175], v[26:29]
	v_mfma_f32_16x16x32_bf16 v[22:25], v[226:229], v[180:183], v[22:25]
	v_mfma_f32_16x16x32_bf16 v[18:21], v[234:237], v[180:183], v[18:21]
	v_mfma_f32_16x16x32_bf16 v[14:17], v[226:229], v[192:195], v[14:17]
	v_mfma_f32_16x16x32_bf16 v[10:13], v[234:237], v[192:195], v[10:13]
	v_mfma_f32_16x16x32_bf16 v[6:9], v[226:229], v[218:221], v[6:9]
	v_mfma_f32_16x16x32_bf16 v[2:5], v[234:237], v[218:221], v[2:5]
	v_mfma_f32_16x16x32_bf16 v[30:33], v[230:233], v[176:179], v[30:33]
	v_mfma_f32_16x16x32_bf16 v[26:29], v[238:241], v[176:179], v[26:29]
	v_mfma_f32_16x16x32_bf16 v[22:25], v[230:233], v[188:191], v[22:25]
	v_mfma_f32_16x16x32_bf16 v[18:21], v[238:241], v[188:191], v[18:21]
	v_mfma_f32_16x16x32_bf16 v[14:17], v[230:233], v[214:217], v[14:17]
	v_mfma_f32_16x16x32_bf16 v[10:13], v[238:241], v[214:217], v[10:13]
	v_mfma_f32_16x16x32_bf16 v[6:9], v[230:233], v[222:225], v[6:9]
	v_mfma_f32_16x16x32_bf16 v[2:5], v[238:241], v[222:225], v[2:5]
	s_setprio 0
	s_add_u32 s2, s2, 0x100
	s_addc_u32 s3, s3, 0
	s_cmp_ge_u32 s5, s68
	s_barrier
; #define STAGE(P, BASE, br, kt) do { const char* _gp = (const char*)((BASE) + (long)(br) * K + (long)(kt) * BK); \
;     __builtin_amdgcn_global_load_lds((const unsigned*)(_gp + sob0), (unsigned*)((char*)(P) + wbase), 16, 0, 0); \
;     __builtin_amdgcn_global_load_lds((const unsigned*)(_gp + sob1), (unsigned*)((char*)(P) + wbase + 8192), 16, 0, 0); } while (0)
; #define LDA(dst, b, h) for (int m = 0; m < 4; ++m) for (int k = 0; k < 2; ++k) \
;     dst[m][k] = *reinterpret_cast<const bf16x8*>(aptr + (((b) * 2 + (h)) * HT * 2 + m * 2048 + k * 1024))
; #define LDB(dst, b, h) for (int n = 0; n < 2; ++n) for (int k = 0; k < 2; ++k) \
;     dst[n][k] = *reinterpret_cast<const bf16x8*>(bptr + (((b) * 2 + (h)) * HT * 2 + n * 2048 + k * 1024))
; #define MMA(ai, bj, At, Bt_) do { __builtin_amdgcn_s_setprio(1); \
;     for (int m = 0; m < 4; ++m) for (int n = 0; n < 2; ++n) for (int k = 0; k < 2; ++k) \
;       acc[ai][bj][m][n] = __builtin_amdgcn_mfma_f32_16x16x32_bf16(Bt_[n][k], At[m][k], acc[ai][bj][m][n], 0, 0, 0); \
;     __builtin_amdgcn_s_setprio(0); } while (0)
; #define WAIT_V(n) asm volatile("s_waitcnt vmcnt(" #n ")" ::: "memory")
; #define WAIT_L(n) asm volatile("s_waitcnt lgkmcnt(" #n ")" ::: "memory")
; #define BAR __builtin_amdgcn_s_barrier()
;     ...
;       WAIT_V(6); BAR; MMA(1, 1, At, B1); BAR;
;     }
;     { LDB(B0, 0, 0); LDA(At, 0, 0); STAGE(SA(1, 1), A, brow + HALF, nt - 1);
;       BAR; WAIT_L(0); MMA(0, 0, At, B0); BAR;
;       LDB(B1, 0, 1); BAR; WAIT_L(0); MMA(0, 1, At, B1); BAR;
;       LDA(At, 0, 1); WAIT_V(4); BAR; WAIT_L(0); MMA(1, 0, At, B0); MMA(1, 1, At, B1); BAR; }
	s_cbranch_scc0 .LBB0_941
	s_mul_hi_i32 s3, s4, s34
	s_mul_i32 s2, s4, s34
	s_lshl_b64 s[2:3], s[2:3], 1
	s_add_u32 s4, s52, s2
	s_addc_u32 s5, s53, s3
	s_add_u32 s4, s4, s42
	s_addc_u32 s5, s5, s43
	s_mov_b32 m0, s7
	v_lshl_add_u64 v[192:193], s[4:5], 0, v[132:133]
	ds_read_b128 v[140:143], v185
	ds_read_b128 v[144:147], v185 offset:1024
	ds_read_b128 v[148:151], v185 offset:2048
	ds_read_b128 v[152:155], v185 offset:3072
	ds_read_b128 v[156:159], v186
	ds_read_b128 v[160:163], v186 offset:1024
	ds_read_b128 v[164:167], v186 offset:2048
	ds_read_b128 v[168:171], v186 offset:3072
	ds_read_b128 v[172:175], v186 offset:4096
	ds_read_b128 v[176:179], v186 offset:5120
	ds_read_b128 v[180:183], v186 offset:6144
	ds_read_b128 v[188:191], v186 offset:7168
	global_load_lds_dwordx4 v[192:193], off
	v_lshl_add_u64 v[192:193], s[4:5], 0, v[134:135]
	s_mov_b32 m0, s6
	s_nop 0
	global_load_lds_dwordx4 v[192:193], off
	s_barrier
	s_waitcnt lgkmcnt(0)
	s_setprio 1
	s_waitcnt lgkmcnt(0)
	v_mfma_f32_16x16x32_bf16 v[126:129], v[140:143], v[156:159], v[126:129]
	v_mfma_f32_16x16x32_bf16 v[122:125], v[148:151], v[156:159], v[122:125]
	v_mfma_f32_16x16x32_bf16 v[118:121], v[140:143], v[164:167], v[118:121]
	v_mfma_f32_16x16x32_bf16 v[114:117], v[148:151], v[164:167], v[114:117]
	v_mfma_f32_16x16x32_bf16 v[110:113], v[140:143], v[172:175], v[110:113]
	v_mfma_f32_16x16x32_bf16 v[106:109], v[148:151], v[172:175], v[106:109]
	v_mfma_f32_16x16x32_bf16 v[102:105], v[140:143], v[180:183], v[102:105]
	v_mfma_f32_16x16x32_bf16 v[98:101], v[148:151], v[180:183], v[98:101]
	v_mfma_f32_16x16x32_bf16 v[126:129], v[144:147], v[160:163], v[126:129]
	v_mfma_f32_16x16x32_bf16 v[122:125], v[152:155], v[160:163], v[122:125]
	v_mfma_f32_16x16x32_bf16 v[118:121], v[144:147], v[168:171], v[118:121]
	v_mfma_f32_16x16x32_bf16 v[114:117], v[152:155], v[168:171], v[114:117]
	v_mfma_f32_16x16x32_bf16 v[110:113], v[144:147], v[176:179], v[110:113]
	v_mfma_f32_16x16x32_bf16 v[106:109], v[152:155], v[176:179], v[106:109]
	v_mfma_f32_16x16x32_bf16 v[102:105], v[144:147], v[188:191], v[102:105]
	v_mfma_f32_16x16x32_bf16 v[98:101], v[152:155], v[188:191], v[98:101]
	s_setprio 0
	s_barrier
	ds_read_b128 v[192:195], v185 offset:16384
	ds_read_b128 v[214:217], v185 offset:17408
	ds_read_b128 v[218:221], v185 offset:18432
	ds_read_b128 v[222:225], v185 offset:19456
	s_barrier
	s_waitcnt lgkmcnt(0)
	s_setprio 1
	s_waitcnt lgkmcnt(0)
	v_mfma_f32_16x16x32_bf16 v[94:97], v[192:195], v[156:159], v[94:97]
	v_mfma_f32_16x16x32_bf16 v[90:93], v[218:221], v[156:159], v[90:93]
	v_mfma_f32_16x16x32_bf16 v[86:89], v[192:195], v[164:167], v[86:89]
	v_mfma_f32_16x16x32_bf16 v[82:85], v[218:221], v[164:167], v[82:85]
	v_mfma_f32_16x16x32_bf16 v[78:81], v[192:195], v[172:175], v[78:81]
	v_mfma_f32_16x16x32_bf16 v[74:77], v[218:221], v[172:175], v[74:77]
	v_mfma_f32_16x16x32_bf16 v[70:73], v[192:195], v[180:183], v[70:73]
	v_mfma_f32_16x16x32_bf16 v[66:69], v[218:221], v[180:183], v[66:69]
	v_mfma_f32_16x16x32_bf16 v[94:97], v[214:217], v[160:163], v[94:97]
	v_mfma_f32_16x16x32_bf16 v[90:93], v[222:225], v[160:163], v[90:93]
	v_mfma_f32_16x16x32_bf16 v[86:89], v[214:217], v[168:171], v[86:89]
	v_mfma_f32_16x16x32_bf16 v[82:85], v[222:225], v[168:171], v[82:85]
	v_mfma_f32_16x16x32_bf16 v[78:81], v[214:217], v[176:179], v[78:81]
	v_mfma_f32_16x16x32_bf16 v[74:77], v[222:225], v[176:179], v[74:77]
	v_mfma_f32_16x16x32_bf16 v[70:73], v[214:217], v[188:191], v[70:73]
	v_mfma_f32_16x16x32_bf16 v[66:69], v[222:225], v[188:191], v[66:69]
	s_setprio 0
	s_barrier
	ds_read_b128 v[156:159], v186 offset:16384
	ds_read_b128 v[160:163], v186 offset:17408
	ds_read_b128 v[164:167], v186 offset:18432
	ds_read_b128 v[168:171], v186 offset:19456
	ds_read_b128 v[172:175], v186 offset:20480
	ds_read_b128 v[176:179], v186 offset:21504
	ds_read_b128 v[180:183], v186 offset:22528
	ds_read_b128 v[188:191], v186 offset:23552
	s_waitcnt vmcnt(4)
	s_barrier
	s_waitcnt lgkmcnt(0)
	s_setprio 1
	s_waitcnt lgkmcnt(0)
	v_mfma_f32_16x16x32_bf16 v[62:65], v[140:143], v[156:159], v[62:65]
	v_mfma_f32_16x16x32_bf16 v[58:61], v[148:151], v[156:159], v[58:61]
	v_mfma_f32_16x16x32_bf16 v[54:57], v[140:143], v[164:167], v[54:57]
	v_mfma_f32_16x16x32_bf16 v[50:53], v[148:151], v[164:167], v[50:53]
	v_mfma_f32_16x16x32_bf16 v[46:49], v[140:143], v[172:175], v[46:49]
	v_mfma_f32_16x16x32_bf16 v[42:45], v[148:151], v[172:175], v[42:45]
	v_mfma_f32_16x16x32_bf16 v[38:41], v[140:143], v[180:183], v[38:41]
	v_mfma_f32_16x16x32_bf16 v[34:37], v[148:151], v[180:183], v[34:37]
	v_mfma_f32_16x16x32_bf16 v[62:65], v[144:147], v[160:163], v[62:65]
	v_mfma_f32_16x16x32_bf16 v[58:61], v[152:155], v[160:163], v[58:61]
	v_mfma_f32_16x16x32_bf16 v[54:57], v[144:147], v[168:171], v[54:57]
	v_mfma_f32_16x16x32_bf16 v[50:53], v[152:155], v[168:171], v[50:53]
	v_mfma_f32_16x16x32_bf16 v[46:49], v[144:147], v[176:179], v[46:49]
	v_mfma_f32_16x16x32_bf16 v[42:45], v[152:155], v[176:179], v[42:45]
	v_mfma_f32_16x16x32_bf16 v[38:41], v[144:147], v[188:191], v[38:41]
	v_mfma_f32_16x16x32_bf16 v[34:37], v[152:155], v[188:191], v[34:37]
	s_setprio 0
	s_setprio 1
	v_mfma_f32_16x16x32_bf16 v[30:33], v[192:195], v[156:159], v[30:33]
	v_mfma_f32_16x16x32_bf16 v[26:29], v[218:221], v[156:159], v[26:29]
	v_mfma_f32_16x16x32_bf16 v[22:25], v[192:195], v[164:167], v[22:25]
	v_mfma_f32_16x16x32_bf16 v[18:21], v[218:221], v[164:167], v[18:21]
	v_mfma_f32_16x16x32_bf16 v[14:17], v[192:195], v[172:175], v[14:17]
	v_mfma_f32_16x16x32_bf16 v[10:13], v[218:221], v[172:175], v[10:13]
	v_mfma_f32_16x16x32_bf16 v[6:9], v[192:195], v[180:183], v[6:9]
	v_mfma_f32_16x16x32_bf16 v[2:5], v[218:221], v[180:183], v[2:5]
	v_mfma_f32_16x16x32_bf16 v[30:33], v[214:217], v[160:163], v[30:33]
	v_mfma_f32_16x16x32_bf16 v[26:29], v[222:225], v[160:163], v[26:29]
	v_mfma_f32_16x16x32_bf16 v[22:25], v[214:217], v[168:171], v[22:25]
	v_mfma_f32_16x16x32_bf16 v[18:21], v[222:225], v[168:171], v[18:21]
	v_mfma_f32_16x16x32_bf16 v[14:17], v[214:217], v[176:179], v[14:17]
	v_mfma_f32_16x16x32_bf16 v[10:13], v[222:225], v[176:179], v[10:13]
	v_mfma_f32_16x16x32_bf16 v[6:9], v[214:217], v[188:191], v[6:9]
	v_mfma_f32_16x16x32_bf16 v[2:5], v[222:225], v[188:191], v[2:5]
	s_setprio 0
	s_barrier
; #define LDA(dst, b, h) for (int m = 0; m < 4; ++m) for (int k = 0; k < 2; ++k) \
;     dst[m][k] = *reinterpret_cast<const bf16x8*>(aptr + (((b) * 2 + (h)) * HT * 2 + m * 2048 + k * 1024))
; #define LDB(dst, b, h) for (int n = 0; n < 2; ++n) for (int k = 0; k < 2; ++k) \
;     dst[n][k] = *reinterpret_cast<const bf16x8*>(bptr + (((b) * 2 + (h)) * HT * 2 + n * 2048 + k * 1024))
; #define MMA(ai, bj, At, Bt_) do { __builtin_amdgcn_s_setprio(1); \
;     for (int m = 0; m < 4; ++m) for (int n = 0; n < 2; ++n) for (int k = 0; k < 2; ++k) \
;       acc[ai][bj][m][n] = __builtin_amdgcn_mfma_f32_16x16x32_bf16(Bt_[n][k], At[m][k], acc[ai][bj][m][n], 0, 0, 0); \
;     __builtin_amdgcn_s_setprio(0); } while (0)
; #define WAIT_V(n) asm volatile("s_waitcnt vmcnt(" #n ")" ::: "memory")
; #define WAIT_L(n) asm volatile("s_waitcnt lgkmcnt(" #n ")" ::: "memory")
; #define BAR __builtin_amdgcn_s_barrier()
;     ...
;     { LDB(B0, 1, 0); LDA(At, 1, 0); WAIT_V(2); BAR; WAIT_L(0); MMA(0, 0, At, B0); BAR;
;       LDB(B1, 1, 1); WAIT_V(0); BAR; WAIT_L(0); MMA(0, 1, At, B1); BAR;
;       LDA(At, 1, 1); BAR; WAIT_L(0); MMA(1, 0, At, B0); MMA(1, 1, At, B1); BAR; }
;     if (wr_s == 0) BAR;
	ds_read_b128 v[140:143], v185 offset:32768
	ds_read_b128 v[144:147], v185 offset:33792
	ds_read_b128 v[148:151], v185 offset:34816
	ds_read_b128 v[152:155], v185 offset:35840
	ds_read_b128 v[156:159], v186 offset:32768
	ds_read_b128 v[160:163], v186 offset:33792
	ds_read_b128 v[164:167], v186 offset:34816
	ds_read_b128 v[168:171], v186 offset:35840
	ds_read_b128 v[172:175], v186 offset:36864
	ds_read_b128 v[176:179], v186 offset:37888
	ds_read_b128 v[180:183], v186 offset:38912
	ds_read_b128 v[188:191], v186 offset:39936
	s_waitcnt vmcnt(2)
	s_barrier
	s_waitcnt lgkmcnt(0)
	s_setprio 1
	s_waitcnt lgkmcnt(0)
	v_mfma_f32_16x16x32_bf16 v[126:129], v[140:143], v[156:159], v[126:129]
	v_mfma_f32_16x16x32_bf16 v[122:125], v[148:151], v[156:159], v[122:125]
	v_mfma_f32_16x16x32_bf16 v[118:121], v[140:143], v[164:167], v[118:121]
	v_mfma_f32_16x16x32_bf16 v[114:117], v[148:151], v[164:167], v[114:117]
	v_mfma_f32_16x16x32_bf16 v[110:113], v[140:143], v[172:175], v[110:113]
	v_mfma_f32_16x16x32_bf16 v[106:109], v[148:151], v[172:175], v[106:109]
	v_mfma_f32_16x16x32_bf16 v[102:105], v[140:143], v[180:183], v[102:105]
	v_mfma_f32_16x16x32_bf16 v[98:101], v[148:151], v[180:183], v[98:101]
	v_mfma_f32_16x16x32_bf16 v[126:129], v[144:147], v[160:163], v[126:129]
	v_mfma_f32_16x16x32_bf16 v[122:125], v[152:155], v[160:163], v[122:125]
	v_mfma_f32_16x16x32_bf16 v[118:121], v[144:147], v[168:171], v[118:121]
	v_mfma_f32_16x16x32_bf16 v[114:117], v[152:155], v[168:171], v[114:117]
	v_mfma_f32_16x16x32_bf16 v[110:113], v[144:147], v[176:179], v[110:113]
	v_mfma_f32_16x16x32_bf16 v[106:109], v[152:155], v[176:179], v[106:109]
	v_mfma_f32_16x16x32_bf16 v[102:105], v[144:147], v[188:191], v[102:105]
	v_mfma_f32_16x16x32_bf16 v[98:101], v[152:155], v[188:191], v[98:101]
	s_setprio 0
	s_barrier
	ds_read_b128 v[192:195], v185 offset:49152
	ds_read_b128 v[214:217], v185 offset:50176
	ds_read_b128 v[218:221], v185 offset:51200
	ds_read_b128 v[222:225], v185 offset:52224
	s_waitcnt vmcnt(0)
	s_barrier
	s_waitcnt lgkmcnt(0)
	s_setprio 1
	s_waitcnt lgkmcnt(0)
	v_mfma_f32_16x16x32_bf16 v[94:97], v[192:195], v[156:159], v[94:97]
	v_mfma_f32_16x16x32_bf16 v[90:93], v[218:221], v[156:159], v[90:93]
	v_mfma_f32_16x16x32_bf16 v[86:89], v[192:195], v[164:167], v[86:89]
	v_mfma_f32_16x16x32_bf16 v[82:85], v[218:221], v[164:167], v[82:85]
	v_mfma_f32_16x16x32_bf16 v[78:81], v[192:195], v[172:175], v[78:81]
	v_mfma_f32_16x16x32_bf16 v[74:77], v[218:221], v[172:175], v[74:77]
	v_mfma_f32_16x16x32_bf16 v[70:73], v[192:195], v[180:183], v[70:73]
	v_mfma_f32_16x16x32_bf16 v[66:69], v[218:221], v[180:183], v[66:69]
	v_mfma_f32_16x16x32_bf16 v[94:97], v[214:217], v[160:163], v[94:97]
	v_mfma_f32_16x16x32_bf16 v[90:93], v[222:225], v[160:163], v[90:93]
	v_mfma_f32_16x16x32_bf16 v[86:89], v[214:217], v[168:171], v[86:89]
	v_mfma_f32_16x16x32_bf16 v[82:85], v[222:225], v[168:171], v[82:85]
	v_mfma_f32_16x16x32_bf16 v[78:81], v[214:217], v[176:179], v[78:81]
	v_mfma_f32_16x16x32_bf16 v[74:77], v[222:225], v[176:179], v[74:77]
	v_mfma_f32_16x16x32_bf16 v[70:73], v[214:217], v[188:191], v[70:73]
	v_mfma_f32_16x16x32_bf16 v[66:69], v[222:225], v[188:191], v[66:69]
	s_setprio 0
	s_barrier
	ds_read_b128 v[156:159], v186 offset:49152
	ds_read_b128 v[160:163], v186 offset:50176
	ds_read_b128 v[164:167], v186 offset:51200
	ds_read_b128 v[168:171], v186 offset:52224
	ds_read_b128 v[172:175], v186 offset:53248
	ds_read_b128 v[176:179], v186 offset:54272
	ds_read_b128 v[180:183], v186 offset:55296
	ds_read_b128 v[188:191], v186 offset:56320
	s_barrier
	s_waitcnt lgkmcnt(0)
	s_setprio 1
	s_waitcnt lgkmcnt(0)
	v_mfma_f32_16x16x32_bf16 v[62:65], v[140:143], v[156:159], v[62:65]
	v_mfma_f32_16x16x32_bf16 v[58:61], v[148:151], v[156:159], v[58:61]
	v_mfma_f32_16x16x32_bf16 v[54:57], v[140:143], v[164:167], v[54:57]
	v_mfma_f32_16x16x32_bf16 v[50:53], v[148:151], v[164:167], v[50:53]
	v_mfma_f32_16x16x32_bf16 v[46:49], v[140:143], v[172:175], v[46:49]
	v_mfma_f32_16x16x32_bf16 v[42:45], v[148:151], v[172:175], v[42:45]
	v_mfma_f32_16x16x32_bf16 v[38:41], v[140:143], v[180:183], v[38:41]
	v_mfma_f32_16x16x32_bf16 v[34:37], v[148:151], v[180:183], v[34:37]
	v_mfma_f32_16x16x32_bf16 v[62:65], v[144:147], v[160:163], v[62:65]
	v_mfma_f32_16x16x32_bf16 v[58:61], v[152:155], v[160:163], v[58:61]
	v_mfma_f32_16x16x32_bf16 v[54:57], v[144:147], v[168:171], v[54:57]
	v_mfma_f32_16x16x32_bf16 v[50:53], v[152:155], v[168:171], v[50:53]
	v_mfma_f32_16x16x32_bf16 v[46:49], v[144:147], v[176:179], v[46:49]
	v_mfma_f32_16x16x32_bf16 v[42:45], v[152:155], v[176:179], v[42:45]
	v_mfma_f32_16x16x32_bf16 v[38:41], v[144:147], v[188:191], v[38:41]
	v_mfma_f32_16x16x32_bf16 v[34:37], v[152:155], v[188:191], v[34:37]
	s_setprio 0
	s_setprio 1
	v_mfma_f32_16x16x32_bf16 v[30:33], v[192:195], v[156:159], v[30:33]
	v_mfma_f32_16x16x32_bf16 v[26:29], v[218:221], v[156:159], v[26:29]
	v_mfma_f32_16x16x32_bf16 v[22:25], v[192:195], v[164:167], v[22:25]
	v_mfma_f32_16x16x32_bf16 v[18:21], v[218:221], v[164:167], v[18:21]
	v_mfma_f32_16x16x32_bf16 v[14:17], v[192:195], v[172:175], v[14:17]
	v_mfma_f32_16x16x32_bf16 v[10:13], v[218:221], v[172:175], v[10:13]
	v_mfma_f32_16x16x32_bf16 v[6:9], v[192:195], v[180:183], v[6:9]
	v_mfma_f32_16x16x32_bf16 v[2:5], v[218:221], v[180:183], v[2:5]
	v_mfma_f32_16x16x32_bf16 v[30:33], v[214:217], v[160:163], v[30:33]
	v_mfma_f32_16x16x32_bf16 v[26:29], v[222:225], v[160:163], v[26:29]
	v_mfma_f32_16x16x32_bf16 v[22:25], v[214:217], v[168:171], v[22:25]
	v_mfma_f32_16x16x32_bf16 v[18:21], v[222:225], v[168:171], v[18:21]
	v_mfma_f32_16x16x32_bf16 v[14:17], v[214:217], v[176:179], v[14:17]
	v_mfma_f32_16x16x32_bf16 v[10:13], v[222:225], v[176:179], v[10:13]
	v_mfma_f32_16x16x32_bf16 v[6:9], v[214:217], v[188:191], v[6:9]
	v_mfma_f32_16x16x32_bf16 v[2:5], v[222:225], v[188:191], v[2:5]
	s_setprio 0
	v_readlane_b32 s4, v255, 27
	v_readlane_b32 s5, v255, 28
	s_and_b64 vcc, exec, s[4:5]
	s_barrier
	s_cbranch_vccz .LBB0_944
	s_barrier

; #define GAS __attribute__((address_space(1)))
; __device__ __forceinline__ uint2 pack4(f32x4 v) { return make_uint2(pack2(v[0], v[1]), pack2(v[2], v[3])); }
; template <int MODE>
; __device__ __forceinline__ void epi_elem(char* ws, float* outp, const float* b_gate, int g0, int rl, int col, f32x4 v) {
;     ...
;   } else if (MODE == E_T || MODE == E_FF) {
;     *(GAS uint2*)((u16*)(ws + (MODE == E_T ? W_T : W_FF)) + (size_t)rl * 1024 + col) = pack4(v);
;     ...
;     int rbase = cur_brow + wr * 64 + fr;
;     int cbase = cur_bcol + wc * 32 + fq * 4;
;     asm volatile("" : "+v"(rbase), "+v"(cbase));
;     char* wsl = p->ws; float* outl = p->out; const float* bgl = p->b_gate;
;     asm volatile("" : "+s"(wsl), "+s"(outl), "+s"(bgl));
;     int em = (mode == E_FFX) ? (int)E_FF : (mode == E_DUAL ? (cur_sub ? (int)E_MG : (int)E_M1) : mode);
;     if (mode == 0) { int seg = cur_bcol >> 10; em = seg >= 5 ? E_G : seg; }
;     switch (em) {
;       case E_U:  epi_store<E_U>(wsl, outl, bgl, g0, acc, rbase, cbase); break;
;       case E_GV: epi_store<E_GV>(wsl, outl, bgl, g0, acc, rbase, cbase); break;
;       case E_Q:  epi_store<E_Q>(wsl, outl, bgl, g0, acc, rbase, cbase); break;
;       case E_K:  epi_store<E_K>(wsl, outl, bgl, g0, acc, rbase, cbase); break;
;       case E_V:  epi_store<E_V>(wsl, outl, bgl, g0, acc, rbase, cbase); break;
;       case E_G:  epi_store<E_G>(wsl, outl, bgl, g0, acc, rbase, cbase); break;
;       case E_M1: epi_store<E_M1>(wsl, outl, bgl, g0, acc, rbase, cbase); break;
;       case E_MG: epi_store<E_MG>(wsl, outl, bgl, g0, acc, rbase, cbase); break;
;       case E_T:  epi_store<E_T>(wsl, outl, bgl, g0, acc, rbase, cbase); break;
;       default:   epi_store<E_FF>(wsl, outl, bgl, g0, acc, rbase, cbase); break;
;     }
.LBB0_960:
	v_readlane_b32 s2, v255, 21
	v_readlane_b32 s3, v255, 22
	s_mov_b64 s[6:7], -1
	s_and_b64 vcc, exec, s[2:3]
	s_cbranch_vccz .LBB0_997
	s_and_b64 s[4:5], s[4:5], exec
	s_cselect_b32 s8, 6, 7
	s_and_b64 s[4:5], s[30:31], exec
	v_readlane_b32 s4, v255, 29
	v_add_u32_e32 v142, s86, v1
	v_add_u32_e32 v140, s70, v184
	s_cselect_b32 s8, s8, s4
	s_ashr_i32 s4, s70, 10
	s_load_dwordx2 s[6:7], s[0:1], 0xb8
	s_load_dwordx2 s[10:11], s[0:1], 0x60
	s_load_dwordx2 s[2:3], s[0:1], 0xc0
	s_min_i32 s9, s4, 5
	v_readlane_b32 s4, v255, 14
	v_readlane_b32 s5, v255, 15
	s_and_b64 s[4:5], s[4:5], exec
	s_cselect_b32 s16, s9, s8
	s_mov_b64 s[12:13], -1
	s_mov_b64 s[8:9], 0
	s_cmp_lt_i32 s16, 4
	s_mov_b64 s[4:5], 0
	s_waitcnt lgkmcnt(0)
	s_cbranch_scc1 .LBB0_980
	s_cmp_gt_i32 s16, 5
	s_cbranch_scc0 .LBB0_974
	s_cmp_gt_i32 s16, 6
	s_cbranch_scc0 .LBB0_971
	s_cmp_gt_i32 s16, 7
	s_cbranch_scc0 .LBB0_968
	s_cmp_eq_u32 s16, 8
	s_mov_b64 s[4:5], -1
	s_cbranch_scc0 .LBB0_967
	v_bfe_u32 v141, v184, 2, 2
	v_and_b32_e32 v143, 1, v141
	v_lshrrev_b32_e32 v187, 1, v141
	v_lshlrev_b32_e32 v143, 4, v143
	v_lshl_add_u32 v143, v187, 3, v143
	v_lshlrev_b32_e32 v141, 2, v141
	v_sub_u32_e32 v143, v143, v141
	v_add_u32_e32 v143, v140, v143
	v_lshlrev_b32_e32 v141, 11, v142
	v_lshl_add_u32 v250, v143, 1, v141
	v_add_u32_e32 v251, 0x8000, v250
	v_add_u32_e32 v252, 0x10000, v250
	v_add_u32_e32 v253, 0x18000, v250
	s_add_u32 s4, s2, 0x2aec0000
	s_addc_u32 s5, s3, 0
	s_add_u32 s6, s2, 0x2af00000
	s_addc_u32 s7, s3, 0
	v_cvt_pk_bf16_f32 v144, v126, v127
	v_cvt_pk_bf16_f32 v145, v128, v129
	v_cvt_pk_bf16_f32 v146, v122, v123
	v_cvt_pk_bf16_f32 v147, v124, v125
	v_cvt_pk_bf16_f32 v148, v118, v119
	v_cvt_pk_bf16_f32 v149, v120, v121
	v_cvt_pk_bf16_f32 v150, v114, v115
	v_cvt_pk_bf16_f32 v151, v116, v117
	v_permlane16_swap_b32_e32 v144, v146
	v_permlane16_swap_b32_e32 v145, v147
	global_store_dwordx4 v250, v[144:147], s[4:5]
	v_cvt_pk_bf16_f32 v152, v110, v111
	v_cvt_pk_bf16_f32 v153, v112, v113
	v_cvt_pk_bf16_f32 v154, v106, v107
	v_cvt_pk_bf16_f32 v155, v108, v109
	v_permlane16_swap_b32_e32 v148, v150
	v_permlane16_swap_b32_e32 v149, v151
	global_store_dwordx4 v251, v[148:151], s[4:5]
	v_cvt_pk_bf16_f32 v156, v102, v103
	v_cvt_pk_bf16_f32 v157, v104, v105
	v_cvt_pk_bf16_f32 v158, v98, v99
	v_cvt_pk_bf16_f32 v159, v100, v101
	v_permlane16_swap_b32_e32 v152, v154
	v_permlane16_swap_b32_e32 v153, v155
	global_store_dwordx4 v252, v[152:155], s[4:5]
	v_cvt_pk_bf16_f32 v144, v94, v95
	v_cvt_pk_bf16_f32 v145, v96, v97
	v_cvt_pk_bf16_f32 v146, v90, v91
	v_cvt_pk_bf16_f32 v147, v92, v93
	v_permlane16_swap_b32_e32 v156, v158
	v_permlane16_swap_b32_e32 v157, v159
	global_store_dwordx4 v253, v[156:159], s[4:5]
	v_cvt_pk_bf16_f32 v148, v86, v87
	v_cvt_pk_bf16_f32 v149, v88, v89
	v_cvt_pk_bf16_f32 v150, v82, v83
	v_cvt_pk_bf16_f32 v151, v84, v85
	v_permlane16_swap_b32_e32 v144, v146
	v_permlane16_swap_b32_e32 v145, v147
	global_store_dwordx4 v250, v[144:147], s[4:5] offset:256
	v_cvt_pk_bf16_f32 v152, v78, v79
	v_cvt_pk_bf16_f32 v153, v80, v81
	v_cvt_pk_bf16_f32 v154, v74, v75
	v_cvt_pk_bf16_f32 v155, v76, v77
	v_permlane16_swap_b32_e32 v148, v150
	v_permlane16_swap_b32_e32 v149, v151
	global_store_dwordx4 v251, v[148:151], s[4:5] offset:256
	v_cvt_pk_bf16_f32 v156, v70, v71
	v_cvt_pk_bf16_f32 v157, v72, v73
	v_cvt_pk_bf16_f32 v158, v66, v67
	v_cvt_pk_bf16_f32 v159, v68, v69
	v_permlane16_swap_b32_e32 v152, v154
	v_permlane16_swap_b32_e32 v153, v155
	global_store_dwordx4 v252, v[152:155], s[4:5] offset:256
	v_cvt_pk_bf16_f32 v144, v62, v63
	v_cvt_pk_bf16_f32 v145, v64, v65
	v_cvt_pk_bf16_f32 v146, v58, v59
	v_cvt_pk_bf16_f32 v147, v60, v61
	v_permlane16_swap_b32_e32 v156, v158
	v_permlane16_swap_b32_e32 v157, v159
	global_store_dwordx4 v253, v[156:159], s[4:5] offset:256
	v_cvt_pk_bf16_f32 v148, v54, v55
	v_cvt_pk_bf16_f32 v149, v56, v57
	v_cvt_pk_bf16_f32 v150, v50, v51
	v_cvt_pk_bf16_f32 v151, v52, v53
	v_permlane16_swap_b32_e32 v144, v146
	v_permlane16_swap_b32_e32 v145, v147
	global_store_dwordx4 v250, v[144:147], s[6:7]
	v_cvt_pk_bf16_f32 v152, v46, v47
	v_cvt_pk_bf16_f32 v153, v48, v49
	v_cvt_pk_bf16_f32 v154, v42, v43
	v_cvt_pk_bf16_f32 v155, v44, v45
	v_permlane16_swap_b32_e32 v148, v150
	v_permlane16_swap_b32_e32 v149, v151
	global_store_dwordx4 v251, v[148:151], s[6:7]
	v_cvt_pk_bf16_f32 v156, v38, v39
	v_cvt_pk_bf16_f32 v157, v40, v41
	v_cvt_pk_bf16_f32 v158, v34, v35
	v_cvt_pk_bf16_f32 v159, v36, v37
	v_permlane16_swap_b32_e32 v152, v154
	v_permlane16_swap_b32_e32 v153, v155
	global_store_dwordx4 v252, v[152:155], s[6:7]
	v_cvt_pk_bf16_f32 v144, v30, v31
	v_cvt_pk_bf16_f32 v145, v32, v33
	v_cvt_pk_bf16_f32 v146, v26, v27
	v_cvt_pk_bf16_f32 v147, v28, v29
	v_permlane16_swap_b32_e32 v156, v158
	v_permlane16_swap_b32_e32 v157, v159
	global_store_dwordx4 v253, v[156:159], s[6:7]
	v_cvt_pk_bf16_f32 v148, v22, v23
	v_cvt_pk_bf16_f32 v149, v24, v25
	v_cvt_pk_bf16_f32 v150, v18, v19
	v_cvt_pk_bf16_f32 v151, v20, v21
	v_permlane16_swap_b32_e32 v144, v146
	v_permlane16_swap_b32_e32 v145, v147
	global_store_dwordx4 v250, v[144:147], s[6:7] offset:256
	v_cvt_pk_bf16_f32 v152, v14, v15
	v_cvt_pk_bf16_f32 v153, v16, v17
	v_cvt_pk_bf16_f32 v154, v10, v11
	v_cvt_pk_bf16_f32 v155, v12, v13
	v_permlane16_swap_b32_e32 v148, v150
	v_permlane16_swap_b32_e32 v149, v151
	global_store_dwordx4 v251, v[148:151], s[6:7] offset:256
	v_cvt_pk_bf16_f32 v156, v6, v7
	v_cvt_pk_bf16_f32 v157, v8, v9
	v_cvt_pk_bf16_f32 v158, v2, v3
	v_cvt_pk_bf16_f32 v159, v4, v5
	v_permlane16_swap_b32_e32 v152, v154
	v_permlane16_swap_b32_e32 v153, v155
	global_store_dwordx4 v252, v[152:155], s[6:7] offset:256
	s_nop 1
	v_permlane16_swap_b32_e32 v156, v158
	v_permlane16_swap_b32_e32 v157, v159
	global_store_dwordx4 v253, v[156:159], s[6:7] offset:256
	s_waitcnt vmcnt(16)
	s_branch .LBB0_996

; #define GAS __attribute__((address_space(1)))
; __device__ __forceinline__ u16 f2bf(float f) { return (u16)(pack2(f, 0.f) & 0xffffu); }
; template <int MODE>
; __device__ __forceinline__ void epi_elem(char* ws, float* outp, const float* b_gate, int g0, int rl, int col, f32x4 v) {
;     ...
;   } else if (MODE == E_V) {
;     int lc = col & 1023;
;     u16* vt = (u16*)(ws + W_VT);
; #pragma unroll
;     for (int i = 0; i < 4; ++i) vt[(size_t)(lc + i) * MAXR + rl] = f2bf(v[i]);
;     int rg = g0 + rl;
;     float* o = rg < NPROMPT ? outp + O_VP + (size_t)rg * 1024 : outp + O_VS + (size_t)(rg - NPROMPT) * 1024;
;     __builtin_nontemporal_store(v, (GAS f32x4*)(o + lc));
.LBB0_977:
	s_andn2_b64 vcc, exec, s[12:13]
	s_cbranch_vccnz .LBB0_979
	v_ashrrev_i32_e32 v143, 31, v142
	v_lshl_add_u64 v[144:145], v[142:143], 1, s[2:3]
	s_mov_b64 s[10:11], 0x169c0000
	v_lshl_add_u64 v[174:175], v[144:145], 0, s[10:11]
	v_readlane_b32 s10, v255, 18
	v_mov_b32_e32 v147, v0
	v_cvt_pk_bf16_f32 v148, v127, s0
	v_add_u32_e32 v141, s10, v142
	s_mov_b32 s10, 0x10000
	v_add_u32_e32 v143, 0xffff0000, v141
	v_ashrrev_i32_e32 v144, 31, v141
	v_cmp_gt_i32_e32 vcc, s10, v141
	s_mov_b32 s11, 0x20000
	v_cvt_pk_bf16_f32 v150, v128, s0
	v_cndmask_b32_e32 v145, 0, v144, vcc
	v_cndmask_b32_e32 v144, v143, v141, vcc
	v_cndmask_b32_e32 v146, v205, v206, vcc
	v_lshl_add_u64 v[146:147], s[6:7], 0, v[146:147]
	v_lshlrev_b64 v[144:145], 12, v[144:145]
	v_and_b32_e32 v143, 0x3ff, v140
	v_lshl_add_u64 v[188:189], v[146:147], 0, v[144:145]
	v_mul_u32_u24_e32 v144, 0x8200, v143
	v_lshlrev_b32_e32 v144, 1, v144
	v_mov_b32_e32 v145, v0
	v_cvt_pk_bf16_f32 v146, v126, s0
	v_lshl_add_u64 v[144:145], v[174:175], 0, v[144:145]
	global_store_short v[144:145], v146, off
	v_add_co_u32_e32 v146, vcc, s10, v144
	s_mov_b32 s12, 0x30000
	s_nop 0
	v_addc_co_u32_e32 v147, vcc, 0, v145, vcc
	global_store_short v[146:147], v148, off offset:1024
	v_add_co_u32_e32 v148, vcc, s11, v144
	v_cvt_pk_bf16_f32 v152, v129, s0
	s_nop 0
	v_addc_co_u32_e32 v149, vcc, 0, v145, vcc
	global_store_short v[148:149], v150, off offset:2048
	v_add_co_u32_e32 v150, vcc, s12, v144
	v_mov_b32_e32 v153, v0
	s_nop 0
	v_addc_co_u32_e32 v151, vcc, 0, v145, vcc
	global_store_short v[150:151], v152, off offset:3072
	v_lshlrev_b32_e32 v152, 2, v143
	v_add_u32_e32 v143, 16, v140
	v_lshl_add_u64 v[154:155], v[188:189], 0, v[152:153]
	v_and_b32_e32 v143, 0x3ff, v143
	global_store_dwordx4 v[154:155], v[126:129], off nt
	v_mul_u32_u24_e32 v154, 0x8200, v143
	v_lshlrev_b32_e32 v154, 1, v154
	v_mov_b32_e32 v155, v0
	v_cvt_pk_bf16_f32 v156, v122, s0
	v_lshl_add_u64 v[154:155], v[174:175], 0, v[154:155]
	global_store_short v[154:155], v156, off
	v_add_co_u32_e32 v156, vcc, s10, v154
	v_cvt_pk_bf16_f32 v158, v123, s0
	s_nop 0
	v_addc_co_u32_e32 v157, vcc, 0, v155, vcc
	global_store_short v[156:157], v158, off offset:1024
	v_add_co_u32_e32 v158, vcc, s11, v154
	v_cvt_pk_bf16_f32 v160, v124, s0
	s_nop 0
	v_addc_co_u32_e32 v159, vcc, 0, v155, vcc
	global_store_short v[158:159], v160, off offset:2048
	v_add_co_u32_e32 v160, vcc, s12, v154
	v_cvt_pk_bf16_f32 v162, v125, s0
	s_nop 0
	v_addc_co_u32_e32 v161, vcc, 0, v155, vcc
	global_store_short v[160:161], v162, off offset:3072
	v_lshlrev_b32_e32 v162, 2, v143
	v_mov_b32_e32 v163, v0
	v_lshl_add_u64 v[164:165], v[188:189], 0, v[162:163]
	v_add_u32_e32 v143, 16, v141
	global_store_dwordx4 v[164:165], v[122:125], off nt
	v_add_u32_e32 v164, 0xffff0010, v141
	v_cmp_gt_i32_e32 vcc, s10, v143
	v_ashrrev_i32_e32 v165, 31, v143
	v_mov_b32_e32 v167, v0
	v_cndmask_b32_e32 v164, v164, v143, vcc
	v_cvt_pk_bf16_f32 v143, v118, s0
	v_cndmask_b32_e32 v165, 0, v165, vcc
	v_cndmask_b32_e32 v166, v205, v206, vcc
	global_store_short v[144:145], v143, off offset:32
	v_cvt_pk_bf16_f32 v143, v119, s0
	v_lshl_add_u64 v[166:167], s[6:7], 0, v[166:167]
	v_lshlrev_b64 v[164:165], 12, v[164:165]
	global_store_short v[146:147], v143, off offset:1056
	v_cvt_pk_bf16_f32 v143, v120, s0
	v_lshl_add_u64 v[190:191], v[166:167], 0, v[164:165]
	global_store_short v[148:149], v143, off offset:2080
	v_cvt_pk_bf16_f32 v143, v121, s0
	global_store_short v[150:151], v143, off offset:3104
	v_lshl_add_u64 v[164:165], v[190:191], 0, v[152:153]
	v_cvt_pk_bf16_f32 v143, v114, s0
	global_store_dwordx4 v[164:165], v[118:121], off nt
	global_store_short v[154:155], v143, off offset:32
	v_cvt_pk_bf16_f32 v143, v115, s0
	global_store_short v[156:157], v143, off offset:1056
	v_cvt_pk_bf16_f32 v143, v116, s0
	global_store_short v[158:159], v143, off offset:2080
	v_cvt_pk_bf16_f32 v143, v117, s0
	v_lshl_add_u64 v[164:165], v[190:191], 0, v[162:163]
	global_store_short v[160:161], v143, off offset:3104
	global_store_dwordx4 v[164:165], v[114:117], off nt
	v_add_u32_e32 v143, 32, v141
	v_add_u32_e32 v164, 0xffff0020, v141
	v_cmp_gt_i32_e32 vcc, s10, v143
	v_ashrrev_i32_e32 v165, 31, v143
	v_mov_b32_e32 v167, v0
	v_cndmask_b32_e32 v164, v164, v143, vcc
	v_cvt_pk_bf16_f32 v143, v110, s0
	v_cndmask_b32_e32 v165, 0, v165, vcc
	v_cndmask_b32_e32 v166, v205, v206, vcc
	global_store_short v[144:145], v143, off offset:64
	v_cvt_pk_bf16_f32 v143, v111, s0
	v_lshl_add_u64 v[166:167], s[6:7], 0, v[166:167]
	v_lshlrev_b64 v[164:165], 12, v[164:165]
	global_store_short v[146:147], v143, off offset:1088
	v_cvt_pk_bf16_f32 v143, v112, s0
	v_lshl_add_u64 v[192:193], v[166:167], 0, v[164:165]
	global_store_short v[148:149], v143, off offset:2112
	v_cvt_pk_bf16_f32 v143, v113, s0
	global_store_short v[150:151], v143, off offset:3136
	v_lshl_add_u64 v[164:165], v[192:193], 0, v[152:153]
	v_cvt_pk_bf16_f32 v143, v106, s0
	global_store_dwordx4 v[164:165], v[110:113], off nt
	global_store_short v[154:155], v143, off offset:64
	v_cvt_pk_bf16_f32 v143, v107, s0
	global_store_short v[156:157], v143, off offset:1088
	v_cvt_pk_bf16_f32 v143, v108, s0
	global_store_short v[158:159], v143, off offset:2112
	v_cvt_pk_bf16_f32 v143, v109, s0
	global_store_short v[160:161], v143, off offset:3136
	v_lshl_add_u64 v[164:165], v[192:193], 0, v[162:163]
	v_add_u32_e32 v143, 48, v141
	global_store_dwordx4 v[164:165], v[106:109], off nt
	v_add_u32_e32 v164, 0xffff0030, v141
	v_cmp_gt_i32_e32 vcc, s10, v143
	v_ashrrev_i32_e32 v165, 31, v143
	v_mov_b32_e32 v167, v0
	v_cndmask_b32_e32 v164, v164, v143, vcc
	v_cvt_pk_bf16_f32 v143, v102, s0
; #define GAS __attribute__((address_space(1)))
; __device__ __forceinline__ u16 f2bf(float f) { return (u16)(pack2(f, 0.f) & 0xffffu); }
; template <int MODE>
; __device__ __forceinline__ void epi_elem(char* ws, float* outp, const float* b_gate, int g0, int rl, int col, f32x4 v) {
;     ...
;   } else if (MODE == E_V) {
;     int lc = col & 1023;
;     u16* vt = (u16*)(ws + W_VT);
; #pragma unroll
;     for (int i = 0; i < 4; ++i) vt[(size_t)(lc + i) * MAXR + rl] = f2bf(v[i]);
;     int rg = g0 + rl;
;     float* o = rg < NPROMPT ? outp + O_VP + (size_t)rg * 1024 : outp + O_VS + (size_t)(rg - NPROMPT) * 1024;
;     __builtin_nontemporal_store(v, (GAS f32x4*)(o + lc));
	v_cndmask_b32_e32 v165, 0, v165, vcc
	v_cndmask_b32_e32 v166, v205, v206, vcc
	global_store_short v[144:145], v143, off offset:96
	v_cvt_pk_bf16_f32 v143, v103, s0
	v_lshl_add_u64 v[166:167], s[6:7], 0, v[166:167]
	v_lshlrev_b64 v[164:165], 12, v[164:165]
	global_store_short v[146:147], v143, off offset:1120
	v_cvt_pk_bf16_f32 v143, v104, s0
	v_lshl_add_u64 v[194:195], v[166:167], 0, v[164:165]
	global_store_short v[148:149], v143, off offset:2144
	v_cvt_pk_bf16_f32 v143, v105, s0
	global_store_short v[150:151], v143, off offset:3168
	v_lshl_add_u64 v[164:165], v[194:195], 0, v[152:153]
	v_cvt_pk_bf16_f32 v143, v98, s0
	global_store_dwordx4 v[164:165], v[102:105], off nt
	global_store_short v[154:155], v143, off offset:96
	v_cvt_pk_bf16_f32 v143, v99, s0
	global_store_short v[156:157], v143, off offset:1120
	v_cvt_pk_bf16_f32 v143, v100, s0
	global_store_short v[158:159], v143, off offset:2144
	v_cvt_pk_bf16_f32 v143, v101, s0
	v_lshl_add_u64 v[164:165], v[194:195], 0, v[162:163]
	global_store_short v[160:161], v143, off offset:3168
	global_store_dwordx4 v[164:165], v[98:101], off nt
	v_add_u32_e32 v143, 0x80, v140
	v_and_b32_e32 v143, 0x3ff, v143
	v_mul_u32_u24_e32 v164, 0x8200, v143
	v_lshlrev_b32_e32 v164, 1, v164
	v_mov_b32_e32 v165, v0
	v_cvt_pk_bf16_f32 v166, v94, s0
	v_lshl_add_u64 v[164:165], v[174:175], 0, v[164:165]
	global_store_short v[164:165], v166, off
	v_add_co_u32_e32 v166, vcc, s10, v164
	v_cvt_pk_bf16_f32 v168, v95, s0
	s_nop 0
	v_addc_co_u32_e32 v167, vcc, 0, v165, vcc
	global_store_short v[166:167], v168, off offset:1024
	v_add_co_u32_e32 v168, vcc, s11, v164
	v_cvt_pk_bf16_f32 v170, v96, s0
	s_nop 0
	v_addc_co_u32_e32 v169, vcc, 0, v165, vcc
	global_store_short v[168:169], v170, off offset:2048
	v_add_co_u32_e32 v170, vcc, s12, v164
	v_cvt_pk_bf16_f32 v172, v97, s0
	s_nop 0
	v_addc_co_u32_e32 v171, vcc, 0, v165, vcc
	global_store_short v[170:171], v172, off offset:3072
	v_lshlrev_b32_e32 v172, 2, v143
	v_mov_b32_e32 v173, v0
	v_add_u32_e32 v143, 0x90, v140
	v_lshl_add_u64 v[176:177], v[188:189], 0, v[172:173]
	v_and_b32_e32 v143, 0x3ff, v143
	global_store_dwordx4 v[176:177], v[94:97], off nt
	v_mul_u32_u24_e32 v176, 0x8200, v143
	v_lshlrev_b32_e32 v176, 1, v176
	v_mov_b32_e32 v177, v0
	v_lshl_add_u64 v[174:175], v[174:175], 0, v[176:177]
	v_cvt_pk_bf16_f32 v178, v90, s0
	v_add_co_u32_e32 v176, vcc, s10, v174
	global_store_short v[174:175], v178, off
	v_cvt_pk_bf16_f32 v178, v91, s0
	v_addc_co_u32_e32 v177, vcc, 0, v175, vcc
	global_store_short v[176:177], v178, off offset:1024
	v_add_co_u32_e32 v178, vcc, s11, v174
	v_cvt_pk_bf16_f32 v180, v92, s0
	s_nop 0
	v_addc_co_u32_e32 v179, vcc, 0, v175, vcc
	global_store_short v[178:179], v180, off offset:2048
	v_add_co_u32_e32 v180, vcc, s12, v174
	v_cvt_pk_bf16_f32 v182, v93, s0
	s_nop 0
	v_addc_co_u32_e32 v181, vcc, 0, v175, vcc
	global_store_short v[180:181], v182, off offset:3072
	v_lshlrev_b32_e32 v182, 2, v143
	v_mov_b32_e32 v183, v0
	v_lshl_add_u64 v[188:189], v[188:189], 0, v[182:183]
	v_cvt_pk_bf16_f32 v143, v86, s0
	global_store_dwordx4 v[188:189], v[90:93], off nt
	global_store_short v[164:165], v143, off offset:32
	v_cvt_pk_bf16_f32 v143, v87, s0
	global_store_short v[166:167], v143, off offset:1056
	v_cvt_pk_bf16_f32 v143, v88, s0
	global_store_short v[168:169], v143, off offset:2080
	v_cvt_pk_bf16_f32 v143, v89, s0
	global_store_short v[170:171], v143, off offset:3104
	v_lshl_add_u64 v[188:189], v[190:191], 0, v[172:173]
	v_cvt_pk_bf16_f32 v143, v82, s0
	global_store_dwordx4 v[188:189], v[86:89], off nt
	global_store_short v[174:175], v143, off offset:32
	v_cvt_pk_bf16_f32 v143, v83, s0
	global_store_short v[176:177], v143, off offset:1056
	v_cvt_pk_bf16_f32 v143, v84, s0
	global_store_short v[178:179], v143, off offset:2080
	v_cvt_pk_bf16_f32 v143, v85, s0
	v_lshl_add_u64 v[188:189], v[190:191], 0, v[182:183]
	global_store_short v[180:181], v143, off offset:3104
	global_store_dwordx4 v[188:189], v[82:85], off nt
	v_cvt_pk_bf16_f32 v143, v78, s0
	global_store_short v[164:165], v143, off offset:64
	v_cvt_pk_bf16_f32 v143, v79, s0
	global_store_short v[166:167], v143, off offset:1088
	v_cvt_pk_bf16_f32 v143, v80, s0
	global_store_short v[168:169], v143, off offset:2112
	v_cvt_pk_bf16_f32 v143, v81, s0
	global_store_short v[170:171], v143, off offset:3136
	v_lshl_add_u64 v[188:189], v[192:193], 0, v[172:173]
	v_cvt_pk_bf16_f32 v143, v74, s0
	global_store_dwordx4 v[188:189], v[78:81], off nt
	global_store_short v[174:175], v143, off offset:64
	v_cvt_pk_bf16_f32 v143, v75, s0
	global_store_short v[176:177], v143, off offset:1088
	v_cvt_pk_bf16_f32 v143, v76, s0
	global_store_short v[178:179], v143, off offset:2112
	v_cvt_pk_bf16_f32 v143, v77, s0
	global_store_short v[180:181], v143, off offset:3136
	v_lshl_add_u64 v[188:189], v[192:193], 0, v[182:183]
	v_cvt_pk_bf16_f32 v143, v70, s0
	global_store_dwordx4 v[188:189], v[74:77], off nt
	global_store_short v[164:165], v143, off offset:96
	v_cvt_pk_bf16_f32 v143, v71, s0
	global_store_short v[166:167], v143, off offset:1120
	v_cvt_pk_bf16_f32 v143, v72, s0
	global_store_short v[168:169], v143, off offset:2144
	v_cvt_pk_bf16_f32 v143, v73, s0
	global_store_short v[170:171], v143, off offset:3168
	v_lshl_add_u64 v[188:189], v[194:195], 0, v[172:173]
	v_cvt_pk_bf16_f32 v143, v66, s0
	global_store_dwordx4 v[188:189], v[70:73], off nt
	global_store_short v[174:175], v143, off offset:96
	v_cvt_pk_bf16_f32 v143, v67, s0
	global_store_short v[176:177], v143, off offset:1120
	v_cvt_pk_bf16_f32 v143, v68, s0
	global_store_short v[178:179], v143, off offset:2144
	v_cvt_pk_bf16_f32 v143, v69, s0
	v_lshl_add_u64 v[188:189], v[194:195], 0, v[182:183]
; #define GAS __attribute__((address_space(1)))
; __device__ __forceinline__ u16 f2bf(float f) { return (u16)(pack2(f, 0.f) & 0xffffu); }
; template <int MODE>
; __device__ __forceinline__ void epi_elem(char* ws, float* outp, const float* b_gate, int g0, int rl, int col, f32x4 v) {
;     ...
;   } else if (MODE == E_V) {
;     int lc = col & 1023;
;     u16* vt = (u16*)(ws + W_VT);
; #pragma unroll
;     for (int i = 0; i < 4; ++i) vt[(size_t)(lc + i) * MAXR + rl] = f2bf(v[i]);
;     int rg = g0 + rl;
;     float* o = rg < NPROMPT ? outp + O_VP + (size_t)rg * 1024 : outp + O_VS + (size_t)(rg - NPROMPT) * 1024;
;     __builtin_nontemporal_store(v, (GAS f32x4*)(o + lc));
	global_store_short v[180:181], v143, off offset:3168
	global_store_dwordx4 v[188:189], v[66:69], off nt
	v_add_u32_e32 v143, 0x80, v141
	v_add_u32_e32 v187, 0xffff0080, v141
	v_ashrrev_i32_e32 v188, 31, v143
	v_cmp_gt_i32_e32 vcc, s10, v143
	v_mov_b32_e32 v191, v0
	v_mov_b32_e32 v193, v0
	v_cndmask_b32_e32 v189, 0, v188, vcc
	v_cndmask_b32_e32 v188, v187, v143, vcc
	v_cvt_pk_bf16_f32 v143, v62, s0
	v_cndmask_b32_e32 v190, v205, v206, vcc
	global_store_short v[144:145], v143, off offset:256
	v_cvt_pk_bf16_f32 v143, v63, s0
	v_lshl_add_u64 v[190:191], s[6:7], 0, v[190:191]
	v_lshlrev_b64 v[188:189], 12, v[188:189]
	global_store_short v[146:147], v143, off offset:1280
	v_cvt_pk_bf16_f32 v143, v64, s0
	v_lshl_add_u64 v[188:189], v[190:191], 0, v[188:189]
	global_store_short v[148:149], v143, off offset:2304
	v_cvt_pk_bf16_f32 v143, v65, s0
	global_store_short v[150:151], v143, off offset:3328
	v_lshl_add_u64 v[190:191], v[188:189], 0, v[152:153]
	v_cvt_pk_bf16_f32 v143, v58, s0
	global_store_dwordx4 v[190:191], v[62:65], off nt
	global_store_short v[154:155], v143, off offset:256
	v_cvt_pk_bf16_f32 v143, v59, s0
	global_store_short v[156:157], v143, off offset:1280
	v_cvt_pk_bf16_f32 v143, v60, s0
	global_store_short v[158:159], v143, off offset:2304
	v_cvt_pk_bf16_f32 v143, v61, s0
	global_store_short v[160:161], v143, off offset:3328
	v_lshl_add_u64 v[190:191], v[188:189], 0, v[162:163]
	v_add_u32_e32 v143, 0x90, v141
	global_store_dwordx4 v[190:191], v[58:61], off nt
	v_add_u32_e32 v187, 0xffff0090, v141
	v_ashrrev_i32_e32 v190, 31, v143
	v_cmp_gt_i32_e32 vcc, s10, v143
	s_nop 1
	v_cndmask_b32_e32 v191, 0, v190, vcc
	v_cndmask_b32_e32 v190, v187, v143, vcc
	v_cvt_pk_bf16_f32 v143, v54, s0
	v_cndmask_b32_e32 v192, v205, v206, vcc
	global_store_short v[144:145], v143, off offset:288
	v_cvt_pk_bf16_f32 v143, v55, s0
	v_lshl_add_u64 v[192:193], s[6:7], 0, v[192:193]
	v_lshlrev_b64 v[190:191], 12, v[190:191]
	global_store_short v[146:147], v143, off offset:1312
	v_cvt_pk_bf16_f32 v143, v56, s0
	v_lshl_add_u64 v[190:191], v[192:193], 0, v[190:191]
	global_store_short v[148:149], v143, off offset:2336
	v_cvt_pk_bf16_f32 v143, v57, s0
	global_store_short v[150:151], v143, off offset:3360
	v_lshl_add_u64 v[192:193], v[190:191], 0, v[152:153]
	v_cvt_pk_bf16_f32 v143, v50, s0
	global_store_dwordx4 v[192:193], v[54:57], off nt
	global_store_short v[154:155], v143, off offset:288
	v_cvt_pk_bf16_f32 v143, v51, s0
	global_store_short v[156:157], v143, off offset:1312
	v_cvt_pk_bf16_f32 v143, v52, s0
	global_store_short v[158:159], v143, off offset:2336
	v_cvt_pk_bf16_f32 v143, v53, s0
	v_lshl_add_u64 v[192:193], v[190:191], 0, v[162:163]
	global_store_short v[160:161], v143, off offset:3360
	global_store_dwordx4 v[192:193], v[50:53], off nt
	v_add_u32_e32 v143, 0xa0, v141
	v_add_u32_e32 v187, 0xffff00a0, v141
	v_ashrrev_i32_e32 v192, 31, v143
	v_cmp_gt_i32_e32 vcc, s10, v143
	v_mov_b32_e32 v195, v0
	v_mov_b32_e32 v197, v0
	v_cndmask_b32_e32 v193, 0, v192, vcc
	v_cndmask_b32_e32 v192, v187, v143, vcc
	v_cvt_pk_bf16_f32 v143, v46, s0
	v_cndmask_b32_e32 v194, v205, v206, vcc
	global_store_short v[144:145], v143, off offset:320
	v_cvt_pk_bf16_f32 v143, v47, s0
	v_lshl_add_u64 v[194:195], s[6:7], 0, v[194:195]
	v_lshlrev_b64 v[192:193], 12, v[192:193]
	global_store_short v[146:147], v143, off offset:1344
	v_cvt_pk_bf16_f32 v143, v48, s0
	v_lshl_add_u64 v[192:193], v[194:195], 0, v[192:193]
	global_store_short v[148:149], v143, off offset:2368
	v_cvt_pk_bf16_f32 v143, v49, s0
	global_store_short v[150:151], v143, off offset:3392
	v_lshl_add_u64 v[194:195], v[192:193], 0, v[152:153]
	v_cvt_pk_bf16_f32 v143, v42, s0
	global_store_dwordx4 v[194:195], v[46:49], off nt
	global_store_short v[154:155], v143, off offset:320
	v_cvt_pk_bf16_f32 v143, v43, s0
	global_store_short v[156:157], v143, off offset:1344
	v_cvt_pk_bf16_f32 v143, v44, s0
	global_store_short v[158:159], v143, off offset:2368
	v_cvt_pk_bf16_f32 v143, v45, s0
	global_store_short v[160:161], v143, off offset:3392
	v_add_u32_e32 v143, 0xb0, v141
	v_lshl_add_u64 v[194:195], v[192:193], 0, v[162:163]
	v_add_u32_e32 v141, 0xffff00b0, v141
	v_cmp_gt_i32_e32 vcc, s10, v143
	global_store_dwordx4 v[194:195], v[42:45], off nt
	v_ashrrev_i32_e32 v187, 31, v143
	v_cndmask_b32_e32 v194, v141, v143, vcc
	v_cvt_pk_bf16_f32 v141, v38, s0
	v_cndmask_b32_e32 v195, 0, v187, vcc
	v_cndmask_b32_e32 v196, v205, v206, vcc
	global_store_short v[144:145], v141, off offset:352
	v_cvt_pk_bf16_f32 v141, v39, s0
; #define GAS __attribute__((address_space(1)))
; __device__ __forceinline__ u16 f2bf(float f) { return (u16)(pack2(f, 0.f) & 0xffffu); }
; template <int MODE>
; __device__ __forceinline__ void epi_elem(char* ws, float* outp, const float* b_gate, int g0, int rl, int col, f32x4 v) {
;     ...
;   } else if (MODE == E_V) {
;     int lc = col & 1023;
;     u16* vt = (u16*)(ws + W_VT);
; #pragma unroll
;     for (int i = 0; i < 4; ++i) vt[(size_t)(lc + i) * MAXR + rl] = f2bf(v[i]);
;     int rg = g0 + rl;
;     float* o = rg < NPROMPT ? outp + O_VP + (size_t)rg * 1024 : outp + O_VS + (size_t)(rg - NPROMPT) * 1024;
;     __builtin_nontemporal_store(v, (GAS f32x4*)(o + lc));
	v_lshl_add_u64 v[196:197], s[6:7], 0, v[196:197]
	v_lshlrev_b64 v[194:195], 12, v[194:195]
	global_store_short v[146:147], v141, off offset:1376
	v_cvt_pk_bf16_f32 v141, v40, s0
	v_lshl_add_u64 v[194:195], v[196:197], 0, v[194:195]
	global_store_short v[148:149], v141, off offset:2400
	v_cvt_pk_bf16_f32 v141, v41, s0
	global_store_short v[150:151], v141, off offset:3424
	v_lshl_add_u64 v[144:145], v[194:195], 0, v[152:153]
	v_cvt_pk_bf16_f32 v141, v34, s0
	global_store_dwordx4 v[144:145], v[38:41], off nt
	global_store_short v[154:155], v141, off offset:352
	v_cvt_pk_bf16_f32 v141, v35, s0
	global_store_short v[156:157], v141, off offset:1376
	v_cvt_pk_bf16_f32 v141, v36, s0
	global_store_short v[158:159], v141, off offset:2400
	v_cvt_pk_bf16_f32 v141, v37, s0
	v_lshl_add_u64 v[144:145], v[194:195], 0, v[162:163]
	global_store_short v[160:161], v141, off offset:3424
	global_store_dwordx4 v[144:145], v[34:37], off nt
	v_cvt_pk_bf16_f32 v141, v30, s0
	global_store_short v[164:165], v141, off offset:256
	v_cvt_pk_bf16_f32 v141, v31, s0
	global_store_short v[166:167], v141, off offset:1280
	v_cvt_pk_bf16_f32 v141, v32, s0
	global_store_short v[168:169], v141, off offset:2304
	v_cvt_pk_bf16_f32 v141, v33, s0
	global_store_short v[170:171], v141, off offset:3328
	v_lshl_add_u64 v[144:145], v[188:189], 0, v[172:173]
	v_cvt_pk_bf16_f32 v141, v26, s0
	global_store_dwordx4 v[144:145], v[30:33], off nt
	global_store_short v[174:175], v141, off offset:256
	v_cvt_pk_bf16_f32 v141, v27, s0
	global_store_short v[176:177], v141, off offset:1280
	v_cvt_pk_bf16_f32 v141, v28, s0
	global_store_short v[178:179], v141, off offset:2304
	v_cvt_pk_bf16_f32 v141, v29, s0
	global_store_short v[180:181], v141, off offset:3328
	v_lshl_add_u64 v[144:145], v[188:189], 0, v[182:183]
	v_cvt_pk_bf16_f32 v141, v22, s0
	global_store_dwordx4 v[144:145], v[26:29], off nt
	global_store_short v[164:165], v141, off offset:288
	v_cvt_pk_bf16_f32 v141, v23, s0
	global_store_short v[166:167], v141, off offset:1312
	v_cvt_pk_bf16_f32 v141, v24, s0
	global_store_short v[168:169], v141, off offset:2336
	v_cvt_pk_bf16_f32 v141, v25, s0
	global_store_short v[170:171], v141, off offset:3360
	v_lshl_add_u64 v[144:145], v[190:191], 0, v[172:173]
	v_cvt_pk_bf16_f32 v141, v18, s0
	global_store_dwordx4 v[144:145], v[22:25], off nt
	global_store_short v[174:175], v141, off offset:288
	v_cvt_pk_bf16_f32 v141, v19, s0
	global_store_short v[176:177], v141, off offset:1312
	v_cvt_pk_bf16_f32 v141, v20, s0
	global_store_short v[178:179], v141, off offset:2336
	v_cvt_pk_bf16_f32 v141, v21, s0
	v_lshl_add_u64 v[144:145], v[190:191], 0, v[182:183]
	global_store_short v[180:181], v141, off offset:3360
	global_store_dwordx4 v[144:145], v[18:21], off nt
	v_cvt_pk_bf16_f32 v141, v14, s0
	global_store_short v[164:165], v141, off offset:320
	v_cvt_pk_bf16_f32 v141, v15, s0
	global_store_short v[166:167], v141, off offset:1344
	v_cvt_pk_bf16_f32 v141, v16, s0
	global_store_short v[168:169], v141, off offset:2368
	v_cvt_pk_bf16_f32 v141, v17, s0
	global_store_short v[170:171], v141, off offset:3392
	v_lshl_add_u64 v[144:145], v[192:193], 0, v[172:173]
	v_cvt_pk_bf16_f32 v141, v10, s0
	global_store_dwordx4 v[144:145], v[14:17], off nt
	global_store_short v[174:175], v141, off offset:320
	v_cvt_pk_bf16_f32 v141, v11, s0
	global_store_short v[176:177], v141, off offset:1344
	v_cvt_pk_bf16_f32 v141, v12, s0
	global_store_short v[178:179], v141, off offset:2368
	v_cvt_pk_bf16_f32 v141, v13, s0
	global_store_short v[180:181], v141, off offset:3392
	v_lshl_add_u64 v[144:145], v[192:193], 0, v[182:183]
	v_cvt_pk_bf16_f32 v141, v6, s0
	global_store_dwordx4 v[144:145], v[10:13], off nt
	global_store_short v[164:165], v141, off offset:352
	v_cvt_pk_bf16_f32 v141, v7, s0
	global_store_short v[166:167], v141, off offset:1376
	v_cvt_pk_bf16_f32 v141, v8, s0
	global_store_short v[168:169], v141, off offset:2400
	v_cvt_pk_bf16_f32 v141, v9, s0
	global_store_short v[170:171], v141, off offset:3424
	v_lshl_add_u64 v[144:145], v[194:195], 0, v[172:173]
	v_cvt_pk_bf16_f32 v141, v2, s0
	global_store_dwordx4 v[144:145], v[6:9], off nt
	global_store_short v[174:175], v141, off offset:352
	v_cvt_pk_bf16_f32 v141, v3, s0
	global_store_short v[176:177], v141, off offset:1376
	v_cvt_pk_bf16_f32 v141, v4, s0
	global_store_short v[178:179], v141, off offset:2400
	v_cvt_pk_bf16_f32 v141, v5, s0
	v_lshl_add_u64 v[144:145], v[194:195], 0, v[182:183]
	global_store_short v[180:181], v141, off offset:3424
	global_store_dwordx4 v[144:145], v[2:5], off nt
	s_waitcnt vmcnt(0)
